# P6: hand-written software-pipelined gate/accumulate epilogues (loads of batch k+1 in flight under math+stores of batch k, saddr addressing), on top of P2 peeled first trip
# speedup vs baseline: 1.0294x; 1.0162x over previous
.Lp6e_done:
	s_and_b64 vcc, exec, s[16:17]
	s_mov_b32 s46, s18
	s_mov_b32 s47, s44
	s_mov_b32 s48, s45
	s_mov_b64 s[26:27], s[20:21]
	s_mov_b64 s[24:25], s[22:23]
	s_cbranch_vccnz .LBB0_1790

.LBB0_1757:
	s_cmp_eq_u32 s46, 0
	s_cbranch_scc1 .Lp6e_nop
	s_load_dwordx2 s[2:3], s[62:63], 0xc0
	v_lshrrev_b32_e32 v164, 8, v208
	v_and_b32_e32 v165, 15, v208
	v_lshl_add_u32 v164, v164, 6, v165
	v_bfe_u32 v165, v208, 6, 2
	v_bfe_u32 v166, v208, 4, 2
	v_lshlrev_b32_e32 v165, 6, v165
	v_lshl_add_u32 v165, v166, 4, v165
	v_lshl_add_u32 v216, v164, 9, v165
	v_lshl_add_u32 v221, v164, 11, v165
	s_mul_i32 s0, s48, 49
	s_lshl_b32 s19, s46, 2
	s_add_i32 s0, s0, s19
	s_add_i32 s0, s0, s47
	s_add_i32 s0, s0, 29
	s_lshl_b32 s0, s0, 17
	s_lshl_b32 s19, s48, 19
	s_lshl_b32 s32, s47, 9
	s_add_i32 s19, s19, s32
	s_mov_b32 s60, 0xbfb8aa3b
	s_mov_b32 s61, 0xbfb8aa3b
	s_mov_b32 s78, 1.0
	s_mov_b32 s79, 1.0
	s_waitcnt lgkmcnt(0)
	s_add_u32 s24, s2, 0x74c2800
	s_addc_u32 s25, s3, 0
	s_add_u32 s24, s24, s0
	s_addc_u32 s25, s25, 0
	s_add_u32 s26, s2, 0x244c2800
	s_addc_u32 s27, s3, 0
	s_add_u32 s26, s26, s19
	s_addc_u32 s27, s27, 0
	s_add_u32 s8, s24, 0x0
	s_addc_u32 s9, s25, 0
	global_load_dwordx4 v[132:135], v216, s[8:9]
	global_load_dwordx4 v[136:139], v216, s[8:9] offset:256
	s_add_u32 s8, s24, 0x2000
	s_addc_u32 s9, s25, 0
	global_load_dwordx4 v[140:143], v216, s[8:9]
	global_load_dwordx4 v[144:147], v216, s[8:9] offset:256
	s_add_u32 s8, s26, 0x0
	s_addc_u32 s9, s27, 0
	global_load_dwordx4 v[148:151], v221, s[8:9]
	global_load_dwordx4 v[152:155], v221, s[8:9] offset:256
	s_add_u32 s8, s26, 0x8000
	s_addc_u32 s9, s27, 0
	global_load_dwordx4 v[156:159], v221, s[8:9]
	global_load_dwordx4 v[160:163], v221, s[8:9] offset:256
	s_add_u32 s8, s24, 0x4000
	s_addc_u32 s9, s25, 0
	global_load_dwordx4 v[224:227], v216, s[8:9]
	global_load_dwordx4 v[228:231], v216, s[8:9] offset:256
	s_add_u32 s8, s24, 0x6000
	s_addc_u32 s9, s25, 0
	global_load_dwordx4 v[232:235], v216, s[8:9]
	global_load_dwordx4 v[236:239], v216, s[8:9] offset:256
	s_add_u32 s8, s26, 0x10000
	s_addc_u32 s9, s27, 0
	global_load_dwordx4 v[194:197], v221, s[8:9]
	global_load_dwordx4 v[198:201], v221, s[8:9] offset:256
	s_add_u32 s8, s26, 0x18000
	s_addc_u32 s9, s27, 0
	global_load_dwordx4 v[202:205], v221, s[8:9]
	global_load_dwordx4 v[240:243], v221, s[8:9] offset:256
	s_waitcnt vmcnt(8)
	s_add_u32 s98, s26, 0x0
	s_addc_u32 s99, s27, 0
	v_lshlrev_b32_e32 v164, 16, v132
	v_lshlrev_b32_e32 v170, 16, v133
	v_lshlrev_b32_e32 v172, 16, v134
	v_lshlrev_b32_e32 v206, 16, v135
	v_and_b32_e32 v165, 0xffff0000, v132
	v_and_b32_e32 v171, 0xffff0000, v133
	v_and_b32_e32 v173, 0xffff0000, v134
	v_and_b32_e32 v207, 0xffff0000, v135
	v_pk_mul_f32 v[164:165], v[164:165], s[60:61]
	v_pk_mul_f32 v[170:171], v[170:171], s[60:61]
	v_pk_mul_f32 v[172:173], v[172:173], s[60:61]
	v_pk_mul_f32 v[206:207], v[206:207], s[60:61]
	v_exp_f32_e32 v164, v164
	v_exp_f32_e32 v170, v170
	v_exp_f32_e32 v172, v172
	v_exp_f32_e32 v206, v206
	v_exp_f32_e32 v165, v165
	v_exp_f32_e32 v171, v171
	v_exp_f32_e32 v173, v173
	v_exp_f32_e32 v207, v207
	v_pk_add_f32 v[164:165], v[164:165], s[78:79]
	v_pk_add_f32 v[170:171], v[170:171], s[78:79]
	v_pk_add_f32 v[172:173], v[172:173], s[78:79]
	v_pk_add_f32 v[206:207], v[206:207], s[78:79]
	v_rcp_f32_e32 v164, v164
	v_rcp_f32_e32 v170, v170
	v_rcp_f32_e32 v172, v172
	v_rcp_f32_e32 v206, v206
	v_rcp_f32_e32 v165, v165
	v_rcp_f32_e32 v171, v171
	v_rcp_f32_e32 v173, v173
	v_rcp_f32_e32 v207, v207
	v_lshlrev_b32_e32 v210, 16, v148
	v_lshlrev_b32_e32 v244, 16, v149
	v_lshlrev_b32_e32 v248, 16, v150
	v_lshlrev_b32_e32 v250, 16, v151
	v_and_b32_e32 v211, 0xffff0000, v148
	v_and_b32_e32 v245, 0xffff0000, v149
	v_and_b32_e32 v249, 0xffff0000, v150
	v_and_b32_e32 v251, 0xffff0000, v151
	v_pk_fma_f32 v[128:129], v[128:129], v[164:165], v[210:211]
	v_pk_fma_f32 v[130:131], v[130:131], v[170:171], v[244:245]
	v_pk_fma_f32 v[124:125], v[124:125], v[172:173], v[248:249]
	v_pk_fma_f32 v[126:127], v[126:127], v[206:207], v[250:251]
	v_cvt_pk_bf16_f32 v128, v128, v129
	v_cvt_pk_bf16_f32 v129, v130, v131
	v_cvt_pk_bf16_f32 v130, v124, v125
	v_cvt_pk_bf16_f32 v131, v126, v127
	global_store_dwordx4 v221, v[128:131], s[98:99]
	v_lshlrev_b32_e32 v164, 16, v136
	v_lshlrev_b32_e32 v170, 16, v137
	v_lshlrev_b32_e32 v172, 16, v138
	v_lshlrev_b32_e32 v206, 16, v139
	v_and_b32_e32 v165, 0xffff0000, v136
	v_and_b32_e32 v171, 0xffff0000, v137
	v_and_b32_e32 v173, 0xffff0000, v138
	v_and_b32_e32 v207, 0xffff0000, v139
	v_pk_mul_f32 v[164:165], v[164:165], s[60:61]
	v_pk_mul_f32 v[170:171], v[170:171], s[60:61]
	v_pk_mul_f32 v[172:173], v[172:173], s[60:61]
	v_pk_mul_f32 v[206:207], v[206:207], s[60:61]
	v_exp_f32_e32 v164, v164
	v_exp_f32_e32 v170, v170
	v_exp_f32_e32 v172, v172
	v_exp_f32_e32 v206, v206
	v_exp_f32_e32 v165, v165
	v_exp_f32_e32 v171, v171
	v_exp_f32_e32 v173, v173
	v_exp_f32_e32 v207, v207
	v_pk_add_f32 v[164:165], v[164:165], s[78:79]
	v_pk_add_f32 v[170:171], v[170:171], s[78:79]
	v_pk_add_f32 v[172:173], v[172:173], s[78:79]
	v_pk_add_f32 v[206:207], v[206:207], s[78:79]
	v_rcp_f32_e32 v164, v164
	v_rcp_f32_e32 v170, v170
	v_rcp_f32_e32 v172, v172
	v_rcp_f32_e32 v206, v206
	v_rcp_f32_e32 v165, v165
	v_rcp_f32_e32 v171, v171
	v_rcp_f32_e32 v173, v173
	v_rcp_f32_e32 v207, v207
	v_lshlrev_b32_e32 v210, 16, v152
	v_lshlrev_b32_e32 v244, 16, v153
	v_lshlrev_b32_e32 v248, 16, v154
	v_lshlrev_b32_e32 v250, 16, v155
	v_and_b32_e32 v211, 0xffff0000, v152
	v_and_b32_e32 v245, 0xffff0000, v153
	v_and_b32_e32 v249, 0xffff0000, v154
	v_and_b32_e32 v251, 0xffff0000, v155
	v_pk_fma_f32 v[120:121], v[120:121], v[164:165], v[210:211]
	v_pk_fma_f32 v[122:123], v[122:123], v[170:171], v[244:245]
	v_pk_fma_f32 v[116:117], v[116:117], v[172:173], v[248:249]
	v_pk_fma_f32 v[118:119], v[118:119], v[206:207], v[250:251]
	v_cvt_pk_bf16_f32 v120, v120, v121
	v_cvt_pk_bf16_f32 v121, v122, v123
	v_cvt_pk_bf16_f32 v122, v116, v117
	v_cvt_pk_bf16_f32 v123, v118, v119
	global_store_dwordx4 v221, v[120:123], s[98:99] offset:256
	s_add_u32 s98, s26, 0x8000
	s_addc_u32 s99, s27, 0
	v_lshlrev_b32_e32 v164, 16, v140
	v_lshlrev_b32_e32 v170, 16, v141
	v_lshlrev_b32_e32 v172, 16, v142
	v_lshlrev_b32_e32 v206, 16, v143
	v_and_b32_e32 v165, 0xffff0000, v140
	v_and_b32_e32 v171, 0xffff0000, v141
	v_and_b32_e32 v173, 0xffff0000, v142
	v_and_b32_e32 v207, 0xffff0000, v143
	v_pk_mul_f32 v[164:165], v[164:165], s[60:61]
	v_pk_mul_f32 v[170:171], v[170:171], s[60:61]
	v_pk_mul_f32 v[172:173], v[172:173], s[60:61]
	v_pk_mul_f32 v[206:207], v[206:207], s[60:61]
	v_exp_f32_e32 v164, v164
	v_exp_f32_e32 v170, v170
	v_exp_f32_e32 v172, v172
	v_exp_f32_e32 v206, v206
	v_exp_f32_e32 v165, v165
	v_exp_f32_e32 v171, v171
	v_exp_f32_e32 v173, v173
	v_exp_f32_e32 v207, v207
	v_pk_add_f32 v[164:165], v[164:165], s[78:79]
	v_pk_add_f32 v[170:171], v[170:171], s[78:79]
	v_pk_add_f32 v[172:173], v[172:173], s[78:79]
	v_pk_add_f32 v[206:207], v[206:207], s[78:79]
	v_rcp_f32_e32 v164, v164
	v_rcp_f32_e32 v170, v170
	v_rcp_f32_e32 v172, v172
	v_rcp_f32_e32 v206, v206
	v_rcp_f32_e32 v165, v165
	v_rcp_f32_e32 v171, v171
	v_rcp_f32_e32 v173, v173
	v_rcp_f32_e32 v207, v207
	v_lshlrev_b32_e32 v210, 16, v156
	v_lshlrev_b32_e32 v244, 16, v157
	v_lshlrev_b32_e32 v248, 16, v158
	v_lshlrev_b32_e32 v250, 16, v159
	v_and_b32_e32 v211, 0xffff0000, v156
	v_and_b32_e32 v245, 0xffff0000, v157
	v_and_b32_e32 v249, 0xffff0000, v158
	v_and_b32_e32 v251, 0xffff0000, v159
	v_pk_fma_f32 v[112:113], v[112:113], v[164:165], v[210:211]
	v_pk_fma_f32 v[114:115], v[114:115], v[170:171], v[244:245]
	v_pk_fma_f32 v[108:109], v[108:109], v[172:173], v[248:249]
	v_pk_fma_f32 v[110:111], v[110:111], v[206:207], v[250:251]
	v_cvt_pk_bf16_f32 v112, v112, v113
	v_cvt_pk_bf16_f32 v113, v114, v115
	v_cvt_pk_bf16_f32 v114, v108, v109
	v_cvt_pk_bf16_f32 v115, v110, v111
	global_store_dwordx4 v221, v[112:115], s[98:99]
	v_lshlrev_b32_e32 v164, 16, v144
	v_lshlrev_b32_e32 v170, 16, v145
	v_lshlrev_b32_e32 v172, 16, v146
	v_lshlrev_b32_e32 v206, 16, v147
	v_and_b32_e32 v165, 0xffff0000, v144
	v_and_b32_e32 v171, 0xffff0000, v145
	v_and_b32_e32 v173, 0xffff0000, v146
	v_and_b32_e32 v207, 0xffff0000, v147
	v_pk_mul_f32 v[164:165], v[164:165], s[60:61]
	v_pk_mul_f32 v[170:171], v[170:171], s[60:61]
	v_pk_mul_f32 v[172:173], v[172:173], s[60:61]
	v_pk_mul_f32 v[206:207], v[206:207], s[60:61]
	v_exp_f32_e32 v164, v164
	v_exp_f32_e32 v170, v170
	v_exp_f32_e32 v172, v172
	v_exp_f32_e32 v206, v206
	v_exp_f32_e32 v165, v165
	v_exp_f32_e32 v171, v171
	v_exp_f32_e32 v173, v173
	v_exp_f32_e32 v207, v207
	v_pk_add_f32 v[164:165], v[164:165], s[78:79]
	v_pk_add_f32 v[170:171], v[170:171], s[78:79]
	v_pk_add_f32 v[172:173], v[172:173], s[78:79]
	v_pk_add_f32 v[206:207], v[206:207], s[78:79]
	v_rcp_f32_e32 v164, v164
	v_rcp_f32_e32 v170, v170
	v_rcp_f32_e32 v172, v172
	v_rcp_f32_e32 v206, v206
	v_rcp_f32_e32 v165, v165
	v_rcp_f32_e32 v171, v171
	v_rcp_f32_e32 v173, v173
	v_rcp_f32_e32 v207, v207
	v_lshlrev_b32_e32 v210, 16, v160
	v_lshlrev_b32_e32 v244, 16, v161
	v_lshlrev_b32_e32 v248, 16, v162
	v_lshlrev_b32_e32 v250, 16, v163
	v_and_b32_e32 v211, 0xffff0000, v160
	v_and_b32_e32 v245, 0xffff0000, v161
	v_and_b32_e32 v249, 0xffff0000, v162
	v_and_b32_e32 v251, 0xffff0000, v163
	v_pk_fma_f32 v[104:105], v[104:105], v[164:165], v[210:211]
	v_pk_fma_f32 v[106:107], v[106:107], v[170:171], v[244:245]
	v_pk_fma_f32 v[100:101], v[100:101], v[172:173], v[248:249]
	v_pk_fma_f32 v[102:103], v[102:103], v[206:207], v[250:251]
	v_cvt_pk_bf16_f32 v104, v104, v105
	v_cvt_pk_bf16_f32 v105, v106, v107
	v_cvt_pk_bf16_f32 v106, v100, v101
	v_cvt_pk_bf16_f32 v107, v102, v103
	global_store_dwordx4 v221, v[104:107], s[98:99] offset:256
	s_add_u32 s8, s24, 0x10000
	s_addc_u32 s9, s25, 0
	global_load_dwordx4 v[132:135], v216, s[8:9]
	global_load_dwordx4 v[136:139], v216, s[8:9] offset:256
	s_add_u32 s8, s24, 0x12000
	s_addc_u32 s9, s25, 0
	global_load_dwordx4 v[140:143], v216, s[8:9]
	global_load_dwordx4 v[144:147], v216, s[8:9] offset:256
	s_add_u32 s8, s26, 0x40000
	s_addc_u32 s9, s27, 0
	global_load_dwordx4 v[148:151], v221, s[8:9]
	global_load_dwordx4 v[152:155], v221, s[8:9] offset:256
	s_add_u32 s8, s26, 0x48000
	s_addc_u32 s9, s27, 0
	global_load_dwordx4 v[156:159], v221, s[8:9]
	global_load_dwordx4 v[160:163], v221, s[8:9] offset:256
	s_waitcnt vmcnt(12)
	s_add_u32 s98, s26, 0x10000
	s_addc_u32 s99, s27, 0
	v_lshlrev_b32_e32 v164, 16, v224
	v_lshlrev_b32_e32 v170, 16, v225
	v_lshlrev_b32_e32 v172, 16, v226
	v_lshlrev_b32_e32 v206, 16, v227
	v_and_b32_e32 v165, 0xffff0000, v224
	v_and_b32_e32 v171, 0xffff0000, v225
	v_and_b32_e32 v173, 0xffff0000, v226
	v_and_b32_e32 v207, 0xffff0000, v227
	v_pk_mul_f32 v[164:165], v[164:165], s[60:61]
	v_pk_mul_f32 v[170:171], v[170:171], s[60:61]
	v_pk_mul_f32 v[172:173], v[172:173], s[60:61]
	v_pk_mul_f32 v[206:207], v[206:207], s[60:61]
	v_exp_f32_e32 v164, v164
	v_exp_f32_e32 v170, v170
	v_exp_f32_e32 v172, v172
	v_exp_f32_e32 v206, v206
	v_exp_f32_e32 v165, v165
	v_exp_f32_e32 v171, v171
	v_exp_f32_e32 v173, v173
	v_exp_f32_e32 v207, v207
	v_pk_add_f32 v[164:165], v[164:165], s[78:79]
	v_pk_add_f32 v[170:171], v[170:171], s[78:79]
	v_pk_add_f32 v[172:173], v[172:173], s[78:79]
	v_pk_add_f32 v[206:207], v[206:207], s[78:79]
	v_rcp_f32_e32 v164, v164
	v_rcp_f32_e32 v170, v170
	v_rcp_f32_e32 v172, v172
	v_rcp_f32_e32 v206, v206
	v_rcp_f32_e32 v165, v165
	v_rcp_f32_e32 v171, v171
	v_rcp_f32_e32 v173, v173
	v_rcp_f32_e32 v207, v207
	v_lshlrev_b32_e32 v210, 16, v194
	v_lshlrev_b32_e32 v244, 16, v195
	v_lshlrev_b32_e32 v248, 16, v196
	v_lshlrev_b32_e32 v250, 16, v197
	v_and_b32_e32 v211, 0xffff0000, v194
	v_and_b32_e32 v245, 0xffff0000, v195
	v_and_b32_e32 v249, 0xffff0000, v196
	v_and_b32_e32 v251, 0xffff0000, v197
	v_pk_fma_f32 v[96:97], v[96:97], v[164:165], v[210:211]
	v_pk_fma_f32 v[98:99], v[98:99], v[170:171], v[244:245]
	v_pk_fma_f32 v[92:93], v[92:93], v[172:173], v[248:249]
	v_pk_fma_f32 v[94:95], v[94:95], v[206:207], v[250:251]
	v_cvt_pk_bf16_f32 v96, v96, v97
	v_cvt_pk_bf16_f32 v97, v98, v99
	v_cvt_pk_bf16_f32 v98, v92, v93
	v_cvt_pk_bf16_f32 v99, v94, v95
	global_store_dwordx4 v221, v[96:99], s[98:99]
	v_lshlrev_b32_e32 v164, 16, v228
	v_lshlrev_b32_e32 v170, 16, v229
	v_lshlrev_b32_e32 v172, 16, v230
	v_lshlrev_b32_e32 v206, 16, v231
	v_and_b32_e32 v165, 0xffff0000, v228
	v_and_b32_e32 v171, 0xffff0000, v229
	v_and_b32_e32 v173, 0xffff0000, v230
	v_and_b32_e32 v207, 0xffff0000, v231
	v_pk_mul_f32 v[164:165], v[164:165], s[60:61]
	v_pk_mul_f32 v[170:171], v[170:171], s[60:61]
	v_pk_mul_f32 v[172:173], v[172:173], s[60:61]
	v_pk_mul_f32 v[206:207], v[206:207], s[60:61]
	v_exp_f32_e32 v164, v164
	v_exp_f32_e32 v170, v170
	v_exp_f32_e32 v172, v172
	v_exp_f32_e32 v206, v206
	v_exp_f32_e32 v165, v165
	v_exp_f32_e32 v171, v171
	v_exp_f32_e32 v173, v173
	v_exp_f32_e32 v207, v207
	v_pk_add_f32 v[164:165], v[164:165], s[78:79]
	v_pk_add_f32 v[170:171], v[170:171], s[78:79]
	v_pk_add_f32 v[172:173], v[172:173], s[78:79]
	v_pk_add_f32 v[206:207], v[206:207], s[78:79]
	v_rcp_f32_e32 v164, v164
	v_rcp_f32_e32 v170, v170
	v_rcp_f32_e32 v172, v172
	v_rcp_f32_e32 v206, v206
	v_rcp_f32_e32 v165, v165
	v_rcp_f32_e32 v171, v171
	v_rcp_f32_e32 v173, v173
	v_rcp_f32_e32 v207, v207
	v_lshlrev_b32_e32 v210, 16, v198
	v_lshlrev_b32_e32 v244, 16, v199
	v_lshlrev_b32_e32 v248, 16, v200
	v_lshlrev_b32_e32 v250, 16, v201
	v_and_b32_e32 v211, 0xffff0000, v198
	v_and_b32_e32 v245, 0xffff0000, v199
	v_and_b32_e32 v249, 0xffff0000, v200
	v_and_b32_e32 v251, 0xffff0000, v201
	v_pk_fma_f32 v[88:89], v[88:89], v[164:165], v[210:211]
	v_pk_fma_f32 v[90:91], v[90:91], v[170:171], v[244:245]
	v_pk_fma_f32 v[84:85], v[84:85], v[172:173], v[248:249]
	v_pk_fma_f32 v[86:87], v[86:87], v[206:207], v[250:251]
	v_cvt_pk_bf16_f32 v88, v88, v89
	v_cvt_pk_bf16_f32 v89, v90, v91
	v_cvt_pk_bf16_f32 v90, v84, v85
	v_cvt_pk_bf16_f32 v91, v86, v87
	global_store_dwordx4 v221, v[88:91], s[98:99] offset:256
	s_add_u32 s98, s26, 0x18000
	s_addc_u32 s99, s27, 0
	v_lshlrev_b32_e32 v164, 16, v232
	v_lshlrev_b32_e32 v170, 16, v233
	v_lshlrev_b32_e32 v172, 16, v234
	v_lshlrev_b32_e32 v206, 16, v235
	v_and_b32_e32 v165, 0xffff0000, v232
	v_and_b32_e32 v171, 0xffff0000, v233
	v_and_b32_e32 v173, 0xffff0000, v234
	v_and_b32_e32 v207, 0xffff0000, v235
	v_pk_mul_f32 v[164:165], v[164:165], s[60:61]
	v_pk_mul_f32 v[170:171], v[170:171], s[60:61]
	v_pk_mul_f32 v[172:173], v[172:173], s[60:61]
	v_pk_mul_f32 v[206:207], v[206:207], s[60:61]
	v_exp_f32_e32 v164, v164
	v_exp_f32_e32 v170, v170
	v_exp_f32_e32 v172, v172
	v_exp_f32_e32 v206, v206
	v_exp_f32_e32 v165, v165
	v_exp_f32_e32 v171, v171
	v_exp_f32_e32 v173, v173
	v_exp_f32_e32 v207, v207
	v_pk_add_f32 v[164:165], v[164:165], s[78:79]
	v_pk_add_f32 v[170:171], v[170:171], s[78:79]
	v_pk_add_f32 v[172:173], v[172:173], s[78:79]
	v_pk_add_f32 v[206:207], v[206:207], s[78:79]
	v_rcp_f32_e32 v164, v164
	v_rcp_f32_e32 v170, v170
	v_rcp_f32_e32 v172, v172
	v_rcp_f32_e32 v206, v206
	v_rcp_f32_e32 v165, v165
	v_rcp_f32_e32 v171, v171
	v_rcp_f32_e32 v173, v173
	v_rcp_f32_e32 v207, v207
	v_lshlrev_b32_e32 v210, 16, v202
	v_lshlrev_b32_e32 v244, 16, v203
	v_lshlrev_b32_e32 v248, 16, v204
	v_lshlrev_b32_e32 v250, 16, v205
	v_and_b32_e32 v211, 0xffff0000, v202
	v_and_b32_e32 v245, 0xffff0000, v203
	v_and_b32_e32 v249, 0xffff0000, v204
	v_and_b32_e32 v251, 0xffff0000, v205
	v_pk_fma_f32 v[76:77], v[76:77], v[164:165], v[210:211]
	v_pk_fma_f32 v[78:79], v[78:79], v[170:171], v[244:245]
	v_pk_fma_f32 v[72:73], v[72:73], v[172:173], v[248:249]
	v_pk_fma_f32 v[74:75], v[74:75], v[206:207], v[250:251]
	v_cvt_pk_bf16_f32 v76, v76, v77
	v_cvt_pk_bf16_f32 v77, v78, v79
	v_cvt_pk_bf16_f32 v78, v72, v73
	v_cvt_pk_bf16_f32 v79, v74, v75
	global_store_dwordx4 v221, v[76:79], s[98:99]
	v_lshlrev_b32_e32 v164, 16, v236
	v_lshlrev_b32_e32 v170, 16, v237
	v_lshlrev_b32_e32 v172, 16, v238
	v_lshlrev_b32_e32 v206, 16, v239
	v_and_b32_e32 v165, 0xffff0000, v236
	v_and_b32_e32 v171, 0xffff0000, v237
	v_and_b32_e32 v173, 0xffff0000, v238
	v_and_b32_e32 v207, 0xffff0000, v239
	v_pk_mul_f32 v[164:165], v[164:165], s[60:61]
	v_pk_mul_f32 v[170:171], v[170:171], s[60:61]
	v_pk_mul_f32 v[172:173], v[172:173], s[60:61]
	v_pk_mul_f32 v[206:207], v[206:207], s[60:61]
	v_exp_f32_e32 v164, v164
	v_exp_f32_e32 v170, v170
	v_exp_f32_e32 v172, v172
	v_exp_f32_e32 v206, v206
	v_exp_f32_e32 v165, v165
	v_exp_f32_e32 v171, v171
	v_exp_f32_e32 v173, v173
	v_exp_f32_e32 v207, v207
	v_pk_add_f32 v[164:165], v[164:165], s[78:79]
	v_pk_add_f32 v[170:171], v[170:171], s[78:79]
	v_pk_add_f32 v[172:173], v[172:173], s[78:79]
	v_pk_add_f32 v[206:207], v[206:207], s[78:79]
	v_rcp_f32_e32 v164, v164
	v_rcp_f32_e32 v170, v170
	v_rcp_f32_e32 v172, v172
	v_rcp_f32_e32 v206, v206
	v_rcp_f32_e32 v165, v165
	v_rcp_f32_e32 v171, v171
	v_rcp_f32_e32 v173, v173
	v_rcp_f32_e32 v207, v207
	v_lshlrev_b32_e32 v210, 16, v240
	v_lshlrev_b32_e32 v244, 16, v241
	v_lshlrev_b32_e32 v248, 16, v242
	v_lshlrev_b32_e32 v250, 16, v243
	v_and_b32_e32 v211, 0xffff0000, v240
	v_and_b32_e32 v245, 0xffff0000, v241
	v_and_b32_e32 v249, 0xffff0000, v242
	v_and_b32_e32 v251, 0xffff0000, v243
	v_pk_fma_f32 v[68:69], v[68:69], v[164:165], v[210:211]
	v_pk_fma_f32 v[70:71], v[70:71], v[170:171], v[244:245]
	v_pk_fma_f32 v[64:65], v[64:65], v[172:173], v[248:249]
	v_pk_fma_f32 v[66:67], v[66:67], v[206:207], v[250:251]
	v_cvt_pk_bf16_f32 v68, v68, v69
	v_cvt_pk_bf16_f32 v69, v70, v71
	v_cvt_pk_bf16_f32 v70, v64, v65
	v_cvt_pk_bf16_f32 v71, v66, v67
	global_store_dwordx4 v221, v[68:71], s[98:99] offset:256
	s_add_u32 s8, s24, 0x14000
	s_addc_u32 s9, s25, 0
	global_load_dwordx4 v[224:227], v216, s[8:9]
	global_load_dwordx4 v[228:231], v216, s[8:9] offset:256
	s_add_u32 s8, s24, 0x16000
	s_addc_u32 s9, s25, 0
	global_load_dwordx4 v[232:235], v216, s[8:9]
	global_load_dwordx4 v[236:239], v216, s[8:9] offset:256
	s_add_u32 s8, s26, 0x50000
	s_addc_u32 s9, s27, 0
	global_load_dwordx4 v[194:197], v221, s[8:9]
	global_load_dwordx4 v[198:201], v221, s[8:9] offset:256
	s_add_u32 s8, s26, 0x58000
	s_addc_u32 s9, s27, 0
	global_load_dwordx4 v[202:205], v221, s[8:9]
	global_load_dwordx4 v[240:243], v221, s[8:9] offset:256
	s_waitcnt vmcnt(12)
	s_add_u32 s98, s26, 0x40000
	s_addc_u32 s99, s27, 0
	v_lshlrev_b32_e32 v164, 16, v132
	v_lshlrev_b32_e32 v170, 16, v133
	v_lshlrev_b32_e32 v172, 16, v134
	v_lshlrev_b32_e32 v206, 16, v135
	v_and_b32_e32 v165, 0xffff0000, v132
	v_and_b32_e32 v171, 0xffff0000, v133
	v_and_b32_e32 v173, 0xffff0000, v134
	v_and_b32_e32 v207, 0xffff0000, v135
	v_pk_mul_f32 v[164:165], v[164:165], s[60:61]
	v_pk_mul_f32 v[170:171], v[170:171], s[60:61]
	v_pk_mul_f32 v[172:173], v[172:173], s[60:61]
	v_pk_mul_f32 v[206:207], v[206:207], s[60:61]
	v_exp_f32_e32 v164, v164
	v_exp_f32_e32 v170, v170
	v_exp_f32_e32 v172, v172
	v_exp_f32_e32 v206, v206
	v_exp_f32_e32 v165, v165
	v_exp_f32_e32 v171, v171
	v_exp_f32_e32 v173, v173
	v_exp_f32_e32 v207, v207
	v_pk_add_f32 v[164:165], v[164:165], s[78:79]
	v_pk_add_f32 v[170:171], v[170:171], s[78:79]
	v_pk_add_f32 v[172:173], v[172:173], s[78:79]
	v_pk_add_f32 v[206:207], v[206:207], s[78:79]
	v_rcp_f32_e32 v164, v164
	v_rcp_f32_e32 v170, v170
	v_rcp_f32_e32 v172, v172
	v_rcp_f32_e32 v206, v206
	v_rcp_f32_e32 v165, v165
	v_rcp_f32_e32 v171, v171
	v_rcp_f32_e32 v173, v173
	v_rcp_f32_e32 v207, v207
	v_lshlrev_b32_e32 v210, 16, v148
	v_lshlrev_b32_e32 v244, 16, v149
	v_lshlrev_b32_e32 v248, 16, v150
	v_lshlrev_b32_e32 v250, 16, v151
	v_and_b32_e32 v211, 0xffff0000, v148
	v_and_b32_e32 v245, 0xffff0000, v149
	v_and_b32_e32 v249, 0xffff0000, v150
	v_and_b32_e32 v251, 0xffff0000, v151
	v_pk_fma_f32 v[60:61], v[60:61], v[164:165], v[210:211]
	v_pk_fma_f32 v[62:63], v[62:63], v[170:171], v[244:245]
	v_pk_fma_f32 v[56:57], v[56:57], v[172:173], v[248:249]
	v_pk_fma_f32 v[58:59], v[58:59], v[206:207], v[250:251]
	v_cvt_pk_bf16_f32 v60, v60, v61
	v_cvt_pk_bf16_f32 v61, v62, v63
	v_cvt_pk_bf16_f32 v62, v56, v57
	v_cvt_pk_bf16_f32 v63, v58, v59
	global_store_dwordx4 v221, v[60:63], s[98:99]
	v_lshlrev_b32_e32 v164, 16, v136
	v_lshlrev_b32_e32 v170, 16, v137
	v_lshlrev_b32_e32 v172, 16, v138
	v_lshlrev_b32_e32 v206, 16, v139
	v_and_b32_e32 v165, 0xffff0000, v136
	v_and_b32_e32 v171, 0xffff0000, v137
	v_and_b32_e32 v173, 0xffff0000, v138
	v_and_b32_e32 v207, 0xffff0000, v139
	v_pk_mul_f32 v[164:165], v[164:165], s[60:61]
	v_pk_mul_f32 v[170:171], v[170:171], s[60:61]
	v_pk_mul_f32 v[172:173], v[172:173], s[60:61]
	v_pk_mul_f32 v[206:207], v[206:207], s[60:61]
	v_exp_f32_e32 v164, v164
	v_exp_f32_e32 v170, v170
	v_exp_f32_e32 v172, v172
	v_exp_f32_e32 v206, v206
	v_exp_f32_e32 v165, v165
	v_exp_f32_e32 v171, v171
	v_exp_f32_e32 v173, v173
	v_exp_f32_e32 v207, v207
	v_pk_add_f32 v[164:165], v[164:165], s[78:79]
	v_pk_add_f32 v[170:171], v[170:171], s[78:79]
	v_pk_add_f32 v[172:173], v[172:173], s[78:79]
	v_pk_add_f32 v[206:207], v[206:207], s[78:79]
	v_rcp_f32_e32 v164, v164
	v_rcp_f32_e32 v170, v170
	v_rcp_f32_e32 v172, v172
	v_rcp_f32_e32 v206, v206
	v_rcp_f32_e32 v165, v165
	v_rcp_f32_e32 v171, v171
	v_rcp_f32_e32 v173, v173
	v_rcp_f32_e32 v207, v207
	v_lshlrev_b32_e32 v210, 16, v152
	v_lshlrev_b32_e32 v244, 16, v153
	v_lshlrev_b32_e32 v248, 16, v154
	v_lshlrev_b32_e32 v250, 16, v155
	v_and_b32_e32 v211, 0xffff0000, v152
	v_and_b32_e32 v245, 0xffff0000, v153
	v_and_b32_e32 v249, 0xffff0000, v154
	v_and_b32_e32 v251, 0xffff0000, v155
	v_pk_fma_f32 v[52:53], v[52:53], v[164:165], v[210:211]
	v_pk_fma_f32 v[54:55], v[54:55], v[170:171], v[244:245]
	v_pk_fma_f32 v[48:49], v[48:49], v[172:173], v[248:249]
	v_pk_fma_f32 v[50:51], v[50:51], v[206:207], v[250:251]
	v_cvt_pk_bf16_f32 v52, v52, v53
	v_cvt_pk_bf16_f32 v53, v54, v55
	v_cvt_pk_bf16_f32 v54, v48, v49
	v_cvt_pk_bf16_f32 v55, v50, v51
	global_store_dwordx4 v221, v[52:55], s[98:99] offset:256
	s_add_u32 s98, s26, 0x48000
	s_addc_u32 s99, s27, 0
	v_lshlrev_b32_e32 v164, 16, v140
	v_lshlrev_b32_e32 v170, 16, v141
	v_lshlrev_b32_e32 v172, 16, v142
	v_lshlrev_b32_e32 v206, 16, v143
	v_and_b32_e32 v165, 0xffff0000, v140
	v_and_b32_e32 v171, 0xffff0000, v141
	v_and_b32_e32 v173, 0xffff0000, v142
	v_and_b32_e32 v207, 0xffff0000, v143
	v_pk_mul_f32 v[164:165], v[164:165], s[60:61]
	v_pk_mul_f32 v[170:171], v[170:171], s[60:61]
	v_pk_mul_f32 v[172:173], v[172:173], s[60:61]
	v_pk_mul_f32 v[206:207], v[206:207], s[60:61]
	v_exp_f32_e32 v164, v164
	v_exp_f32_e32 v170, v170
	v_exp_f32_e32 v172, v172
	v_exp_f32_e32 v206, v206
	v_exp_f32_e32 v165, v165
	v_exp_f32_e32 v171, v171
	v_exp_f32_e32 v173, v173
	v_exp_f32_e32 v207, v207
	v_pk_add_f32 v[164:165], v[164:165], s[78:79]
	v_pk_add_f32 v[170:171], v[170:171], s[78:79]
	v_pk_add_f32 v[172:173], v[172:173], s[78:79]
	v_pk_add_f32 v[206:207], v[206:207], s[78:79]
	v_rcp_f32_e32 v164, v164
	v_rcp_f32_e32 v170, v170
	v_rcp_f32_e32 v172, v172
	v_rcp_f32_e32 v206, v206
	v_rcp_f32_e32 v165, v165
	v_rcp_f32_e32 v171, v171
	v_rcp_f32_e32 v173, v173
	v_rcp_f32_e32 v207, v207
	v_lshlrev_b32_e32 v210, 16, v156
	v_lshlrev_b32_e32 v244, 16, v157
	v_lshlrev_b32_e32 v248, 16, v158
	v_lshlrev_b32_e32 v250, 16, v159
	v_and_b32_e32 v211, 0xffff0000, v156
	v_and_b32_e32 v245, 0xffff0000, v157
	v_and_b32_e32 v249, 0xffff0000, v158
	v_and_b32_e32 v251, 0xffff0000, v159
	v_pk_fma_f32 v[44:45], v[44:45], v[164:165], v[210:211]
	v_pk_fma_f32 v[46:47], v[46:47], v[170:171], v[244:245]
	v_pk_fma_f32 v[40:41], v[40:41], v[172:173], v[248:249]
	v_pk_fma_f32 v[42:43], v[42:43], v[206:207], v[250:251]
	v_cvt_pk_bf16_f32 v44, v44, v45
	v_cvt_pk_bf16_f32 v45, v46, v47
	v_cvt_pk_bf16_f32 v46, v40, v41
	v_cvt_pk_bf16_f32 v47, v42, v43
	global_store_dwordx4 v221, v[44:47], s[98:99]
	v_lshlrev_b32_e32 v164, 16, v144
	v_lshlrev_b32_e32 v170, 16, v145
	v_lshlrev_b32_e32 v172, 16, v146
	v_lshlrev_b32_e32 v206, 16, v147
	v_and_b32_e32 v165, 0xffff0000, v144
	v_and_b32_e32 v171, 0xffff0000, v145
	v_and_b32_e32 v173, 0xffff0000, v146
	v_and_b32_e32 v207, 0xffff0000, v147
	v_pk_mul_f32 v[164:165], v[164:165], s[60:61]
	v_pk_mul_f32 v[170:171], v[170:171], s[60:61]
	v_pk_mul_f32 v[172:173], v[172:173], s[60:61]
	v_pk_mul_f32 v[206:207], v[206:207], s[60:61]
	v_exp_f32_e32 v164, v164
	v_exp_f32_e32 v170, v170
	v_exp_f32_e32 v172, v172
	v_exp_f32_e32 v206, v206
	v_exp_f32_e32 v165, v165
	v_exp_f32_e32 v171, v171
	v_exp_f32_e32 v173, v173
	v_exp_f32_e32 v207, v207
	v_pk_add_f32 v[164:165], v[164:165], s[78:79]
	v_pk_add_f32 v[170:171], v[170:171], s[78:79]
	v_pk_add_f32 v[172:173], v[172:173], s[78:79]
	v_pk_add_f32 v[206:207], v[206:207], s[78:79]
	v_rcp_f32_e32 v164, v164
	v_rcp_f32_e32 v170, v170
	v_rcp_f32_e32 v172, v172
	v_rcp_f32_e32 v206, v206
	v_rcp_f32_e32 v165, v165
	v_rcp_f32_e32 v171, v171
	v_rcp_f32_e32 v173, v173
	v_rcp_f32_e32 v207, v207
	v_lshlrev_b32_e32 v210, 16, v160
	v_lshlrev_b32_e32 v244, 16, v161
	v_lshlrev_b32_e32 v248, 16, v162
	v_lshlrev_b32_e32 v250, 16, v163
	v_and_b32_e32 v211, 0xffff0000, v160
	v_and_b32_e32 v245, 0xffff0000, v161
	v_and_b32_e32 v249, 0xffff0000, v162
	v_and_b32_e32 v251, 0xffff0000, v163
	v_pk_fma_f32 v[36:37], v[36:37], v[164:165], v[210:211]
	v_pk_fma_f32 v[38:39], v[38:39], v[170:171], v[244:245]
	v_pk_fma_f32 v[32:33], v[32:33], v[172:173], v[248:249]
	v_pk_fma_f32 v[34:35], v[34:35], v[206:207], v[250:251]
	v_cvt_pk_bf16_f32 v36, v36, v37
	v_cvt_pk_bf16_f32 v37, v38, v39
	v_cvt_pk_bf16_f32 v38, v32, v33
	v_cvt_pk_bf16_f32 v39, v34, v35
	global_store_dwordx4 v221, v[36:39], s[98:99] offset:256
	s_waitcnt vmcnt(4)
	s_add_u32 s98, s26, 0x50000
	s_addc_u32 s99, s27, 0
	v_lshlrev_b32_e32 v164, 16, v224
	v_lshlrev_b32_e32 v170, 16, v225
	v_lshlrev_b32_e32 v172, 16, v226
	v_lshlrev_b32_e32 v206, 16, v227
	v_and_b32_e32 v165, 0xffff0000, v224
	v_and_b32_e32 v171, 0xffff0000, v225
	v_and_b32_e32 v173, 0xffff0000, v226
	v_and_b32_e32 v207, 0xffff0000, v227
	v_pk_mul_f32 v[164:165], v[164:165], s[60:61]
	v_pk_mul_f32 v[170:171], v[170:171], s[60:61]
	v_pk_mul_f32 v[172:173], v[172:173], s[60:61]
	v_pk_mul_f32 v[206:207], v[206:207], s[60:61]
	v_exp_f32_e32 v164, v164
	v_exp_f32_e32 v170, v170
	v_exp_f32_e32 v172, v172
	v_exp_f32_e32 v206, v206
	v_exp_f32_e32 v165, v165
	v_exp_f32_e32 v171, v171
	v_exp_f32_e32 v173, v173
	v_exp_f32_e32 v207, v207
	v_pk_add_f32 v[164:165], v[164:165], s[78:79]
	v_pk_add_f32 v[170:171], v[170:171], s[78:79]
	v_pk_add_f32 v[172:173], v[172:173], s[78:79]
	v_pk_add_f32 v[206:207], v[206:207], s[78:79]
	v_rcp_f32_e32 v164, v164
	v_rcp_f32_e32 v170, v170
	v_rcp_f32_e32 v172, v172
	v_rcp_f32_e32 v206, v206
	v_rcp_f32_e32 v165, v165
	v_rcp_f32_e32 v171, v171
	v_rcp_f32_e32 v173, v173
	v_rcp_f32_e32 v207, v207
	v_lshlrev_b32_e32 v210, 16, v194
	v_lshlrev_b32_e32 v244, 16, v195
	v_lshlrev_b32_e32 v248, 16, v196
	v_lshlrev_b32_e32 v250, 16, v197
	v_and_b32_e32 v211, 0xffff0000, v194
	v_and_b32_e32 v245, 0xffff0000, v195
	v_and_b32_e32 v249, 0xffff0000, v196
	v_and_b32_e32 v251, 0xffff0000, v197
	v_pk_fma_f32 v[28:29], v[28:29], v[164:165], v[210:211]
	v_pk_fma_f32 v[30:31], v[30:31], v[170:171], v[244:245]
	v_pk_fma_f32 v[24:25], v[24:25], v[172:173], v[248:249]
	v_pk_fma_f32 v[26:27], v[26:27], v[206:207], v[250:251]
	v_cvt_pk_bf16_f32 v28, v28, v29
	v_cvt_pk_bf16_f32 v29, v30, v31
	v_cvt_pk_bf16_f32 v30, v24, v25
	v_cvt_pk_bf16_f32 v31, v26, v27
	global_store_dwordx4 v221, v[28:31], s[98:99]
	v_lshlrev_b32_e32 v164, 16, v228
	v_lshlrev_b32_e32 v170, 16, v229
	v_lshlrev_b32_e32 v172, 16, v230
	v_lshlrev_b32_e32 v206, 16, v231
	v_and_b32_e32 v165, 0xffff0000, v228
	v_and_b32_e32 v171, 0xffff0000, v229
	v_and_b32_e32 v173, 0xffff0000, v230
	v_and_b32_e32 v207, 0xffff0000, v231
	v_pk_mul_f32 v[164:165], v[164:165], s[60:61]
	v_pk_mul_f32 v[170:171], v[170:171], s[60:61]
	v_pk_mul_f32 v[172:173], v[172:173], s[60:61]
	v_pk_mul_f32 v[206:207], v[206:207], s[60:61]
	v_exp_f32_e32 v164, v164
	v_exp_f32_e32 v170, v170
	v_exp_f32_e32 v172, v172
	v_exp_f32_e32 v206, v206
	v_exp_f32_e32 v165, v165
	v_exp_f32_e32 v171, v171
	v_exp_f32_e32 v173, v173
	v_exp_f32_e32 v207, v207
	v_pk_add_f32 v[164:165], v[164:165], s[78:79]
	v_pk_add_f32 v[170:171], v[170:171], s[78:79]
	v_pk_add_f32 v[172:173], v[172:173], s[78:79]
	v_pk_add_f32 v[206:207], v[206:207], s[78:79]
	v_rcp_f32_e32 v164, v164
	v_rcp_f32_e32 v170, v170
	v_rcp_f32_e32 v172, v172
	v_rcp_f32_e32 v206, v206
	v_rcp_f32_e32 v165, v165
	v_rcp_f32_e32 v171, v171
	v_rcp_f32_e32 v173, v173
	v_rcp_f32_e32 v207, v207
	v_lshlrev_b32_e32 v210, 16, v198
	v_lshlrev_b32_e32 v244, 16, v199
	v_lshlrev_b32_e32 v248, 16, v200
	v_lshlrev_b32_e32 v250, 16, v201
	v_and_b32_e32 v211, 0xffff0000, v198
	v_and_b32_e32 v245, 0xffff0000, v199
	v_and_b32_e32 v249, 0xffff0000, v200
	v_and_b32_e32 v251, 0xffff0000, v201
	v_pk_fma_f32 v[20:21], v[20:21], v[164:165], v[210:211]
	v_pk_fma_f32 v[22:23], v[22:23], v[170:171], v[244:245]
	v_pk_fma_f32 v[16:17], v[16:17], v[172:173], v[248:249]
	v_pk_fma_f32 v[18:19], v[18:19], v[206:207], v[250:251]
	v_cvt_pk_bf16_f32 v20, v20, v21
	v_cvt_pk_bf16_f32 v21, v22, v23
	v_cvt_pk_bf16_f32 v22, v16, v17
	v_cvt_pk_bf16_f32 v23, v18, v19
	global_store_dwordx4 v221, v[20:23], s[98:99] offset:256
	s_add_u32 s98, s26, 0x58000
	s_addc_u32 s99, s27, 0
	v_lshlrev_b32_e32 v164, 16, v232
	v_lshlrev_b32_e32 v170, 16, v233
	v_lshlrev_b32_e32 v172, 16, v234
	v_lshlrev_b32_e32 v206, 16, v235
	v_and_b32_e32 v165, 0xffff0000, v232
	v_and_b32_e32 v171, 0xffff0000, v233
	v_and_b32_e32 v173, 0xffff0000, v234
	v_and_b32_e32 v207, 0xffff0000, v235
	v_pk_mul_f32 v[164:165], v[164:165], s[60:61]
	v_pk_mul_f32 v[170:171], v[170:171], s[60:61]
	v_pk_mul_f32 v[172:173], v[172:173], s[60:61]
	v_pk_mul_f32 v[206:207], v[206:207], s[60:61]
	v_exp_f32_e32 v164, v164
	v_exp_f32_e32 v170, v170
	v_exp_f32_e32 v172, v172
	v_exp_f32_e32 v206, v206
	v_exp_f32_e32 v165, v165
	v_exp_f32_e32 v171, v171
	v_exp_f32_e32 v173, v173
	v_exp_f32_e32 v207, v207
	v_pk_add_f32 v[164:165], v[164:165], s[78:79]
	v_pk_add_f32 v[170:171], v[170:171], s[78:79]
	v_pk_add_f32 v[172:173], v[172:173], s[78:79]
	v_pk_add_f32 v[206:207], v[206:207], s[78:79]
	v_rcp_f32_e32 v164, v164
	v_rcp_f32_e32 v170, v170
	v_rcp_f32_e32 v172, v172
	v_rcp_f32_e32 v206, v206
	v_rcp_f32_e32 v165, v165
	v_rcp_f32_e32 v171, v171
	v_rcp_f32_e32 v173, v173
	v_rcp_f32_e32 v207, v207
	v_lshlrev_b32_e32 v210, 16, v202
	v_lshlrev_b32_e32 v244, 16, v203
	v_lshlrev_b32_e32 v248, 16, v204
	v_lshlrev_b32_e32 v250, 16, v205
	v_and_b32_e32 v211, 0xffff0000, v202
	v_and_b32_e32 v245, 0xffff0000, v203
	v_and_b32_e32 v249, 0xffff0000, v204
	v_and_b32_e32 v251, 0xffff0000, v205
	v_pk_fma_f32 v[12:13], v[12:13], v[164:165], v[210:211]
	v_pk_fma_f32 v[14:15], v[14:15], v[170:171], v[244:245]
	v_pk_fma_f32 v[8:9], v[8:9], v[172:173], v[248:249]
	v_pk_fma_f32 v[10:11], v[10:11], v[206:207], v[250:251]
	v_cvt_pk_bf16_f32 v12, v12, v13
	v_cvt_pk_bf16_f32 v13, v14, v15
	v_cvt_pk_bf16_f32 v14, v8, v9
	v_cvt_pk_bf16_f32 v15, v10, v11
	global_store_dwordx4 v221, v[12:15], s[98:99]
	v_lshlrev_b32_e32 v164, 16, v236
	v_lshlrev_b32_e32 v170, 16, v237
	v_lshlrev_b32_e32 v172, 16, v238
	v_lshlrev_b32_e32 v206, 16, v239
	v_and_b32_e32 v165, 0xffff0000, v236
	v_and_b32_e32 v171, 0xffff0000, v237
	v_and_b32_e32 v173, 0xffff0000, v238
	v_and_b32_e32 v207, 0xffff0000, v239
	v_pk_mul_f32 v[164:165], v[164:165], s[60:61]
	v_pk_mul_f32 v[170:171], v[170:171], s[60:61]
	v_pk_mul_f32 v[172:173], v[172:173], s[60:61]
	v_pk_mul_f32 v[206:207], v[206:207], s[60:61]
	v_exp_f32_e32 v164, v164
	v_exp_f32_e32 v170, v170
	v_exp_f32_e32 v172, v172
	v_exp_f32_e32 v206, v206
	v_exp_f32_e32 v165, v165
	v_exp_f32_e32 v171, v171
	v_exp_f32_e32 v173, v173
	v_exp_f32_e32 v207, v207
	v_pk_add_f32 v[164:165], v[164:165], s[78:79]
	v_pk_add_f32 v[170:171], v[170:171], s[78:79]
	v_pk_add_f32 v[172:173], v[172:173], s[78:79]
	v_pk_add_f32 v[206:207], v[206:207], s[78:79]
	v_rcp_f32_e32 v164, v164
	v_rcp_f32_e32 v170, v170
	v_rcp_f32_e32 v172, v172
	v_rcp_f32_e32 v206, v206
	v_rcp_f32_e32 v165, v165
	v_rcp_f32_e32 v171, v171
	v_rcp_f32_e32 v173, v173
	v_rcp_f32_e32 v207, v207
	v_lshlrev_b32_e32 v210, 16, v240
	v_lshlrev_b32_e32 v244, 16, v241
	v_lshlrev_b32_e32 v248, 16, v242
	v_lshlrev_b32_e32 v250, 16, v243
	v_and_b32_e32 v211, 0xffff0000, v240
	v_and_b32_e32 v245, 0xffff0000, v241
	v_and_b32_e32 v249, 0xffff0000, v242
	v_and_b32_e32 v251, 0xffff0000, v243
	v_pk_fma_f32 v[4:5], v[4:5], v[164:165], v[210:211]
	v_pk_fma_f32 v[6:7], v[6:7], v[170:171], v[244:245]
	v_pk_fma_f32 v[0:1], v[0:1], v[172:173], v[248:249]
	v_pk_fma_f32 v[2:3], v[2:3], v[206:207], v[250:251]
	v_cvt_pk_bf16_f32 v4, v4, v5
	v_cvt_pk_bf16_f32 v5, v6, v7
	v_cvt_pk_bf16_f32 v6, v0, v1
	v_cvt_pk_bf16_f32 v7, v2, v3
	global_store_dwordx4 v221, v[4:7], s[98:99] offset:256
	s_branch .Lp6e_done
.Lp6e_nop:
	s_load_dwordx2 s[2:3], s[62:63], 0xc0
	v_lshrrev_b32_e32 v164, 8, v208
	v_and_b32_e32 v165, 15, v208
	v_lshl_add_u32 v164, v164, 6, v165
	v_bfe_u32 v165, v208, 6, 2
	v_bfe_u32 v166, v208, 4, 2
	v_lshlrev_b32_e32 v165, 6, v165
	v_lshl_add_u32 v165, v166, 4, v165
	v_lshl_add_u32 v216, v164, 9, v165
	v_lshl_add_u32 v221, v164, 11, v165
	s_mul_i32 s0, s48, 49
	s_lshl_b32 s19, s46, 2
	s_add_i32 s0, s0, s19
	s_add_i32 s0, s0, s47
	s_add_i32 s0, s0, 29
	s_lshl_b32 s0, s0, 17
	s_lshl_b32 s19, s48, 19
	s_lshl_b32 s32, s47, 9
	s_add_i32 s19, s19, s32
	s_mov_b32 s60, 0xbfb8aa3b
	s_mov_b32 s61, 0xbfb8aa3b
	s_mov_b32 s78, 1.0
	s_mov_b32 s79, 1.0
	s_waitcnt lgkmcnt(0)
	s_add_u32 s24, s2, 0x74c2800
	s_addc_u32 s25, s3, 0
	s_add_u32 s24, s24, s0
	s_addc_u32 s25, s25, 0
	s_add_u32 s26, s2, 0x244c2800
	s_addc_u32 s27, s3, 0
	s_add_u32 s26, s26, s19
	s_addc_u32 s27, s27, 0
	s_add_u32 s8, s24, 0x0
	s_addc_u32 s9, s25, 0
	global_load_dwordx4 v[132:135], v216, s[8:9]
	global_load_dwordx4 v[136:139], v216, s[8:9] offset:256
	s_add_u32 s8, s24, 0x2000
	s_addc_u32 s9, s25, 0
	global_load_dwordx4 v[140:143], v216, s[8:9]
	global_load_dwordx4 v[144:147], v216, s[8:9] offset:256
	s_add_u32 s8, s24, 0x4000
	s_addc_u32 s9, s25, 0
	global_load_dwordx4 v[224:227], v216, s[8:9]
	global_load_dwordx4 v[228:231], v216, s[8:9] offset:256
	s_add_u32 s8, s24, 0x6000
	s_addc_u32 s9, s25, 0
	global_load_dwordx4 v[232:235], v216, s[8:9]
	global_load_dwordx4 v[236:239], v216, s[8:9] offset:256
	s_waitcnt vmcnt(4)
	s_add_u32 s98, s26, 0x0
	s_addc_u32 s99, s27, 0
	v_lshlrev_b32_e32 v164, 16, v132
	v_lshlrev_b32_e32 v170, 16, v133
	v_lshlrev_b32_e32 v172, 16, v134
	v_lshlrev_b32_e32 v206, 16, v135
	v_and_b32_e32 v165, 0xffff0000, v132
	v_and_b32_e32 v171, 0xffff0000, v133
	v_and_b32_e32 v173, 0xffff0000, v134
	v_and_b32_e32 v207, 0xffff0000, v135
	v_pk_mul_f32 v[164:165], v[164:165], s[60:61]
	v_pk_mul_f32 v[170:171], v[170:171], s[60:61]
	v_pk_mul_f32 v[172:173], v[172:173], s[60:61]
	v_pk_mul_f32 v[206:207], v[206:207], s[60:61]
	v_exp_f32_e32 v164, v164
	v_exp_f32_e32 v170, v170
	v_exp_f32_e32 v172, v172
	v_exp_f32_e32 v206, v206
	v_exp_f32_e32 v165, v165
	v_exp_f32_e32 v171, v171
	v_exp_f32_e32 v173, v173
	v_exp_f32_e32 v207, v207
	v_pk_add_f32 v[164:165], v[164:165], s[78:79]
	v_pk_add_f32 v[170:171], v[170:171], s[78:79]
	v_pk_add_f32 v[172:173], v[172:173], s[78:79]
	v_pk_add_f32 v[206:207], v[206:207], s[78:79]
	v_rcp_f32_e32 v164, v164
	v_rcp_f32_e32 v170, v170
	v_rcp_f32_e32 v172, v172
	v_rcp_f32_e32 v206, v206
	v_rcp_f32_e32 v165, v165
	v_rcp_f32_e32 v171, v171
	v_rcp_f32_e32 v173, v173
	v_rcp_f32_e32 v207, v207
	s_nop 0
	v_pk_mul_f32 v[128:129], v[128:129], v[164:165]
	v_pk_mul_f32 v[130:131], v[130:131], v[170:171]
	v_pk_mul_f32 v[124:125], v[124:125], v[172:173]
	v_pk_mul_f32 v[126:127], v[126:127], v[206:207]
	v_cvt_pk_bf16_f32 v128, v128, v129
	v_cvt_pk_bf16_f32 v129, v130, v131
	v_cvt_pk_bf16_f32 v130, v124, v125
	v_cvt_pk_bf16_f32 v131, v126, v127
	global_store_dwordx4 v221, v[128:131], s[98:99]
	v_lshlrev_b32_e32 v164, 16, v136
	v_lshlrev_b32_e32 v170, 16, v137
	v_lshlrev_b32_e32 v172, 16, v138
	v_lshlrev_b32_e32 v206, 16, v139
	v_and_b32_e32 v165, 0xffff0000, v136
	v_and_b32_e32 v171, 0xffff0000, v137
	v_and_b32_e32 v173, 0xffff0000, v138
	v_and_b32_e32 v207, 0xffff0000, v139
	v_pk_mul_f32 v[164:165], v[164:165], s[60:61]
	v_pk_mul_f32 v[170:171], v[170:171], s[60:61]
	v_pk_mul_f32 v[172:173], v[172:173], s[60:61]
	v_pk_mul_f32 v[206:207], v[206:207], s[60:61]
	v_exp_f32_e32 v164, v164
	v_exp_f32_e32 v170, v170
	v_exp_f32_e32 v172, v172
	v_exp_f32_e32 v206, v206
	v_exp_f32_e32 v165, v165
	v_exp_f32_e32 v171, v171
	v_exp_f32_e32 v173, v173
	v_exp_f32_e32 v207, v207
	v_pk_add_f32 v[164:165], v[164:165], s[78:79]
	v_pk_add_f32 v[170:171], v[170:171], s[78:79]
	v_pk_add_f32 v[172:173], v[172:173], s[78:79]
	v_pk_add_f32 v[206:207], v[206:207], s[78:79]
	v_rcp_f32_e32 v164, v164
	v_rcp_f32_e32 v170, v170
	v_rcp_f32_e32 v172, v172
	v_rcp_f32_e32 v206, v206
	v_rcp_f32_e32 v165, v165
	v_rcp_f32_e32 v171, v171
	v_rcp_f32_e32 v173, v173
	v_rcp_f32_e32 v207, v207
	s_nop 0
	v_pk_mul_f32 v[120:121], v[120:121], v[164:165]
	v_pk_mul_f32 v[122:123], v[122:123], v[170:171]
	v_pk_mul_f32 v[116:117], v[116:117], v[172:173]
	v_pk_mul_f32 v[118:119], v[118:119], v[206:207]
	v_cvt_pk_bf16_f32 v120, v120, v121
	v_cvt_pk_bf16_f32 v121, v122, v123
	v_cvt_pk_bf16_f32 v122, v116, v117
	v_cvt_pk_bf16_f32 v123, v118, v119
	global_store_dwordx4 v221, v[120:123], s[98:99] offset:256
	s_add_u32 s98, s26, 0x8000
	s_addc_u32 s99, s27, 0
	v_lshlrev_b32_e32 v164, 16, v140
	v_lshlrev_b32_e32 v170, 16, v141
	v_lshlrev_b32_e32 v172, 16, v142
	v_lshlrev_b32_e32 v206, 16, v143
	v_and_b32_e32 v165, 0xffff0000, v140
	v_and_b32_e32 v171, 0xffff0000, v141
	v_and_b32_e32 v173, 0xffff0000, v142
	v_and_b32_e32 v207, 0xffff0000, v143
	v_pk_mul_f32 v[164:165], v[164:165], s[60:61]
	v_pk_mul_f32 v[170:171], v[170:171], s[60:61]
	v_pk_mul_f32 v[172:173], v[172:173], s[60:61]
	v_pk_mul_f32 v[206:207], v[206:207], s[60:61]
	v_exp_f32_e32 v164, v164
	v_exp_f32_e32 v170, v170
	v_exp_f32_e32 v172, v172
	v_exp_f32_e32 v206, v206
	v_exp_f32_e32 v165, v165
	v_exp_f32_e32 v171, v171
	v_exp_f32_e32 v173, v173
	v_exp_f32_e32 v207, v207
	v_pk_add_f32 v[164:165], v[164:165], s[78:79]
	v_pk_add_f32 v[170:171], v[170:171], s[78:79]
	v_pk_add_f32 v[172:173], v[172:173], s[78:79]
	v_pk_add_f32 v[206:207], v[206:207], s[78:79]
	v_rcp_f32_e32 v164, v164
	v_rcp_f32_e32 v170, v170
	v_rcp_f32_e32 v172, v172
	v_rcp_f32_e32 v206, v206
	v_rcp_f32_e32 v165, v165
	v_rcp_f32_e32 v171, v171
	v_rcp_f32_e32 v173, v173
	v_rcp_f32_e32 v207, v207
	s_nop 0
	v_pk_mul_f32 v[112:113], v[112:113], v[164:165]
	v_pk_mul_f32 v[114:115], v[114:115], v[170:171]
	v_pk_mul_f32 v[108:109], v[108:109], v[172:173]
	v_pk_mul_f32 v[110:111], v[110:111], v[206:207]
	v_cvt_pk_bf16_f32 v112, v112, v113
	v_cvt_pk_bf16_f32 v113, v114, v115
	v_cvt_pk_bf16_f32 v114, v108, v109
	v_cvt_pk_bf16_f32 v115, v110, v111
	global_store_dwordx4 v221, v[112:115], s[98:99]
	v_lshlrev_b32_e32 v164, 16, v144
	v_lshlrev_b32_e32 v170, 16, v145
	v_lshlrev_b32_e32 v172, 16, v146
	v_lshlrev_b32_e32 v206, 16, v147
	v_and_b32_e32 v165, 0xffff0000, v144
	v_and_b32_e32 v171, 0xffff0000, v145
	v_and_b32_e32 v173, 0xffff0000, v146
	v_and_b32_e32 v207, 0xffff0000, v147
	v_pk_mul_f32 v[164:165], v[164:165], s[60:61]
	v_pk_mul_f32 v[170:171], v[170:171], s[60:61]
	v_pk_mul_f32 v[172:173], v[172:173], s[60:61]
	v_pk_mul_f32 v[206:207], v[206:207], s[60:61]
	v_exp_f32_e32 v164, v164
	v_exp_f32_e32 v170, v170
	v_exp_f32_e32 v172, v172
	v_exp_f32_e32 v206, v206
	v_exp_f32_e32 v165, v165
	v_exp_f32_e32 v171, v171
	v_exp_f32_e32 v173, v173
	v_exp_f32_e32 v207, v207
	v_pk_add_f32 v[164:165], v[164:165], s[78:79]
	v_pk_add_f32 v[170:171], v[170:171], s[78:79]
	v_pk_add_f32 v[172:173], v[172:173], s[78:79]
	v_pk_add_f32 v[206:207], v[206:207], s[78:79]
	v_rcp_f32_e32 v164, v164
	v_rcp_f32_e32 v170, v170
	v_rcp_f32_e32 v172, v172
	v_rcp_f32_e32 v206, v206
	v_rcp_f32_e32 v165, v165
	v_rcp_f32_e32 v171, v171
	v_rcp_f32_e32 v173, v173
	v_rcp_f32_e32 v207, v207
	s_nop 0
	v_pk_mul_f32 v[104:105], v[104:105], v[164:165]
	v_pk_mul_f32 v[106:107], v[106:107], v[170:171]
	v_pk_mul_f32 v[100:101], v[100:101], v[172:173]
	v_pk_mul_f32 v[102:103], v[102:103], v[206:207]
	v_cvt_pk_bf16_f32 v104, v104, v105
	v_cvt_pk_bf16_f32 v105, v106, v107
	v_cvt_pk_bf16_f32 v106, v100, v101
	v_cvt_pk_bf16_f32 v107, v102, v103
	global_store_dwordx4 v221, v[104:107], s[98:99] offset:256
	s_add_u32 s8, s24, 0x10000
	s_addc_u32 s9, s25, 0
	global_load_dwordx4 v[132:135], v216, s[8:9]
	global_load_dwordx4 v[136:139], v216, s[8:9] offset:256
	s_add_u32 s8, s24, 0x12000
	s_addc_u32 s9, s25, 0
	global_load_dwordx4 v[140:143], v216, s[8:9]
	global_load_dwordx4 v[144:147], v216, s[8:9] offset:256
	s_waitcnt vmcnt(8)
	s_add_u32 s98, s26, 0x10000
	s_addc_u32 s99, s27, 0
	v_lshlrev_b32_e32 v164, 16, v224
	v_lshlrev_b32_e32 v170, 16, v225
	v_lshlrev_b32_e32 v172, 16, v226
	v_lshlrev_b32_e32 v206, 16, v227
	v_and_b32_e32 v165, 0xffff0000, v224
	v_and_b32_e32 v171, 0xffff0000, v225
	v_and_b32_e32 v173, 0xffff0000, v226
	v_and_b32_e32 v207, 0xffff0000, v227
	v_pk_mul_f32 v[164:165], v[164:165], s[60:61]
	v_pk_mul_f32 v[170:171], v[170:171], s[60:61]
	v_pk_mul_f32 v[172:173], v[172:173], s[60:61]
	v_pk_mul_f32 v[206:207], v[206:207], s[60:61]
	v_exp_f32_e32 v164, v164
	v_exp_f32_e32 v170, v170
	v_exp_f32_e32 v172, v172
	v_exp_f32_e32 v206, v206
	v_exp_f32_e32 v165, v165
	v_exp_f32_e32 v171, v171
	v_exp_f32_e32 v173, v173
	v_exp_f32_e32 v207, v207
	v_pk_add_f32 v[164:165], v[164:165], s[78:79]
	v_pk_add_f32 v[170:171], v[170:171], s[78:79]
	v_pk_add_f32 v[172:173], v[172:173], s[78:79]
	v_pk_add_f32 v[206:207], v[206:207], s[78:79]
	v_rcp_f32_e32 v164, v164
	v_rcp_f32_e32 v170, v170
	v_rcp_f32_e32 v172, v172
	v_rcp_f32_e32 v206, v206
	v_rcp_f32_e32 v165, v165
	v_rcp_f32_e32 v171, v171
	v_rcp_f32_e32 v173, v173
	v_rcp_f32_e32 v207, v207
	s_nop 0
	v_pk_mul_f32 v[96:97], v[96:97], v[164:165]
	v_pk_mul_f32 v[98:99], v[98:99], v[170:171]
	v_pk_mul_f32 v[92:93], v[92:93], v[172:173]
	v_pk_mul_f32 v[94:95], v[94:95], v[206:207]
	v_cvt_pk_bf16_f32 v96, v96, v97
	v_cvt_pk_bf16_f32 v97, v98, v99
	v_cvt_pk_bf16_f32 v98, v92, v93
	v_cvt_pk_bf16_f32 v99, v94, v95
	global_store_dwordx4 v221, v[96:99], s[98:99]
	v_lshlrev_b32_e32 v164, 16, v228
	v_lshlrev_b32_e32 v170, 16, v229
	v_lshlrev_b32_e32 v172, 16, v230
	v_lshlrev_b32_e32 v206, 16, v231
	v_and_b32_e32 v165, 0xffff0000, v228
	v_and_b32_e32 v171, 0xffff0000, v229
	v_and_b32_e32 v173, 0xffff0000, v230
	v_and_b32_e32 v207, 0xffff0000, v231
	v_pk_mul_f32 v[164:165], v[164:165], s[60:61]
	v_pk_mul_f32 v[170:171], v[170:171], s[60:61]
	v_pk_mul_f32 v[172:173], v[172:173], s[60:61]
	v_pk_mul_f32 v[206:207], v[206:207], s[60:61]
	v_exp_f32_e32 v164, v164
	v_exp_f32_e32 v170, v170
	v_exp_f32_e32 v172, v172
	v_exp_f32_e32 v206, v206
	v_exp_f32_e32 v165, v165
	v_exp_f32_e32 v171, v171
	v_exp_f32_e32 v173, v173
	v_exp_f32_e32 v207, v207
	v_pk_add_f32 v[164:165], v[164:165], s[78:79]
	v_pk_add_f32 v[170:171], v[170:171], s[78:79]
	v_pk_add_f32 v[172:173], v[172:173], s[78:79]
	v_pk_add_f32 v[206:207], v[206:207], s[78:79]
	v_rcp_f32_e32 v164, v164
	v_rcp_f32_e32 v170, v170
	v_rcp_f32_e32 v172, v172
	v_rcp_f32_e32 v206, v206
	v_rcp_f32_e32 v165, v165
	v_rcp_f32_e32 v171, v171
	v_rcp_f32_e32 v173, v173
	v_rcp_f32_e32 v207, v207
	s_nop 0
	v_pk_mul_f32 v[88:89], v[88:89], v[164:165]
	v_pk_mul_f32 v[90:91], v[90:91], v[170:171]
	v_pk_mul_f32 v[84:85], v[84:85], v[172:173]
	v_pk_mul_f32 v[86:87], v[86:87], v[206:207]
	v_cvt_pk_bf16_f32 v88, v88, v89
	v_cvt_pk_bf16_f32 v89, v90, v91
	v_cvt_pk_bf16_f32 v90, v84, v85
	v_cvt_pk_bf16_f32 v91, v86, v87
	global_store_dwordx4 v221, v[88:91], s[98:99] offset:256
	s_add_u32 s98, s26, 0x18000
	s_addc_u32 s99, s27, 0
	v_lshlrev_b32_e32 v164, 16, v232
	v_lshlrev_b32_e32 v170, 16, v233
	v_lshlrev_b32_e32 v172, 16, v234
	v_lshlrev_b32_e32 v206, 16, v235
	v_and_b32_e32 v165, 0xffff0000, v232
	v_and_b32_e32 v171, 0xffff0000, v233
	v_and_b32_e32 v173, 0xffff0000, v234
	v_and_b32_e32 v207, 0xffff0000, v235
	v_pk_mul_f32 v[164:165], v[164:165], s[60:61]
	v_pk_mul_f32 v[170:171], v[170:171], s[60:61]
	v_pk_mul_f32 v[172:173], v[172:173], s[60:61]
	v_pk_mul_f32 v[206:207], v[206:207], s[60:61]
	v_exp_f32_e32 v164, v164
	v_exp_f32_e32 v170, v170
	v_exp_f32_e32 v172, v172
	v_exp_f32_e32 v206, v206
	v_exp_f32_e32 v165, v165
	v_exp_f32_e32 v171, v171
	v_exp_f32_e32 v173, v173
	v_exp_f32_e32 v207, v207
	v_pk_add_f32 v[164:165], v[164:165], s[78:79]
	v_pk_add_f32 v[170:171], v[170:171], s[78:79]
	v_pk_add_f32 v[172:173], v[172:173], s[78:79]
	v_pk_add_f32 v[206:207], v[206:207], s[78:79]
	v_rcp_f32_e32 v164, v164
	v_rcp_f32_e32 v170, v170
	v_rcp_f32_e32 v172, v172
	v_rcp_f32_e32 v206, v206
	v_rcp_f32_e32 v165, v165
	v_rcp_f32_e32 v171, v171
	v_rcp_f32_e32 v173, v173
	v_rcp_f32_e32 v207, v207
	s_nop 0
	v_pk_mul_f32 v[76:77], v[76:77], v[164:165]
	v_pk_mul_f32 v[78:79], v[78:79], v[170:171]
	v_pk_mul_f32 v[72:73], v[72:73], v[172:173]
	v_pk_mul_f32 v[74:75], v[74:75], v[206:207]
	v_cvt_pk_bf16_f32 v76, v76, v77
	v_cvt_pk_bf16_f32 v77, v78, v79
	v_cvt_pk_bf16_f32 v78, v72, v73
	v_cvt_pk_bf16_f32 v79, v74, v75
	global_store_dwordx4 v221, v[76:79], s[98:99]
	v_lshlrev_b32_e32 v164, 16, v236
	v_lshlrev_b32_e32 v170, 16, v237
	v_lshlrev_b32_e32 v172, 16, v238
	v_lshlrev_b32_e32 v206, 16, v239
	v_and_b32_e32 v165, 0xffff0000, v236
	v_and_b32_e32 v171, 0xffff0000, v237
	v_and_b32_e32 v173, 0xffff0000, v238
	v_and_b32_e32 v207, 0xffff0000, v239
	v_pk_mul_f32 v[164:165], v[164:165], s[60:61]
	v_pk_mul_f32 v[170:171], v[170:171], s[60:61]
	v_pk_mul_f32 v[172:173], v[172:173], s[60:61]
	v_pk_mul_f32 v[206:207], v[206:207], s[60:61]
	v_exp_f32_e32 v164, v164
	v_exp_f32_e32 v170, v170
	v_exp_f32_e32 v172, v172
	v_exp_f32_e32 v206, v206
	v_exp_f32_e32 v165, v165
	v_exp_f32_e32 v171, v171
	v_exp_f32_e32 v173, v173
	v_exp_f32_e32 v207, v207
	v_pk_add_f32 v[164:165], v[164:165], s[78:79]
	v_pk_add_f32 v[170:171], v[170:171], s[78:79]
	v_pk_add_f32 v[172:173], v[172:173], s[78:79]
	v_pk_add_f32 v[206:207], v[206:207], s[78:79]
	v_rcp_f32_e32 v164, v164
	v_rcp_f32_e32 v170, v170
	v_rcp_f32_e32 v172, v172
	v_rcp_f32_e32 v206, v206
	v_rcp_f32_e32 v165, v165
	v_rcp_f32_e32 v171, v171
	v_rcp_f32_e32 v173, v173
	v_rcp_f32_e32 v207, v207
	s_nop 0
	v_pk_mul_f32 v[68:69], v[68:69], v[164:165]
	v_pk_mul_f32 v[70:71], v[70:71], v[170:171]
	v_pk_mul_f32 v[64:65], v[64:65], v[172:173]
	v_pk_mul_f32 v[66:67], v[66:67], v[206:207]
	v_cvt_pk_bf16_f32 v68, v68, v69
	v_cvt_pk_bf16_f32 v69, v70, v71
	v_cvt_pk_bf16_f32 v70, v64, v65
	v_cvt_pk_bf16_f32 v71, v66, v67
	global_store_dwordx4 v221, v[68:71], s[98:99] offset:256
	s_add_u32 s8, s24, 0x14000
	s_addc_u32 s9, s25, 0
	global_load_dwordx4 v[224:227], v216, s[8:9]
	global_load_dwordx4 v[228:231], v216, s[8:9] offset:256
	s_add_u32 s8, s24, 0x16000
	s_addc_u32 s9, s25, 0
	global_load_dwordx4 v[232:235], v216, s[8:9]
	global_load_dwordx4 v[236:239], v216, s[8:9] offset:256
	s_waitcnt vmcnt(8)
	s_add_u32 s98, s26, 0x40000
	s_addc_u32 s99, s27, 0
	v_lshlrev_b32_e32 v164, 16, v132
	v_lshlrev_b32_e32 v170, 16, v133
	v_lshlrev_b32_e32 v172, 16, v134
	v_lshlrev_b32_e32 v206, 16, v135
	v_and_b32_e32 v165, 0xffff0000, v132
	v_and_b32_e32 v171, 0xffff0000, v133
	v_and_b32_e32 v173, 0xffff0000, v134
	v_and_b32_e32 v207, 0xffff0000, v135
	v_pk_mul_f32 v[164:165], v[164:165], s[60:61]
	v_pk_mul_f32 v[170:171], v[170:171], s[60:61]
	v_pk_mul_f32 v[172:173], v[172:173], s[60:61]
	v_pk_mul_f32 v[206:207], v[206:207], s[60:61]
	v_exp_f32_e32 v164, v164
	v_exp_f32_e32 v170, v170
	v_exp_f32_e32 v172, v172
	v_exp_f32_e32 v206, v206
	v_exp_f32_e32 v165, v165
	v_exp_f32_e32 v171, v171
	v_exp_f32_e32 v173, v173
	v_exp_f32_e32 v207, v207
	v_pk_add_f32 v[164:165], v[164:165], s[78:79]
	v_pk_add_f32 v[170:171], v[170:171], s[78:79]
	v_pk_add_f32 v[172:173], v[172:173], s[78:79]
	v_pk_add_f32 v[206:207], v[206:207], s[78:79]
	v_rcp_f32_e32 v164, v164
	v_rcp_f32_e32 v170, v170
	v_rcp_f32_e32 v172, v172
	v_rcp_f32_e32 v206, v206
	v_rcp_f32_e32 v165, v165
	v_rcp_f32_e32 v171, v171
	v_rcp_f32_e32 v173, v173
	v_rcp_f32_e32 v207, v207
	s_nop 0
	v_pk_mul_f32 v[60:61], v[60:61], v[164:165]
	v_pk_mul_f32 v[62:63], v[62:63], v[170:171]
	v_pk_mul_f32 v[56:57], v[56:57], v[172:173]
	v_pk_mul_f32 v[58:59], v[58:59], v[206:207]
	v_cvt_pk_bf16_f32 v60, v60, v61
	v_cvt_pk_bf16_f32 v61, v62, v63
	v_cvt_pk_bf16_f32 v62, v56, v57
	v_cvt_pk_bf16_f32 v63, v58, v59
	global_store_dwordx4 v221, v[60:63], s[98:99]
	v_lshlrev_b32_e32 v164, 16, v136
	v_lshlrev_b32_e32 v170, 16, v137
	v_lshlrev_b32_e32 v172, 16, v138
	v_lshlrev_b32_e32 v206, 16, v139
	v_and_b32_e32 v165, 0xffff0000, v136
	v_and_b32_e32 v171, 0xffff0000, v137
	v_and_b32_e32 v173, 0xffff0000, v138
	v_and_b32_e32 v207, 0xffff0000, v139
	v_pk_mul_f32 v[164:165], v[164:165], s[60:61]
	v_pk_mul_f32 v[170:171], v[170:171], s[60:61]
	v_pk_mul_f32 v[172:173], v[172:173], s[60:61]
	v_pk_mul_f32 v[206:207], v[206:207], s[60:61]
	v_exp_f32_e32 v164, v164
	v_exp_f32_e32 v170, v170
	v_exp_f32_e32 v172, v172
	v_exp_f32_e32 v206, v206
	v_exp_f32_e32 v165, v165
	v_exp_f32_e32 v171, v171
	v_exp_f32_e32 v173, v173
	v_exp_f32_e32 v207, v207
	v_pk_add_f32 v[164:165], v[164:165], s[78:79]
	v_pk_add_f32 v[170:171], v[170:171], s[78:79]
	v_pk_add_f32 v[172:173], v[172:173], s[78:79]
	v_pk_add_f32 v[206:207], v[206:207], s[78:79]
	v_rcp_f32_e32 v164, v164
	v_rcp_f32_e32 v170, v170
	v_rcp_f32_e32 v172, v172
	v_rcp_f32_e32 v206, v206
	v_rcp_f32_e32 v165, v165
	v_rcp_f32_e32 v171, v171
	v_rcp_f32_e32 v173, v173
	v_rcp_f32_e32 v207, v207
	s_nop 0
	v_pk_mul_f32 v[52:53], v[52:53], v[164:165]
	v_pk_mul_f32 v[54:55], v[54:55], v[170:171]
	v_pk_mul_f32 v[48:49], v[48:49], v[172:173]
	v_pk_mul_f32 v[50:51], v[50:51], v[206:207]
	v_cvt_pk_bf16_f32 v52, v52, v53
	v_cvt_pk_bf16_f32 v53, v54, v55
	v_cvt_pk_bf16_f32 v54, v48, v49
	v_cvt_pk_bf16_f32 v55, v50, v51
	global_store_dwordx4 v221, v[52:55], s[98:99] offset:256
	s_add_u32 s98, s26, 0x48000
	s_addc_u32 s99, s27, 0
	v_lshlrev_b32_e32 v164, 16, v140
	v_lshlrev_b32_e32 v170, 16, v141
	v_lshlrev_b32_e32 v172, 16, v142
	v_lshlrev_b32_e32 v206, 16, v143
	v_and_b32_e32 v165, 0xffff0000, v140
	v_and_b32_e32 v171, 0xffff0000, v141
	v_and_b32_e32 v173, 0xffff0000, v142
	v_and_b32_e32 v207, 0xffff0000, v143
	v_pk_mul_f32 v[164:165], v[164:165], s[60:61]
	v_pk_mul_f32 v[170:171], v[170:171], s[60:61]
	v_pk_mul_f32 v[172:173], v[172:173], s[60:61]
	v_pk_mul_f32 v[206:207], v[206:207], s[60:61]
	v_exp_f32_e32 v164, v164
	v_exp_f32_e32 v170, v170
	v_exp_f32_e32 v172, v172
	v_exp_f32_e32 v206, v206
	v_exp_f32_e32 v165, v165
	v_exp_f32_e32 v171, v171
	v_exp_f32_e32 v173, v173
	v_exp_f32_e32 v207, v207
	v_pk_add_f32 v[164:165], v[164:165], s[78:79]
	v_pk_add_f32 v[170:171], v[170:171], s[78:79]
	v_pk_add_f32 v[172:173], v[172:173], s[78:79]
	v_pk_add_f32 v[206:207], v[206:207], s[78:79]
	v_rcp_f32_e32 v164, v164
	v_rcp_f32_e32 v170, v170
	v_rcp_f32_e32 v172, v172
	v_rcp_f32_e32 v206, v206
	v_rcp_f32_e32 v165, v165
	v_rcp_f32_e32 v171, v171
	v_rcp_f32_e32 v173, v173
	v_rcp_f32_e32 v207, v207
	s_nop 0
	v_pk_mul_f32 v[44:45], v[44:45], v[164:165]
	v_pk_mul_f32 v[46:47], v[46:47], v[170:171]
	v_pk_mul_f32 v[40:41], v[40:41], v[172:173]
	v_pk_mul_f32 v[42:43], v[42:43], v[206:207]
	v_cvt_pk_bf16_f32 v44, v44, v45
	v_cvt_pk_bf16_f32 v45, v46, v47
	v_cvt_pk_bf16_f32 v46, v40, v41
	v_cvt_pk_bf16_f32 v47, v42, v43
	global_store_dwordx4 v221, v[44:47], s[98:99]
	v_lshlrev_b32_e32 v164, 16, v144
	v_lshlrev_b32_e32 v170, 16, v145
	v_lshlrev_b32_e32 v172, 16, v146
	v_lshlrev_b32_e32 v206, 16, v147
	v_and_b32_e32 v165, 0xffff0000, v144
	v_and_b32_e32 v171, 0xffff0000, v145
	v_and_b32_e32 v173, 0xffff0000, v146
	v_and_b32_e32 v207, 0xffff0000, v147
	v_pk_mul_f32 v[164:165], v[164:165], s[60:61]
	v_pk_mul_f32 v[170:171], v[170:171], s[60:61]
	v_pk_mul_f32 v[172:173], v[172:173], s[60:61]
	v_pk_mul_f32 v[206:207], v[206:207], s[60:61]
	v_exp_f32_e32 v164, v164
	v_exp_f32_e32 v170, v170
	v_exp_f32_e32 v172, v172
	v_exp_f32_e32 v206, v206
	v_exp_f32_e32 v165, v165
	v_exp_f32_e32 v171, v171
	v_exp_f32_e32 v173, v173
	v_exp_f32_e32 v207, v207
	v_pk_add_f32 v[164:165], v[164:165], s[78:79]
	v_pk_add_f32 v[170:171], v[170:171], s[78:79]
	v_pk_add_f32 v[172:173], v[172:173], s[78:79]
	v_pk_add_f32 v[206:207], v[206:207], s[78:79]
	v_rcp_f32_e32 v164, v164
	v_rcp_f32_e32 v170, v170
	v_rcp_f32_e32 v172, v172
	v_rcp_f32_e32 v206, v206
	v_rcp_f32_e32 v165, v165
	v_rcp_f32_e32 v171, v171
	v_rcp_f32_e32 v173, v173
	v_rcp_f32_e32 v207, v207
	s_nop 0
	v_pk_mul_f32 v[36:37], v[36:37], v[164:165]
	v_pk_mul_f32 v[38:39], v[38:39], v[170:171]
	v_pk_mul_f32 v[32:33], v[32:33], v[172:173]
	v_pk_mul_f32 v[34:35], v[34:35], v[206:207]
	v_cvt_pk_bf16_f32 v36, v36, v37
	v_cvt_pk_bf16_f32 v37, v38, v39
	v_cvt_pk_bf16_f32 v38, v32, v33
	v_cvt_pk_bf16_f32 v39, v34, v35
	global_store_dwordx4 v221, v[36:39], s[98:99] offset:256
	s_waitcnt vmcnt(4)
	s_add_u32 s98, s26, 0x50000
	s_addc_u32 s99, s27, 0
	v_lshlrev_b32_e32 v164, 16, v224
	v_lshlrev_b32_e32 v170, 16, v225
	v_lshlrev_b32_e32 v172, 16, v226
	v_lshlrev_b32_e32 v206, 16, v227
	v_and_b32_e32 v165, 0xffff0000, v224
	v_and_b32_e32 v171, 0xffff0000, v225
	v_and_b32_e32 v173, 0xffff0000, v226
	v_and_b32_e32 v207, 0xffff0000, v227
	v_pk_mul_f32 v[164:165], v[164:165], s[60:61]
	v_pk_mul_f32 v[170:171], v[170:171], s[60:61]
	v_pk_mul_f32 v[172:173], v[172:173], s[60:61]
	v_pk_mul_f32 v[206:207], v[206:207], s[60:61]
	v_exp_f32_e32 v164, v164
	v_exp_f32_e32 v170, v170
	v_exp_f32_e32 v172, v172
	v_exp_f32_e32 v206, v206
	v_exp_f32_e32 v165, v165
	v_exp_f32_e32 v171, v171
	v_exp_f32_e32 v173, v173
	v_exp_f32_e32 v207, v207
	v_pk_add_f32 v[164:165], v[164:165], s[78:79]
	v_pk_add_f32 v[170:171], v[170:171], s[78:79]
	v_pk_add_f32 v[172:173], v[172:173], s[78:79]
	v_pk_add_f32 v[206:207], v[206:207], s[78:79]
	v_rcp_f32_e32 v164, v164
	v_rcp_f32_e32 v170, v170
	v_rcp_f32_e32 v172, v172
	v_rcp_f32_e32 v206, v206
	v_rcp_f32_e32 v165, v165
	v_rcp_f32_e32 v171, v171
	v_rcp_f32_e32 v173, v173
	v_rcp_f32_e32 v207, v207
	s_nop 0
	v_pk_mul_f32 v[28:29], v[28:29], v[164:165]
	v_pk_mul_f32 v[30:31], v[30:31], v[170:171]
	v_pk_mul_f32 v[24:25], v[24:25], v[172:173]
	v_pk_mul_f32 v[26:27], v[26:27], v[206:207]
	v_cvt_pk_bf16_f32 v28, v28, v29
	v_cvt_pk_bf16_f32 v29, v30, v31
	v_cvt_pk_bf16_f32 v30, v24, v25
	v_cvt_pk_bf16_f32 v31, v26, v27
	global_store_dwordx4 v221, v[28:31], s[98:99]
	v_lshlrev_b32_e32 v164, 16, v228
	v_lshlrev_b32_e32 v170, 16, v229
	v_lshlrev_b32_e32 v172, 16, v230
	v_lshlrev_b32_e32 v206, 16, v231
	v_and_b32_e32 v165, 0xffff0000, v228
	v_and_b32_e32 v171, 0xffff0000, v229
	v_and_b32_e32 v173, 0xffff0000, v230
	v_and_b32_e32 v207, 0xffff0000, v231
	v_pk_mul_f32 v[164:165], v[164:165], s[60:61]
	v_pk_mul_f32 v[170:171], v[170:171], s[60:61]
	v_pk_mul_f32 v[172:173], v[172:173], s[60:61]
	v_pk_mul_f32 v[206:207], v[206:207], s[60:61]
	v_exp_f32_e32 v164, v164
	v_exp_f32_e32 v170, v170
	v_exp_f32_e32 v172, v172
	v_exp_f32_e32 v206, v206
	v_exp_f32_e32 v165, v165
	v_exp_f32_e32 v171, v171
	v_exp_f32_e32 v173, v173
	v_exp_f32_e32 v207, v207
	v_pk_add_f32 v[164:165], v[164:165], s[78:79]
	v_pk_add_f32 v[170:171], v[170:171], s[78:79]
	v_pk_add_f32 v[172:173], v[172:173], s[78:79]
	v_pk_add_f32 v[206:207], v[206:207], s[78:79]
	v_rcp_f32_e32 v164, v164
	v_rcp_f32_e32 v170, v170
	v_rcp_f32_e32 v172, v172
	v_rcp_f32_e32 v206, v206
	v_rcp_f32_e32 v165, v165
	v_rcp_f32_e32 v171, v171
	v_rcp_f32_e32 v173, v173
	v_rcp_f32_e32 v207, v207
	s_nop 0
	v_pk_mul_f32 v[20:21], v[20:21], v[164:165]
	v_pk_mul_f32 v[22:23], v[22:23], v[170:171]
	v_pk_mul_f32 v[16:17], v[16:17], v[172:173]
	v_pk_mul_f32 v[18:19], v[18:19], v[206:207]
	v_cvt_pk_bf16_f32 v20, v20, v21
	v_cvt_pk_bf16_f32 v21, v22, v23
	v_cvt_pk_bf16_f32 v22, v16, v17
	v_cvt_pk_bf16_f32 v23, v18, v19
	global_store_dwordx4 v221, v[20:23], s[98:99] offset:256
	s_add_u32 s98, s26, 0x58000
	s_addc_u32 s99, s27, 0
	v_lshlrev_b32_e32 v164, 16, v232
	v_lshlrev_b32_e32 v170, 16, v233
	v_lshlrev_b32_e32 v172, 16, v234
	v_lshlrev_b32_e32 v206, 16, v235
	v_and_b32_e32 v165, 0xffff0000, v232
	v_and_b32_e32 v171, 0xffff0000, v233
	v_and_b32_e32 v173, 0xffff0000, v234
	v_and_b32_e32 v207, 0xffff0000, v235
	v_pk_mul_f32 v[164:165], v[164:165], s[60:61]
	v_pk_mul_f32 v[170:171], v[170:171], s[60:61]
	v_pk_mul_f32 v[172:173], v[172:173], s[60:61]
	v_pk_mul_f32 v[206:207], v[206:207], s[60:61]
	v_exp_f32_e32 v164, v164
	v_exp_f32_e32 v170, v170
	v_exp_f32_e32 v172, v172
	v_exp_f32_e32 v206, v206
	v_exp_f32_e32 v165, v165
	v_exp_f32_e32 v171, v171
	v_exp_f32_e32 v173, v173
	v_exp_f32_e32 v207, v207
	v_pk_add_f32 v[164:165], v[164:165], s[78:79]
	v_pk_add_f32 v[170:171], v[170:171], s[78:79]
	v_pk_add_f32 v[172:173], v[172:173], s[78:79]
	v_pk_add_f32 v[206:207], v[206:207], s[78:79]
	v_rcp_f32_e32 v164, v164
	v_rcp_f32_e32 v170, v170
	v_rcp_f32_e32 v172, v172
	v_rcp_f32_e32 v206, v206
	v_rcp_f32_e32 v165, v165
	v_rcp_f32_e32 v171, v171
	v_rcp_f32_e32 v173, v173
	v_rcp_f32_e32 v207, v207
	s_nop 0
	v_pk_mul_f32 v[12:13], v[12:13], v[164:165]
	v_pk_mul_f32 v[14:15], v[14:15], v[170:171]
	v_pk_mul_f32 v[8:9], v[8:9], v[172:173]
	v_pk_mul_f32 v[10:11], v[10:11], v[206:207]
	v_cvt_pk_bf16_f32 v12, v12, v13
	v_cvt_pk_bf16_f32 v13, v14, v15
	v_cvt_pk_bf16_f32 v14, v8, v9
	v_cvt_pk_bf16_f32 v15, v10, v11
	global_store_dwordx4 v221, v[12:15], s[98:99]
	v_lshlrev_b32_e32 v164, 16, v236
	v_lshlrev_b32_e32 v170, 16, v237
	v_lshlrev_b32_e32 v172, 16, v238
	v_lshlrev_b32_e32 v206, 16, v239
	v_and_b32_e32 v165, 0xffff0000, v236
	v_and_b32_e32 v171, 0xffff0000, v237
	v_and_b32_e32 v173, 0xffff0000, v238
	v_and_b32_e32 v207, 0xffff0000, v239
	v_pk_mul_f32 v[164:165], v[164:165], s[60:61]
	v_pk_mul_f32 v[170:171], v[170:171], s[60:61]
	v_pk_mul_f32 v[172:173], v[172:173], s[60:61]
	v_pk_mul_f32 v[206:207], v[206:207], s[60:61]
	v_exp_f32_e32 v164, v164
	v_exp_f32_e32 v170, v170
	v_exp_f32_e32 v172, v172
	v_exp_f32_e32 v206, v206
	v_exp_f32_e32 v165, v165
	v_exp_f32_e32 v171, v171
	v_exp_f32_e32 v173, v173
	v_exp_f32_e32 v207, v207
	v_pk_add_f32 v[164:165], v[164:165], s[78:79]
	v_pk_add_f32 v[170:171], v[170:171], s[78:79]
	v_pk_add_f32 v[172:173], v[172:173], s[78:79]
	v_pk_add_f32 v[206:207], v[206:207], s[78:79]
	v_rcp_f32_e32 v164, v164
	v_rcp_f32_e32 v170, v170
	v_rcp_f32_e32 v172, v172
	v_rcp_f32_e32 v206, v206
	v_rcp_f32_e32 v165, v165
	v_rcp_f32_e32 v171, v171
	v_rcp_f32_e32 v173, v173
	v_rcp_f32_e32 v207, v207
	s_nop 0
	v_pk_mul_f32 v[4:5], v[4:5], v[164:165]
	v_pk_mul_f32 v[6:7], v[6:7], v[170:171]
	v_pk_mul_f32 v[0:1], v[0:1], v[172:173]
	v_pk_mul_f32 v[2:3], v[2:3], v[206:207]
	v_cvt_pk_bf16_f32 v4, v4, v5
	v_cvt_pk_bf16_f32 v5, v6, v7
	v_cvt_pk_bf16_f32 v6, v0, v1
	v_cvt_pk_bf16_f32 v7, v2, v3
	global_store_dwordx4 v221, v[4:7], s[98:99] offset:256
	s_branch .Lp6e_done
	s_lshl_b32 s9, s46, 2
	s_mul_i32 s8, s48, 49
	s_add_i32 s9, s47, s9
	s_add_i32 s8, s9, s8
	s_add_i32 s8, s8, 29
	v_lshl_add_u32 v196, s48, 8, v169
	s_ashr_i32 s9, s8, 31
	s_lshl_b64 s[8:9], s[8:9], 17
	v_lshlrev_b32_e32 v132, 9, v196
	v_lshl_add_u64 v[198:199], v[188:189], 0, s[8:9]
	v_and_b32_e32 v166, 0x19e00, v132
	v_lshl_add_u64 v[134:135], v[198:199], 0, v[166:167]
	global_load_dwordx4 v[158:161], v[134:135], off
	v_lshl_or_b32 v194, s47, 8, v219
	v_ashrrev_i32_e32 v195, 31, v194
	v_ashrrev_i32_e32 v197, 31, v196
	v_lshl_add_u64 v[200:201], v[194:195], 1, v[176:177]
	s_cmp_gt_i32 s46, 0
	v_lshlrev_b64 v[204:205], 11, v[196:197]
	s_cselect_b64 s[24:25], -1, 0
	s_cmp_lt_i32 s46, 1
	v_lshl_add_u64 v[132:133], v[200:201], 0, v[204:205]
	s_cbranch_scc1 .LBB0_1759
	global_load_dwordx4 v[162:165], v[132:133], off
	s_branch .LBB0_1760

.LBB0_1797:
	s_load_dwordx2 s[98:99], s[62:63], 0xc0
	v_lshrrev_b32_e32 v170, 8, v208
	v_and_b32_e32 v171, 15, v208
	v_lshl_add_u32 v170, v170, 6, v171
	v_bfe_u32 v171, v208, 6, 2
	v_bfe_u32 v172, v208, 4, 2
	v_lshlrev_b32_e32 v171, 6, v171
	v_lshl_add_u32 v171, v172, 4, v171
	v_lshl_add_u32 v216, v170, 9, v171
	v_lshl_add_u32 v166, v170, 11, v171
	s_mul_i32 s0, s43, 49
	s_add_i32 s0, s0, s42
	s_add_i32 s0, s0, 45
	s_lshl_b32 s0, s0, 17
	s_lshl_b32 s32, s43, 19
	s_lshl_b32 s46, s42, 9
	s_add_i32 s32, s32, s46
	s_mov_b32 s60, 0xbfb8aa3b
	s_mov_b32 s61, 0xbfb8aa3b
	s_mov_b32 s78, 1.0
	s_mov_b32 s79, 1.0
	s_waitcnt lgkmcnt(0)
	s_add_u32 s18, s98, 0x74c2800
	s_addc_u32 s19, s99, 0
	s_add_u32 s18, s18, s0
	s_addc_u32 s19, s19, 0
	s_add_u32 s20, s98, 0x244c2800
	s_addc_u32 s21, s99, 0
	s_add_u32 s20, s20, s32
	s_addc_u32 s21, s21, 0
	s_add_u32 s48, s98, 0x5300000
	s_addc_u32 s49, s99, 0
	s_add_u32 s48, s48, s32
	s_addc_u32 s49, s49, 0
	s_add_u32 s42, s18, 0x0
	s_addc_u32 s43, s19, 0
	global_load_dwordx4 v[132:135], v216, s[42:43]
	global_load_dwordx4 v[136:139], v216, s[42:43] offset:256
	s_add_u32 s42, s18, 0x2000
	s_addc_u32 s43, s19, 0
	global_load_dwordx4 v[140:143], v216, s[42:43]
	global_load_dwordx4 v[144:147], v216, s[42:43] offset:256
	s_add_u32 s42, s20, 0x0
	s_addc_u32 s43, s21, 0
	global_load_dwordx4 v[148:151], v166, s[42:43]
	global_load_dwordx4 v[152:155], v166, s[42:43] offset:256
	s_add_u32 s42, s20, 0x8000
	s_addc_u32 s43, s21, 0
	global_load_dwordx4 v[184:187], v166, s[42:43]
	global_load_dwordx4 v[188:191], v166, s[42:43] offset:256
	s_add_u32 s42, s18, 0x4000
	s_addc_u32 s43, s19, 0
	global_load_dwordx4 v[224:227], v216, s[42:43]
	global_load_dwordx4 v[228:231], v216, s[42:43] offset:256
	s_add_u32 s42, s18, 0x6000
	s_addc_u32 s43, s19, 0
	global_load_dwordx4 v[232:235], v216, s[42:43]
	global_load_dwordx4 v[236:239], v216, s[42:43] offset:256
	s_add_u32 s42, s20, 0x10000
	s_addc_u32 s43, s21, 0
	global_load_dwordx4 v[192:195], v166, s[42:43]
	global_load_dwordx4 v[200:203], v166, s[42:43] offset:256
	s_add_u32 s42, s20, 0x18000
	s_addc_u32 s43, s21, 0
	global_load_dwordx4 v[204:207], v166, s[42:43]
	global_load_dwordx4 v[240:243], v166, s[42:43] offset:256
	s_waitcnt vmcnt(8)
	s_add_u32 s98, s48, 0x0
	s_addc_u32 s99, s49, 0
	v_lshlrev_b32_e32 v170, 16, v132
	v_lshlrev_b32_e32 v172, 16, v133
	v_lshlrev_b32_e32 v210, 16, v134
	v_lshlrev_b32_e32 v218, 16, v135
	v_and_b32_e32 v171, 0xffff0000, v132
	v_and_b32_e32 v173, 0xffff0000, v133
	v_and_b32_e32 v211, 0xffff0000, v134
	v_and_b32_e32 v219, 0xffff0000, v135
	v_pk_mul_f32 v[170:171], v[170:171], s[60:61]
	v_pk_mul_f32 v[172:173], v[172:173], s[60:61]
	v_pk_mul_f32 v[210:211], v[210:211], s[60:61]
	v_pk_mul_f32 v[218:219], v[218:219], s[60:61]
	v_exp_f32_e32 v170, v170
	v_exp_f32_e32 v172, v172
	v_exp_f32_e32 v210, v210
	v_exp_f32_e32 v218, v218
	v_exp_f32_e32 v171, v171
	v_exp_f32_e32 v173, v173
	v_exp_f32_e32 v211, v211
	v_exp_f32_e32 v219, v219
	v_pk_add_f32 v[170:171], v[170:171], s[78:79]
	v_pk_add_f32 v[172:173], v[172:173], s[78:79]
	v_pk_add_f32 v[210:211], v[210:211], s[78:79]
	v_pk_add_f32 v[218:219], v[218:219], s[78:79]
	v_rcp_f32_e32 v170, v170
	v_rcp_f32_e32 v172, v172
	v_rcp_f32_e32 v210, v210
	v_rcp_f32_e32 v218, v218
	v_rcp_f32_e32 v171, v171
	v_rcp_f32_e32 v173, v173
	v_rcp_f32_e32 v211, v211
	v_rcp_f32_e32 v219, v219
	v_lshlrev_b32_e32 v220, 16, v148
	v_lshlrev_b32_e32 v244, 16, v149
	v_lshlrev_b32_e32 v248, 16, v150
	v_lshlrev_b32_e32 v250, 16, v151
	v_and_b32_e32 v221, 0xffff0000, v148
	v_and_b32_e32 v245, 0xffff0000, v149
	v_and_b32_e32 v249, 0xffff0000, v150
	v_and_b32_e32 v251, 0xffff0000, v151
	v_pk_fma_f32 v[128:129], v[128:129], v[170:171], v[220:221]
	v_pk_fma_f32 v[130:131], v[130:131], v[172:173], v[244:245]
	v_pk_fma_f32 v[124:125], v[124:125], v[210:211], v[248:249]
	v_pk_fma_f32 v[126:127], v[126:127], v[218:219], v[250:251]
	v_cvt_pk_bf16_f32 v128, v128, v129
	v_cvt_pk_bf16_f32 v129, v130, v131
	v_cvt_pk_bf16_f32 v130, v124, v125
	v_cvt_pk_bf16_f32 v131, v126, v127
	global_store_dwordx4 v166, v[128:131], s[98:99]
	v_lshlrev_b32_e32 v170, 16, v136
	v_lshlrev_b32_e32 v172, 16, v137
	v_lshlrev_b32_e32 v210, 16, v138
	v_lshlrev_b32_e32 v218, 16, v139
	v_and_b32_e32 v171, 0xffff0000, v136
	v_and_b32_e32 v173, 0xffff0000, v137
	v_and_b32_e32 v211, 0xffff0000, v138
	v_and_b32_e32 v219, 0xffff0000, v139
	v_pk_mul_f32 v[170:171], v[170:171], s[60:61]
	v_pk_mul_f32 v[172:173], v[172:173], s[60:61]
	v_pk_mul_f32 v[210:211], v[210:211], s[60:61]
	v_pk_mul_f32 v[218:219], v[218:219], s[60:61]
	v_exp_f32_e32 v170, v170
	v_exp_f32_e32 v172, v172
	v_exp_f32_e32 v210, v210
	v_exp_f32_e32 v218, v218
	v_exp_f32_e32 v171, v171
	v_exp_f32_e32 v173, v173
	v_exp_f32_e32 v211, v211
	v_exp_f32_e32 v219, v219
	v_pk_add_f32 v[170:171], v[170:171], s[78:79]
	v_pk_add_f32 v[172:173], v[172:173], s[78:79]
	v_pk_add_f32 v[210:211], v[210:211], s[78:79]
	v_pk_add_f32 v[218:219], v[218:219], s[78:79]
	v_rcp_f32_e32 v170, v170
	v_rcp_f32_e32 v172, v172
	v_rcp_f32_e32 v210, v210
	v_rcp_f32_e32 v218, v218
	v_rcp_f32_e32 v171, v171
	v_rcp_f32_e32 v173, v173
	v_rcp_f32_e32 v211, v211
	v_rcp_f32_e32 v219, v219
	v_lshlrev_b32_e32 v220, 16, v152
	v_lshlrev_b32_e32 v244, 16, v153
	v_lshlrev_b32_e32 v248, 16, v154
	v_lshlrev_b32_e32 v250, 16, v155
	v_and_b32_e32 v221, 0xffff0000, v152
	v_and_b32_e32 v245, 0xffff0000, v153
	v_and_b32_e32 v249, 0xffff0000, v154
	v_and_b32_e32 v251, 0xffff0000, v155
	v_pk_fma_f32 v[120:121], v[120:121], v[170:171], v[220:221]
	v_pk_fma_f32 v[122:123], v[122:123], v[172:173], v[244:245]
	v_pk_fma_f32 v[116:117], v[116:117], v[210:211], v[248:249]
	v_pk_fma_f32 v[118:119], v[118:119], v[218:219], v[250:251]
	v_cvt_pk_bf16_f32 v120, v120, v121
	v_cvt_pk_bf16_f32 v121, v122, v123
	v_cvt_pk_bf16_f32 v122, v116, v117
	v_cvt_pk_bf16_f32 v123, v118, v119
	global_store_dwordx4 v166, v[120:123], s[98:99] offset:256
	s_add_u32 s98, s48, 0x8000
	s_addc_u32 s99, s49, 0
	v_lshlrev_b32_e32 v170, 16, v140
	v_lshlrev_b32_e32 v172, 16, v141
	v_lshlrev_b32_e32 v210, 16, v142
	v_lshlrev_b32_e32 v218, 16, v143
	v_and_b32_e32 v171, 0xffff0000, v140
	v_and_b32_e32 v173, 0xffff0000, v141
	v_and_b32_e32 v211, 0xffff0000, v142
	v_and_b32_e32 v219, 0xffff0000, v143
	v_pk_mul_f32 v[170:171], v[170:171], s[60:61]
	v_pk_mul_f32 v[172:173], v[172:173], s[60:61]
	v_pk_mul_f32 v[210:211], v[210:211], s[60:61]
	v_pk_mul_f32 v[218:219], v[218:219], s[60:61]
	v_exp_f32_e32 v170, v170
	v_exp_f32_e32 v172, v172
	v_exp_f32_e32 v210, v210
	v_exp_f32_e32 v218, v218
	v_exp_f32_e32 v171, v171
	v_exp_f32_e32 v173, v173
	v_exp_f32_e32 v211, v211
	v_exp_f32_e32 v219, v219
	v_pk_add_f32 v[170:171], v[170:171], s[78:79]
	v_pk_add_f32 v[172:173], v[172:173], s[78:79]
	v_pk_add_f32 v[210:211], v[210:211], s[78:79]
	v_pk_add_f32 v[218:219], v[218:219], s[78:79]
	v_rcp_f32_e32 v170, v170
	v_rcp_f32_e32 v172, v172
	v_rcp_f32_e32 v210, v210
	v_rcp_f32_e32 v218, v218
	v_rcp_f32_e32 v171, v171
	v_rcp_f32_e32 v173, v173
	v_rcp_f32_e32 v211, v211
	v_rcp_f32_e32 v219, v219
	v_lshlrev_b32_e32 v220, 16, v184
	v_lshlrev_b32_e32 v244, 16, v185
	v_lshlrev_b32_e32 v248, 16, v186
	v_lshlrev_b32_e32 v250, 16, v187
	v_and_b32_e32 v221, 0xffff0000, v184
	v_and_b32_e32 v245, 0xffff0000, v185
	v_and_b32_e32 v249, 0xffff0000, v186
	v_and_b32_e32 v251, 0xffff0000, v187
	v_pk_fma_f32 v[112:113], v[112:113], v[170:171], v[220:221]
	v_pk_fma_f32 v[114:115], v[114:115], v[172:173], v[244:245]
	v_pk_fma_f32 v[108:109], v[108:109], v[210:211], v[248:249]
	v_pk_fma_f32 v[110:111], v[110:111], v[218:219], v[250:251]
	v_cvt_pk_bf16_f32 v112, v112, v113
	v_cvt_pk_bf16_f32 v113, v114, v115
	v_cvt_pk_bf16_f32 v114, v108, v109
	v_cvt_pk_bf16_f32 v115, v110, v111
	global_store_dwordx4 v166, v[112:115], s[98:99]
	v_lshlrev_b32_e32 v170, 16, v144
	v_lshlrev_b32_e32 v172, 16, v145
	v_lshlrev_b32_e32 v210, 16, v146
	v_lshlrev_b32_e32 v218, 16, v147
	v_and_b32_e32 v171, 0xffff0000, v144
	v_and_b32_e32 v173, 0xffff0000, v145
	v_and_b32_e32 v211, 0xffff0000, v146
	v_and_b32_e32 v219, 0xffff0000, v147
	v_pk_mul_f32 v[170:171], v[170:171], s[60:61]
	v_pk_mul_f32 v[172:173], v[172:173], s[60:61]
	v_pk_mul_f32 v[210:211], v[210:211], s[60:61]
	v_pk_mul_f32 v[218:219], v[218:219], s[60:61]
	v_exp_f32_e32 v170, v170
	v_exp_f32_e32 v172, v172
	v_exp_f32_e32 v210, v210
	v_exp_f32_e32 v218, v218
	v_exp_f32_e32 v171, v171
	v_exp_f32_e32 v173, v173
	v_exp_f32_e32 v211, v211
	v_exp_f32_e32 v219, v219
	v_pk_add_f32 v[170:171], v[170:171], s[78:79]
	v_pk_add_f32 v[172:173], v[172:173], s[78:79]
	v_pk_add_f32 v[210:211], v[210:211], s[78:79]
	v_pk_add_f32 v[218:219], v[218:219], s[78:79]
	v_rcp_f32_e32 v170, v170
	v_rcp_f32_e32 v172, v172
	v_rcp_f32_e32 v210, v210
	v_rcp_f32_e32 v218, v218
	v_rcp_f32_e32 v171, v171
	v_rcp_f32_e32 v173, v173
	v_rcp_f32_e32 v211, v211
	v_rcp_f32_e32 v219, v219
	v_lshlrev_b32_e32 v220, 16, v188
	v_lshlrev_b32_e32 v244, 16, v189
	v_lshlrev_b32_e32 v248, 16, v190
	v_lshlrev_b32_e32 v250, 16, v191
	v_and_b32_e32 v221, 0xffff0000, v188
	v_and_b32_e32 v245, 0xffff0000, v189
	v_and_b32_e32 v249, 0xffff0000, v190
	v_and_b32_e32 v251, 0xffff0000, v191
	v_pk_fma_f32 v[104:105], v[104:105], v[170:171], v[220:221]
	v_pk_fma_f32 v[106:107], v[106:107], v[172:173], v[244:245]
	v_pk_fma_f32 v[100:101], v[100:101], v[210:211], v[248:249]
	v_pk_fma_f32 v[102:103], v[102:103], v[218:219], v[250:251]
	v_cvt_pk_bf16_f32 v104, v104, v105
	v_cvt_pk_bf16_f32 v105, v106, v107
	v_cvt_pk_bf16_f32 v106, v100, v101
	v_cvt_pk_bf16_f32 v107, v102, v103
	global_store_dwordx4 v166, v[104:107], s[98:99] offset:256
	s_add_u32 s42, s18, 0x10000
	s_addc_u32 s43, s19, 0
	global_load_dwordx4 v[132:135], v216, s[42:43]
	global_load_dwordx4 v[136:139], v216, s[42:43] offset:256
	s_add_u32 s42, s18, 0x12000
	s_addc_u32 s43, s19, 0
	global_load_dwordx4 v[140:143], v216, s[42:43]
	global_load_dwordx4 v[144:147], v216, s[42:43] offset:256
	s_add_u32 s42, s20, 0x40000
	s_addc_u32 s43, s21, 0
	global_load_dwordx4 v[148:151], v166, s[42:43]
	global_load_dwordx4 v[152:155], v166, s[42:43] offset:256
	s_add_u32 s42, s20, 0x48000
	s_addc_u32 s43, s21, 0
	global_load_dwordx4 v[184:187], v166, s[42:43]
	global_load_dwordx4 v[188:191], v166, s[42:43] offset:256
	s_waitcnt vmcnt(12)
	s_add_u32 s98, s48, 0x10000
	s_addc_u32 s99, s49, 0
	v_lshlrev_b32_e32 v170, 16, v224
	v_lshlrev_b32_e32 v172, 16, v225
	v_lshlrev_b32_e32 v210, 16, v226
	v_lshlrev_b32_e32 v218, 16, v227
	v_and_b32_e32 v171, 0xffff0000, v224
	v_and_b32_e32 v173, 0xffff0000, v225
	v_and_b32_e32 v211, 0xffff0000, v226
	v_and_b32_e32 v219, 0xffff0000, v227
	v_pk_mul_f32 v[170:171], v[170:171], s[60:61]
	v_pk_mul_f32 v[172:173], v[172:173], s[60:61]
	v_pk_mul_f32 v[210:211], v[210:211], s[60:61]
	v_pk_mul_f32 v[218:219], v[218:219], s[60:61]
	v_exp_f32_e32 v170, v170
	v_exp_f32_e32 v172, v172
	v_exp_f32_e32 v210, v210
	v_exp_f32_e32 v218, v218
	v_exp_f32_e32 v171, v171
	v_exp_f32_e32 v173, v173
	v_exp_f32_e32 v211, v211
	v_exp_f32_e32 v219, v219
	v_pk_add_f32 v[170:171], v[170:171], s[78:79]
	v_pk_add_f32 v[172:173], v[172:173], s[78:79]
	v_pk_add_f32 v[210:211], v[210:211], s[78:79]
	v_pk_add_f32 v[218:219], v[218:219], s[78:79]
	v_rcp_f32_e32 v170, v170
	v_rcp_f32_e32 v172, v172
	v_rcp_f32_e32 v210, v210
	v_rcp_f32_e32 v218, v218
	v_rcp_f32_e32 v171, v171
	v_rcp_f32_e32 v173, v173
	v_rcp_f32_e32 v211, v211
	v_rcp_f32_e32 v219, v219
	v_lshlrev_b32_e32 v220, 16, v192
	v_lshlrev_b32_e32 v244, 16, v193
	v_lshlrev_b32_e32 v248, 16, v194
	v_lshlrev_b32_e32 v250, 16, v195
	v_and_b32_e32 v221, 0xffff0000, v192
	v_and_b32_e32 v245, 0xffff0000, v193
	v_and_b32_e32 v249, 0xffff0000, v194
	v_and_b32_e32 v251, 0xffff0000, v195
	v_pk_fma_f32 v[96:97], v[96:97], v[170:171], v[220:221]
	v_pk_fma_f32 v[98:99], v[98:99], v[172:173], v[244:245]
	v_pk_fma_f32 v[92:93], v[92:93], v[210:211], v[248:249]
	v_pk_fma_f32 v[94:95], v[94:95], v[218:219], v[250:251]
	v_cvt_pk_bf16_f32 v96, v96, v97
	v_cvt_pk_bf16_f32 v97, v98, v99
	v_cvt_pk_bf16_f32 v98, v92, v93
	v_cvt_pk_bf16_f32 v99, v94, v95
	global_store_dwordx4 v166, v[96:99], s[98:99]
	v_lshlrev_b32_e32 v170, 16, v228
	v_lshlrev_b32_e32 v172, 16, v229
	v_lshlrev_b32_e32 v210, 16, v230
	v_lshlrev_b32_e32 v218, 16, v231
	v_and_b32_e32 v171, 0xffff0000, v228
	v_and_b32_e32 v173, 0xffff0000, v229
	v_and_b32_e32 v211, 0xffff0000, v230
	v_and_b32_e32 v219, 0xffff0000, v231
	v_pk_mul_f32 v[170:171], v[170:171], s[60:61]
	v_pk_mul_f32 v[172:173], v[172:173], s[60:61]
	v_pk_mul_f32 v[210:211], v[210:211], s[60:61]
	v_pk_mul_f32 v[218:219], v[218:219], s[60:61]
	v_exp_f32_e32 v170, v170
	v_exp_f32_e32 v172, v172
	v_exp_f32_e32 v210, v210
	v_exp_f32_e32 v218, v218
	v_exp_f32_e32 v171, v171
	v_exp_f32_e32 v173, v173
	v_exp_f32_e32 v211, v211
	v_exp_f32_e32 v219, v219
	v_pk_add_f32 v[170:171], v[170:171], s[78:79]
	v_pk_add_f32 v[172:173], v[172:173], s[78:79]
	v_pk_add_f32 v[210:211], v[210:211], s[78:79]
	v_pk_add_f32 v[218:219], v[218:219], s[78:79]
	v_rcp_f32_e32 v170, v170
	v_rcp_f32_e32 v172, v172
	v_rcp_f32_e32 v210, v210
	v_rcp_f32_e32 v218, v218
	v_rcp_f32_e32 v171, v171
	v_rcp_f32_e32 v173, v173
	v_rcp_f32_e32 v211, v211
	v_rcp_f32_e32 v219, v219
	v_lshlrev_b32_e32 v220, 16, v200
	v_lshlrev_b32_e32 v244, 16, v201
	v_lshlrev_b32_e32 v248, 16, v202
	v_lshlrev_b32_e32 v250, 16, v203
	v_and_b32_e32 v221, 0xffff0000, v200
	v_and_b32_e32 v245, 0xffff0000, v201
	v_and_b32_e32 v249, 0xffff0000, v202
	v_and_b32_e32 v251, 0xffff0000, v203
	v_pk_fma_f32 v[88:89], v[88:89], v[170:171], v[220:221]
	v_pk_fma_f32 v[90:91], v[90:91], v[172:173], v[244:245]
	v_pk_fma_f32 v[84:85], v[84:85], v[210:211], v[248:249]
	v_pk_fma_f32 v[86:87], v[86:87], v[218:219], v[250:251]
	v_cvt_pk_bf16_f32 v88, v88, v89
	v_cvt_pk_bf16_f32 v89, v90, v91
	v_cvt_pk_bf16_f32 v90, v84, v85
	v_cvt_pk_bf16_f32 v91, v86, v87
	global_store_dwordx4 v166, v[88:91], s[98:99] offset:256
	s_add_u32 s98, s48, 0x18000
	s_addc_u32 s99, s49, 0
	v_lshlrev_b32_e32 v170, 16, v232
	v_lshlrev_b32_e32 v172, 16, v233
	v_lshlrev_b32_e32 v210, 16, v234
	v_lshlrev_b32_e32 v218, 16, v235
	v_and_b32_e32 v171, 0xffff0000, v232
	v_and_b32_e32 v173, 0xffff0000, v233
	v_and_b32_e32 v211, 0xffff0000, v234
	v_and_b32_e32 v219, 0xffff0000, v235
	v_pk_mul_f32 v[170:171], v[170:171], s[60:61]
	v_pk_mul_f32 v[172:173], v[172:173], s[60:61]
	v_pk_mul_f32 v[210:211], v[210:211], s[60:61]
	v_pk_mul_f32 v[218:219], v[218:219], s[60:61]
	v_exp_f32_e32 v170, v170
	v_exp_f32_e32 v172, v172
	v_exp_f32_e32 v210, v210
	v_exp_f32_e32 v218, v218
	v_exp_f32_e32 v171, v171
	v_exp_f32_e32 v173, v173
	v_exp_f32_e32 v211, v211
	v_exp_f32_e32 v219, v219
	v_pk_add_f32 v[170:171], v[170:171], s[78:79]
	v_pk_add_f32 v[172:173], v[172:173], s[78:79]
	v_pk_add_f32 v[210:211], v[210:211], s[78:79]
	v_pk_add_f32 v[218:219], v[218:219], s[78:79]
	v_rcp_f32_e32 v170, v170
	v_rcp_f32_e32 v172, v172
	v_rcp_f32_e32 v210, v210
	v_rcp_f32_e32 v218, v218
	v_rcp_f32_e32 v171, v171
	v_rcp_f32_e32 v173, v173
	v_rcp_f32_e32 v211, v211
	v_rcp_f32_e32 v219, v219
	v_lshlrev_b32_e32 v220, 16, v204
	v_lshlrev_b32_e32 v244, 16, v205
	v_lshlrev_b32_e32 v248, 16, v206
	v_lshlrev_b32_e32 v250, 16, v207
	v_and_b32_e32 v221, 0xffff0000, v204
	v_and_b32_e32 v245, 0xffff0000, v205
	v_and_b32_e32 v249, 0xffff0000, v206
	v_and_b32_e32 v251, 0xffff0000, v207
	v_pk_fma_f32 v[76:77], v[76:77], v[170:171], v[220:221]
	v_pk_fma_f32 v[78:79], v[78:79], v[172:173], v[244:245]
	v_pk_fma_f32 v[72:73], v[72:73], v[210:211], v[248:249]
	v_pk_fma_f32 v[74:75], v[74:75], v[218:219], v[250:251]
	v_cvt_pk_bf16_f32 v76, v76, v77
	v_cvt_pk_bf16_f32 v77, v78, v79
	v_cvt_pk_bf16_f32 v78, v72, v73
	v_cvt_pk_bf16_f32 v79, v74, v75
	global_store_dwordx4 v166, v[76:79], s[98:99]
	v_lshlrev_b32_e32 v170, 16, v236
	v_lshlrev_b32_e32 v172, 16, v237
	v_lshlrev_b32_e32 v210, 16, v238
	v_lshlrev_b32_e32 v218, 16, v239
	v_and_b32_e32 v171, 0xffff0000, v236
	v_and_b32_e32 v173, 0xffff0000, v237
	v_and_b32_e32 v211, 0xffff0000, v238
	v_and_b32_e32 v219, 0xffff0000, v239
	v_pk_mul_f32 v[170:171], v[170:171], s[60:61]
	v_pk_mul_f32 v[172:173], v[172:173], s[60:61]
	v_pk_mul_f32 v[210:211], v[210:211], s[60:61]
	v_pk_mul_f32 v[218:219], v[218:219], s[60:61]
	v_exp_f32_e32 v170, v170
	v_exp_f32_e32 v172, v172
	v_exp_f32_e32 v210, v210
	v_exp_f32_e32 v218, v218
	v_exp_f32_e32 v171, v171
	v_exp_f32_e32 v173, v173
	v_exp_f32_e32 v211, v211
	v_exp_f32_e32 v219, v219
	v_pk_add_f32 v[170:171], v[170:171], s[78:79]
	v_pk_add_f32 v[172:173], v[172:173], s[78:79]
	v_pk_add_f32 v[210:211], v[210:211], s[78:79]
	v_pk_add_f32 v[218:219], v[218:219], s[78:79]
	v_rcp_f32_e32 v170, v170
	v_rcp_f32_e32 v172, v172
	v_rcp_f32_e32 v210, v210
	v_rcp_f32_e32 v218, v218
	v_rcp_f32_e32 v171, v171
	v_rcp_f32_e32 v173, v173
	v_rcp_f32_e32 v211, v211
	v_rcp_f32_e32 v219, v219
	v_lshlrev_b32_e32 v220, 16, v240
	v_lshlrev_b32_e32 v244, 16, v241
	v_lshlrev_b32_e32 v248, 16, v242
	v_lshlrev_b32_e32 v250, 16, v243
	v_and_b32_e32 v221, 0xffff0000, v240
	v_and_b32_e32 v245, 0xffff0000, v241
	v_and_b32_e32 v249, 0xffff0000, v242
	v_and_b32_e32 v251, 0xffff0000, v243
	v_pk_fma_f32 v[68:69], v[68:69], v[170:171], v[220:221]
	v_pk_fma_f32 v[70:71], v[70:71], v[172:173], v[244:245]
	v_pk_fma_f32 v[64:65], v[64:65], v[210:211], v[248:249]
	v_pk_fma_f32 v[66:67], v[66:67], v[218:219], v[250:251]
	v_cvt_pk_bf16_f32 v68, v68, v69
	v_cvt_pk_bf16_f32 v69, v70, v71
	v_cvt_pk_bf16_f32 v70, v64, v65
	v_cvt_pk_bf16_f32 v71, v66, v67
	global_store_dwordx4 v166, v[68:71], s[98:99] offset:256
	s_add_u32 s42, s18, 0x14000
	s_addc_u32 s43, s19, 0
	global_load_dwordx4 v[224:227], v216, s[42:43]
	global_load_dwordx4 v[228:231], v216, s[42:43] offset:256
	s_add_u32 s42, s18, 0x16000
	s_addc_u32 s43, s19, 0
	global_load_dwordx4 v[232:235], v216, s[42:43]
	global_load_dwordx4 v[236:239], v216, s[42:43] offset:256
	s_add_u32 s42, s20, 0x50000
	s_addc_u32 s43, s21, 0
	global_load_dwordx4 v[192:195], v166, s[42:43]
	global_load_dwordx4 v[200:203], v166, s[42:43] offset:256
	s_add_u32 s42, s20, 0x58000
	s_addc_u32 s43, s21, 0
	global_load_dwordx4 v[204:207], v166, s[42:43]
	global_load_dwordx4 v[240:243], v166, s[42:43] offset:256
	s_waitcnt vmcnt(12)
	s_add_u32 s98, s48, 0x40000
	s_addc_u32 s99, s49, 0
	v_lshlrev_b32_e32 v170, 16, v132
	v_lshlrev_b32_e32 v172, 16, v133
	v_lshlrev_b32_e32 v210, 16, v134
	v_lshlrev_b32_e32 v218, 16, v135
	v_and_b32_e32 v171, 0xffff0000, v132
	v_and_b32_e32 v173, 0xffff0000, v133
	v_and_b32_e32 v211, 0xffff0000, v134
	v_and_b32_e32 v219, 0xffff0000, v135
	v_pk_mul_f32 v[170:171], v[170:171], s[60:61]
	v_pk_mul_f32 v[172:173], v[172:173], s[60:61]
	v_pk_mul_f32 v[210:211], v[210:211], s[60:61]
	v_pk_mul_f32 v[218:219], v[218:219], s[60:61]
	v_exp_f32_e32 v170, v170
	v_exp_f32_e32 v172, v172
	v_exp_f32_e32 v210, v210
	v_exp_f32_e32 v218, v218
	v_exp_f32_e32 v171, v171
	v_exp_f32_e32 v173, v173
	v_exp_f32_e32 v211, v211
	v_exp_f32_e32 v219, v219
	v_pk_add_f32 v[170:171], v[170:171], s[78:79]
	v_pk_add_f32 v[172:173], v[172:173], s[78:79]
	v_pk_add_f32 v[210:211], v[210:211], s[78:79]
	v_pk_add_f32 v[218:219], v[218:219], s[78:79]
	v_rcp_f32_e32 v170, v170
	v_rcp_f32_e32 v172, v172
	v_rcp_f32_e32 v210, v210
	v_rcp_f32_e32 v218, v218
	v_rcp_f32_e32 v171, v171
	v_rcp_f32_e32 v173, v173
	v_rcp_f32_e32 v211, v211
	v_rcp_f32_e32 v219, v219
	v_lshlrev_b32_e32 v220, 16, v148
	v_lshlrev_b32_e32 v244, 16, v149
	v_lshlrev_b32_e32 v248, 16, v150
	v_lshlrev_b32_e32 v250, 16, v151
	v_and_b32_e32 v221, 0xffff0000, v148
	v_and_b32_e32 v245, 0xffff0000, v149
	v_and_b32_e32 v249, 0xffff0000, v150
	v_and_b32_e32 v251, 0xffff0000, v151
	v_pk_fma_f32 v[60:61], v[60:61], v[170:171], v[220:221]
	v_pk_fma_f32 v[62:63], v[62:63], v[172:173], v[244:245]
	v_pk_fma_f32 v[56:57], v[56:57], v[210:211], v[248:249]
	v_pk_fma_f32 v[58:59], v[58:59], v[218:219], v[250:251]
	v_cvt_pk_bf16_f32 v60, v60, v61
	v_cvt_pk_bf16_f32 v61, v62, v63
	v_cvt_pk_bf16_f32 v62, v56, v57
	v_cvt_pk_bf16_f32 v63, v58, v59
	global_store_dwordx4 v166, v[60:63], s[98:99]
	v_lshlrev_b32_e32 v170, 16, v136
	v_lshlrev_b32_e32 v172, 16, v137
	v_lshlrev_b32_e32 v210, 16, v138
	v_lshlrev_b32_e32 v218, 16, v139
	v_and_b32_e32 v171, 0xffff0000, v136
	v_and_b32_e32 v173, 0xffff0000, v137
	v_and_b32_e32 v211, 0xffff0000, v138
	v_and_b32_e32 v219, 0xffff0000, v139
	v_pk_mul_f32 v[170:171], v[170:171], s[60:61]
	v_pk_mul_f32 v[172:173], v[172:173], s[60:61]
	v_pk_mul_f32 v[210:211], v[210:211], s[60:61]
	v_pk_mul_f32 v[218:219], v[218:219], s[60:61]
	v_exp_f32_e32 v170, v170
	v_exp_f32_e32 v172, v172
	v_exp_f32_e32 v210, v210
	v_exp_f32_e32 v218, v218
	v_exp_f32_e32 v171, v171
	v_exp_f32_e32 v173, v173
	v_exp_f32_e32 v211, v211
	v_exp_f32_e32 v219, v219
	v_pk_add_f32 v[170:171], v[170:171], s[78:79]
	v_pk_add_f32 v[172:173], v[172:173], s[78:79]
	v_pk_add_f32 v[210:211], v[210:211], s[78:79]
	v_pk_add_f32 v[218:219], v[218:219], s[78:79]
	v_rcp_f32_e32 v170, v170
	v_rcp_f32_e32 v172, v172
	v_rcp_f32_e32 v210, v210
	v_rcp_f32_e32 v218, v218
	v_rcp_f32_e32 v171, v171
	v_rcp_f32_e32 v173, v173
	v_rcp_f32_e32 v211, v211
	v_rcp_f32_e32 v219, v219
	v_lshlrev_b32_e32 v220, 16, v152
	v_lshlrev_b32_e32 v244, 16, v153
	v_lshlrev_b32_e32 v248, 16, v154
	v_lshlrev_b32_e32 v250, 16, v155
	v_and_b32_e32 v221, 0xffff0000, v152
	v_and_b32_e32 v245, 0xffff0000, v153
	v_and_b32_e32 v249, 0xffff0000, v154
	v_and_b32_e32 v251, 0xffff0000, v155
	v_pk_fma_f32 v[52:53], v[52:53], v[170:171], v[220:221]
	v_pk_fma_f32 v[54:55], v[54:55], v[172:173], v[244:245]
	v_pk_fma_f32 v[48:49], v[48:49], v[210:211], v[248:249]
	v_pk_fma_f32 v[50:51], v[50:51], v[218:219], v[250:251]
	v_cvt_pk_bf16_f32 v52, v52, v53
	v_cvt_pk_bf16_f32 v53, v54, v55
	v_cvt_pk_bf16_f32 v54, v48, v49
	v_cvt_pk_bf16_f32 v55, v50, v51
	global_store_dwordx4 v166, v[52:55], s[98:99] offset:256
	s_add_u32 s98, s48, 0x48000
	s_addc_u32 s99, s49, 0
	v_lshlrev_b32_e32 v170, 16, v140
	v_lshlrev_b32_e32 v172, 16, v141
	v_lshlrev_b32_e32 v210, 16, v142
	v_lshlrev_b32_e32 v218, 16, v143
	v_and_b32_e32 v171, 0xffff0000, v140
	v_and_b32_e32 v173, 0xffff0000, v141
	v_and_b32_e32 v211, 0xffff0000, v142
	v_and_b32_e32 v219, 0xffff0000, v143
	v_pk_mul_f32 v[170:171], v[170:171], s[60:61]
	v_pk_mul_f32 v[172:173], v[172:173], s[60:61]
	v_pk_mul_f32 v[210:211], v[210:211], s[60:61]
	v_pk_mul_f32 v[218:219], v[218:219], s[60:61]
	v_exp_f32_e32 v170, v170
	v_exp_f32_e32 v172, v172
	v_exp_f32_e32 v210, v210
	v_exp_f32_e32 v218, v218
	v_exp_f32_e32 v171, v171
	v_exp_f32_e32 v173, v173
	v_exp_f32_e32 v211, v211
	v_exp_f32_e32 v219, v219
	v_pk_add_f32 v[170:171], v[170:171], s[78:79]
	v_pk_add_f32 v[172:173], v[172:173], s[78:79]
	v_pk_add_f32 v[210:211], v[210:211], s[78:79]
	v_pk_add_f32 v[218:219], v[218:219], s[78:79]
	v_rcp_f32_e32 v170, v170
	v_rcp_f32_e32 v172, v172
	v_rcp_f32_e32 v210, v210
	v_rcp_f32_e32 v218, v218
	v_rcp_f32_e32 v171, v171
	v_rcp_f32_e32 v173, v173
	v_rcp_f32_e32 v211, v211
	v_rcp_f32_e32 v219, v219
	v_lshlrev_b32_e32 v220, 16, v184
	v_lshlrev_b32_e32 v244, 16, v185
	v_lshlrev_b32_e32 v248, 16, v186
	v_lshlrev_b32_e32 v250, 16, v187
	v_and_b32_e32 v221, 0xffff0000, v184
	v_and_b32_e32 v245, 0xffff0000, v185
	v_and_b32_e32 v249, 0xffff0000, v186
	v_and_b32_e32 v251, 0xffff0000, v187
	v_pk_fma_f32 v[44:45], v[44:45], v[170:171], v[220:221]
	v_pk_fma_f32 v[46:47], v[46:47], v[172:173], v[244:245]
	v_pk_fma_f32 v[40:41], v[40:41], v[210:211], v[248:249]
	v_pk_fma_f32 v[42:43], v[42:43], v[218:219], v[250:251]
	v_cvt_pk_bf16_f32 v44, v44, v45
	v_cvt_pk_bf16_f32 v45, v46, v47
	v_cvt_pk_bf16_f32 v46, v40, v41
	v_cvt_pk_bf16_f32 v47, v42, v43
	global_store_dwordx4 v166, v[44:47], s[98:99]
	v_lshlrev_b32_e32 v170, 16, v144
	v_lshlrev_b32_e32 v172, 16, v145
	v_lshlrev_b32_e32 v210, 16, v146
	v_lshlrev_b32_e32 v218, 16, v147
	v_and_b32_e32 v171, 0xffff0000, v144
	v_and_b32_e32 v173, 0xffff0000, v145
	v_and_b32_e32 v211, 0xffff0000, v146
	v_and_b32_e32 v219, 0xffff0000, v147
	v_pk_mul_f32 v[170:171], v[170:171], s[60:61]
	v_pk_mul_f32 v[172:173], v[172:173], s[60:61]
	v_pk_mul_f32 v[210:211], v[210:211], s[60:61]
	v_pk_mul_f32 v[218:219], v[218:219], s[60:61]
	v_exp_f32_e32 v170, v170
	v_exp_f32_e32 v172, v172
	v_exp_f32_e32 v210, v210
	v_exp_f32_e32 v218, v218
	v_exp_f32_e32 v171, v171
	v_exp_f32_e32 v173, v173
	v_exp_f32_e32 v211, v211
	v_exp_f32_e32 v219, v219
	v_pk_add_f32 v[170:171], v[170:171], s[78:79]
	v_pk_add_f32 v[172:173], v[172:173], s[78:79]
	v_pk_add_f32 v[210:211], v[210:211], s[78:79]
	v_pk_add_f32 v[218:219], v[218:219], s[78:79]
	v_rcp_f32_e32 v170, v170
	v_rcp_f32_e32 v172, v172
	v_rcp_f32_e32 v210, v210
	v_rcp_f32_e32 v218, v218
	v_rcp_f32_e32 v171, v171
	v_rcp_f32_e32 v173, v173
	v_rcp_f32_e32 v211, v211
	v_rcp_f32_e32 v219, v219
	v_lshlrev_b32_e32 v220, 16, v188
	v_lshlrev_b32_e32 v244, 16, v189
	v_lshlrev_b32_e32 v248, 16, v190
	v_lshlrev_b32_e32 v250, 16, v191
	v_and_b32_e32 v221, 0xffff0000, v188
	v_and_b32_e32 v245, 0xffff0000, v189
	v_and_b32_e32 v249, 0xffff0000, v190
	v_and_b32_e32 v251, 0xffff0000, v191
	v_pk_fma_f32 v[36:37], v[36:37], v[170:171], v[220:221]
	v_pk_fma_f32 v[38:39], v[38:39], v[172:173], v[244:245]
	v_pk_fma_f32 v[32:33], v[32:33], v[210:211], v[248:249]
	v_pk_fma_f32 v[34:35], v[34:35], v[218:219], v[250:251]
	v_cvt_pk_bf16_f32 v36, v36, v37
	v_cvt_pk_bf16_f32 v37, v38, v39
	v_cvt_pk_bf16_f32 v38, v32, v33
	v_cvt_pk_bf16_f32 v39, v34, v35
	global_store_dwordx4 v166, v[36:39], s[98:99] offset:256
	s_waitcnt vmcnt(4)
	s_add_u32 s98, s48, 0x50000
	s_addc_u32 s99, s49, 0
	v_lshlrev_b32_e32 v170, 16, v224
	v_lshlrev_b32_e32 v172, 16, v225
	v_lshlrev_b32_e32 v210, 16, v226
	v_lshlrev_b32_e32 v218, 16, v227
	v_and_b32_e32 v171, 0xffff0000, v224
	v_and_b32_e32 v173, 0xffff0000, v225
	v_and_b32_e32 v211, 0xffff0000, v226
	v_and_b32_e32 v219, 0xffff0000, v227
	v_pk_mul_f32 v[170:171], v[170:171], s[60:61]
	v_pk_mul_f32 v[172:173], v[172:173], s[60:61]
	v_pk_mul_f32 v[210:211], v[210:211], s[60:61]
	v_pk_mul_f32 v[218:219], v[218:219], s[60:61]
	v_exp_f32_e32 v170, v170
	v_exp_f32_e32 v172, v172
	v_exp_f32_e32 v210, v210
	v_exp_f32_e32 v218, v218
	v_exp_f32_e32 v171, v171
	v_exp_f32_e32 v173, v173
	v_exp_f32_e32 v211, v211
	v_exp_f32_e32 v219, v219
	v_pk_add_f32 v[170:171], v[170:171], s[78:79]
	v_pk_add_f32 v[172:173], v[172:173], s[78:79]
	v_pk_add_f32 v[210:211], v[210:211], s[78:79]
	v_pk_add_f32 v[218:219], v[218:219], s[78:79]
	v_rcp_f32_e32 v170, v170
	v_rcp_f32_e32 v172, v172
	v_rcp_f32_e32 v210, v210
	v_rcp_f32_e32 v218, v218
	v_rcp_f32_e32 v171, v171
	v_rcp_f32_e32 v173, v173
	v_rcp_f32_e32 v211, v211
	v_rcp_f32_e32 v219, v219
	v_lshlrev_b32_e32 v220, 16, v192
	v_lshlrev_b32_e32 v244, 16, v193
	v_lshlrev_b32_e32 v248, 16, v194
	v_lshlrev_b32_e32 v250, 16, v195
	v_and_b32_e32 v221, 0xffff0000, v192
	v_and_b32_e32 v245, 0xffff0000, v193
	v_and_b32_e32 v249, 0xffff0000, v194
	v_and_b32_e32 v251, 0xffff0000, v195
	v_pk_fma_f32 v[28:29], v[28:29], v[170:171], v[220:221]
	v_pk_fma_f32 v[30:31], v[30:31], v[172:173], v[244:245]
	v_pk_fma_f32 v[24:25], v[24:25], v[210:211], v[248:249]
	v_pk_fma_f32 v[26:27], v[26:27], v[218:219], v[250:251]
	v_cvt_pk_bf16_f32 v28, v28, v29
	v_cvt_pk_bf16_f32 v29, v30, v31
	v_cvt_pk_bf16_f32 v30, v24, v25
	v_cvt_pk_bf16_f32 v31, v26, v27
	global_store_dwordx4 v166, v[28:31], s[98:99]
	v_lshlrev_b32_e32 v170, 16, v228
	v_lshlrev_b32_e32 v172, 16, v229
	v_lshlrev_b32_e32 v210, 16, v230
	v_lshlrev_b32_e32 v218, 16, v231
	v_and_b32_e32 v171, 0xffff0000, v228
	v_and_b32_e32 v173, 0xffff0000, v229
	v_and_b32_e32 v211, 0xffff0000, v230
	v_and_b32_e32 v219, 0xffff0000, v231
	v_pk_mul_f32 v[170:171], v[170:171], s[60:61]
	v_pk_mul_f32 v[172:173], v[172:173], s[60:61]
	v_pk_mul_f32 v[210:211], v[210:211], s[60:61]
	v_pk_mul_f32 v[218:219], v[218:219], s[60:61]
	v_exp_f32_e32 v170, v170
	v_exp_f32_e32 v172, v172
	v_exp_f32_e32 v210, v210
	v_exp_f32_e32 v218, v218
	v_exp_f32_e32 v171, v171
	v_exp_f32_e32 v173, v173
	v_exp_f32_e32 v211, v211
	v_exp_f32_e32 v219, v219
	v_pk_add_f32 v[170:171], v[170:171], s[78:79]
	v_pk_add_f32 v[172:173], v[172:173], s[78:79]
	v_pk_add_f32 v[210:211], v[210:211], s[78:79]
	v_pk_add_f32 v[218:219], v[218:219], s[78:79]
	v_rcp_f32_e32 v170, v170
	v_rcp_f32_e32 v172, v172
	v_rcp_f32_e32 v210, v210
	v_rcp_f32_e32 v218, v218
	v_rcp_f32_e32 v171, v171
	v_rcp_f32_e32 v173, v173
	v_rcp_f32_e32 v211, v211
	v_rcp_f32_e32 v219, v219
	v_lshlrev_b32_e32 v220, 16, v200
	v_lshlrev_b32_e32 v244, 16, v201
	v_lshlrev_b32_e32 v248, 16, v202
	v_lshlrev_b32_e32 v250, 16, v203
	v_and_b32_e32 v221, 0xffff0000, v200
	v_and_b32_e32 v245, 0xffff0000, v201
	v_and_b32_e32 v249, 0xffff0000, v202
	v_and_b32_e32 v251, 0xffff0000, v203
	v_pk_fma_f32 v[20:21], v[20:21], v[170:171], v[220:221]
	v_pk_fma_f32 v[22:23], v[22:23], v[172:173], v[244:245]
	v_pk_fma_f32 v[16:17], v[16:17], v[210:211], v[248:249]
	v_pk_fma_f32 v[18:19], v[18:19], v[218:219], v[250:251]
	v_cvt_pk_bf16_f32 v20, v20, v21
	v_cvt_pk_bf16_f32 v21, v22, v23
	v_cvt_pk_bf16_f32 v22, v16, v17
	v_cvt_pk_bf16_f32 v23, v18, v19
	global_store_dwordx4 v166, v[20:23], s[98:99] offset:256
	s_add_u32 s98, s48, 0x58000
	s_addc_u32 s99, s49, 0
	v_lshlrev_b32_e32 v170, 16, v232
	v_lshlrev_b32_e32 v172, 16, v233
	v_lshlrev_b32_e32 v210, 16, v234
	v_lshlrev_b32_e32 v218, 16, v235
	v_and_b32_e32 v171, 0xffff0000, v232
	v_and_b32_e32 v173, 0xffff0000, v233
	v_and_b32_e32 v211, 0xffff0000, v234
	v_and_b32_e32 v219, 0xffff0000, v235
	v_pk_mul_f32 v[170:171], v[170:171], s[60:61]
	v_pk_mul_f32 v[172:173], v[172:173], s[60:61]
	v_pk_mul_f32 v[210:211], v[210:211], s[60:61]
	v_pk_mul_f32 v[218:219], v[218:219], s[60:61]
	v_exp_f32_e32 v170, v170
	v_exp_f32_e32 v172, v172
	v_exp_f32_e32 v210, v210
	v_exp_f32_e32 v218, v218
	v_exp_f32_e32 v171, v171
	v_exp_f32_e32 v173, v173
	v_exp_f32_e32 v211, v211
	v_exp_f32_e32 v219, v219
	v_pk_add_f32 v[170:171], v[170:171], s[78:79]
	v_pk_add_f32 v[172:173], v[172:173], s[78:79]
	v_pk_add_f32 v[210:211], v[210:211], s[78:79]
	v_pk_add_f32 v[218:219], v[218:219], s[78:79]
	v_rcp_f32_e32 v170, v170
	v_rcp_f32_e32 v172, v172
	v_rcp_f32_e32 v210, v210
	v_rcp_f32_e32 v218, v218
	v_rcp_f32_e32 v171, v171
	v_rcp_f32_e32 v173, v173
	v_rcp_f32_e32 v211, v211
	v_rcp_f32_e32 v219, v219
	v_lshlrev_b32_e32 v220, 16, v204
	v_lshlrev_b32_e32 v244, 16, v205
	v_lshlrev_b32_e32 v248, 16, v206
	v_lshlrev_b32_e32 v250, 16, v207
	v_and_b32_e32 v221, 0xffff0000, v204
	v_and_b32_e32 v245, 0xffff0000, v205
	v_and_b32_e32 v249, 0xffff0000, v206
	v_and_b32_e32 v251, 0xffff0000, v207
	v_pk_fma_f32 v[12:13], v[12:13], v[170:171], v[220:221]
	v_pk_fma_f32 v[14:15], v[14:15], v[172:173], v[244:245]
	v_pk_fma_f32 v[8:9], v[8:9], v[210:211], v[248:249]
	v_pk_fma_f32 v[10:11], v[10:11], v[218:219], v[250:251]
	v_cvt_pk_bf16_f32 v12, v12, v13
	v_cvt_pk_bf16_f32 v13, v14, v15
	v_cvt_pk_bf16_f32 v14, v8, v9
	v_cvt_pk_bf16_f32 v15, v10, v11
	global_store_dwordx4 v166, v[12:15], s[98:99]
	v_lshlrev_b32_e32 v170, 16, v236
	v_lshlrev_b32_e32 v172, 16, v237
	v_lshlrev_b32_e32 v210, 16, v238
	v_lshlrev_b32_e32 v218, 16, v239
	v_and_b32_e32 v171, 0xffff0000, v236
	v_and_b32_e32 v173, 0xffff0000, v237
	v_and_b32_e32 v211, 0xffff0000, v238
	v_and_b32_e32 v219, 0xffff0000, v239
	v_pk_mul_f32 v[170:171], v[170:171], s[60:61]
	v_pk_mul_f32 v[172:173], v[172:173], s[60:61]
	v_pk_mul_f32 v[210:211], v[210:211], s[60:61]
	v_pk_mul_f32 v[218:219], v[218:219], s[60:61]
	v_exp_f32_e32 v170, v170
	v_exp_f32_e32 v172, v172
	v_exp_f32_e32 v210, v210
	v_exp_f32_e32 v218, v218
	v_exp_f32_e32 v171, v171
	v_exp_f32_e32 v173, v173
	v_exp_f32_e32 v211, v211
	v_exp_f32_e32 v219, v219
	v_pk_add_f32 v[170:171], v[170:171], s[78:79]
	v_pk_add_f32 v[172:173], v[172:173], s[78:79]
	v_pk_add_f32 v[210:211], v[210:211], s[78:79]
	v_pk_add_f32 v[218:219], v[218:219], s[78:79]
	v_rcp_f32_e32 v170, v170
	v_rcp_f32_e32 v172, v172
	v_rcp_f32_e32 v210, v210
	v_rcp_f32_e32 v218, v218
	v_rcp_f32_e32 v171, v171
	v_rcp_f32_e32 v173, v173
	v_rcp_f32_e32 v211, v211
	v_rcp_f32_e32 v219, v219
	v_lshlrev_b32_e32 v220, 16, v240
	v_lshlrev_b32_e32 v244, 16, v241
	v_lshlrev_b32_e32 v248, 16, v242
	v_lshlrev_b32_e32 v250, 16, v243
	v_and_b32_e32 v221, 0xffff0000, v240
	v_and_b32_e32 v245, 0xffff0000, v241
	v_and_b32_e32 v249, 0xffff0000, v242
	v_and_b32_e32 v251, 0xffff0000, v243
	v_pk_fma_f32 v[4:5], v[4:5], v[170:171], v[220:221]
	v_pk_fma_f32 v[6:7], v[6:7], v[172:173], v[244:245]
	v_pk_fma_f32 v[0:1], v[0:1], v[210:211], v[248:249]
	v_pk_fma_f32 v[2:3], v[2:3], v[218:219], v[250:251]
	v_cvt_pk_bf16_f32 v4, v4, v5
	v_cvt_pk_bf16_f32 v5, v6, v7
	v_cvt_pk_bf16_f32 v6, v0, v1
	v_cvt_pk_bf16_f32 v7, v2, v3
	global_store_dwordx4 v166, v[4:7], s[98:99] offset:256
	s_branch .Lp6e2_done
	s_mul_i32 s18, s43, 49
	s_add_i32 s18, s42, s18
	v_lshl_or_b32 v132, s42, 8, v197
	s_add_i32 s18, s18, 45
	v_lshl_add_u32 v186, s43, 8, v169
	s_ashr_i32 s19, s18, 31
	v_ashrrev_i32_e32 v133, 31, v132
	s_lshl_b64 s[18:19], s[18:19], 17
	v_lshlrev_b64 v[170:171], 1, v[132:133]
	v_lshlrev_b32_e32 v132, 9, v186
	v_lshl_add_u64 v[188:189], v[178:179], 0, s[18:19]
	v_ashrrev_i32_e32 v187, 31, v186
	v_and_b32_e32 v166, 0x19e00, v132
	v_lshl_add_u64 v[190:191], v[176:177], 0, v[170:171]
	v_lshl_add_u64 v[132:133], v[188:189], 0, v[166:167]
	v_lshlrev_b64 v[172:173], 11, v[186:187]
	v_lshl_add_u64 v[134:135], v[190:191], 0, v[172:173]
	global_load_dwordx4 v[200:203], v[132:133], off
	global_load_dwordx4 v[152:155], v[132:133], off offset:256
	global_load_dwordx4 v[204:207], v[134:135], off
	global_load_dwordx4 v[148:151], v[134:135], off offset:256
	v_or_b32_e32 v132, 16, v186
	v_ashrrev_i32_e32 v133, 31, v132
	v_lshlrev_b32_e32 v134, 9, v132
	v_and_b32_e32 v166, 0x1fe00, v134
	v_lshlrev_b64 v[192:193], 11, v[132:133]
	v_lshl_add_u64 v[134:135], v[188:189], 0, v[166:167]
	v_lshl_add_u64 v[132:133], v[190:191], 0, v[192:193]
	global_load_dwordx4 v[144:147], v[134:135], off
	global_load_dwordx4 v[136:139], v[134:135], off offset:256
	global_load_dwordx4 v[140:143], v[132:133], off
	s_nop 0
	global_load_dwordx4 v[132:135], v[132:133], off offset:256
	v_lshl_add_u64 v[184:185], v[164:165], 0, v[170:171]
	s_waitcnt vmcnt(0)
	v_lshlrev_b32_e32 v166, 16, v200
	v_mul_f32_e32 v166, 0xbfb8aa3b, v166
	v_exp_f32_e32 v166, v166
	v_lshl_add_u64 v[194:195], v[184:185], 0, v[172:173]
	v_lshlrev_b32_e32 v172, 16, v204
	v_and_b32_e32 v173, 0xffff0000, v204
	v_add_f32_e32 v166, 1.0, v166
	v_rcp_f32_e32 v170, v166
	v_and_b32_e32 v166, 0xffff0000, v200
	v_mul_f32_e32 v166, 0xbfb8aa3b, v166
	v_exp_f32_e32 v166, v166
	s_nop 0
	v_add_f32_e32 v166, 1.0, v166
	v_rcp_f32_e32 v171, v166
	v_lshlrev_b32_e32 v166, 16, v201
	v_mul_f32_e32 v166, 0xbfb8aa3b, v166
	v_exp_f32_e32 v166, v166
	v_pk_fma_f32 v[128:129], v[128:129], v[170:171], v[172:173]
	v_lshlrev_b32_e32 v172, 16, v205
	v_and_b32_e32 v173, 0xffff0000, v205
	v_add_f32_e32 v166, 1.0, v166
	v_rcp_f32_e32 v170, v166
	v_and_b32_e32 v166, 0xffff0000, v201
	v_mul_f32_e32 v166, 0xbfb8aa3b, v166
	v_exp_f32_e32 v166, v166
	s_nop 0
	v_add_f32_e32 v166, 1.0, v166
	v_rcp_f32_e32 v171, v166
	v_lshlrev_b32_e32 v166, 16, v202
	v_mul_f32_e32 v166, 0xbfb8aa3b, v166
	v_exp_f32_e32 v166, v166
	v_pk_fma_f32 v[130:131], v[130:131], v[170:171], v[172:173]
	v_lshlrev_b32_e32 v172, 16, v206
	v_and_b32_e32 v173, 0xffff0000, v206
	v_add_f32_e32 v166, 1.0, v166
	v_rcp_f32_e32 v170, v166
	v_and_b32_e32 v166, 0xffff0000, v202
	v_mul_f32_e32 v166, 0xbfb8aa3b, v166
	v_exp_f32_e32 v166, v166
	s_nop 0
	v_add_f32_e32 v166, 1.0, v166
	v_rcp_f32_e32 v171, v166
	s_nop 0
	v_pk_fma_f32 v[170:171], v[124:125], v[170:171], v[172:173]
	v_lshlrev_b32_e32 v124, 16, v203
	v_and_b32_e32 v125, 0xffff0000, v203
	v_mul_f32_e32 v124, 0xbfb8aa3b, v124
	v_mul_f32_e32 v125, 0xbfb8aa3b, v125
	v_exp_f32_e32 v124, v124
	v_exp_f32_e32 v125, v125
	v_lshlrev_b32_e32 v172, 16, v207
	v_and_b32_e32 v173, 0xffff0000, v207
	v_add_f32_e32 v124, 1.0, v124
	v_add_f32_e32 v125, 1.0, v125
	v_rcp_f32_e32 v124, v124
	v_rcp_f32_e32 v125, v125
	s_nop 0
	v_pk_fma_f32 v[172:173], v[126:127], v[124:125], v[172:173]
	v_cvt_pk_bf16_f32 v124, v128, v129
	v_cvt_pk_bf16_f32 v125, v130, v131
	v_cvt_pk_bf16_f32 v126, v170, v171
	v_cvt_pk_bf16_f32 v127, v172, v173
	global_store_dwordx4 v[194:195], v[124:127], off
	s_nop 1
	v_lshlrev_b32_e32 v124, 16, v152
	v_and_b32_e32 v125, 0xffff0000, v152
	v_mul_f32_e32 v124, 0xbfb8aa3b, v124
	v_mul_f32_e32 v125, 0xbfb8aa3b, v125
	v_exp_f32_e32 v124, v124
	v_exp_f32_e32 v125, v125
	v_lshlrev_b32_e32 v126, 16, v148
	v_and_b32_e32 v127, 0xffff0000, v148
	v_add_f32_e32 v124, 1.0, v124
	v_add_f32_e32 v125, 1.0, v125
	v_rcp_f32_e32 v124, v124
	v_rcp_f32_e32 v125, v125
	s_nop 0
	v_pk_fma_f32 v[120:121], v[120:121], v[124:125], v[126:127]
	v_lshlrev_b32_e32 v124, 16, v153
	v_and_b32_e32 v125, 0xffff0000, v153
	v_mul_f32_e32 v124, 0xbfb8aa3b, v124
	v_mul_f32_e32 v125, 0xbfb8aa3b, v125
	v_exp_f32_e32 v124, v124
	v_exp_f32_e32 v125, v125
	v_lshlrev_b32_e32 v126, 16, v149
	v_and_b32_e32 v127, 0xffff0000, v149
	v_add_f32_e32 v124, 1.0, v124
	v_add_f32_e32 v125, 1.0, v125
	v_rcp_f32_e32 v124, v124
	v_rcp_f32_e32 v125, v125
	s_nop 0
	v_pk_fma_f32 v[122:123], v[122:123], v[124:125], v[126:127]
	v_lshlrev_b32_e32 v124, 16, v154
	v_and_b32_e32 v125, 0xffff0000, v154
	v_mul_f32_e32 v124, 0xbfb8aa3b, v124
	v_mul_f32_e32 v125, 0xbfb8aa3b, v125
	v_exp_f32_e32 v124, v124
	v_exp_f32_e32 v125, v125
	v_lshlrev_b32_e32 v126, 16, v150
	v_and_b32_e32 v127, 0xffff0000, v150
	v_add_f32_e32 v124, 1.0, v124
	v_add_f32_e32 v125, 1.0, v125
	v_rcp_f32_e32 v124, v124
	v_rcp_f32_e32 v125, v125
	s_nop 0
	v_pk_fma_f32 v[124:125], v[116:117], v[124:125], v[126:127]
	v_lshlrev_b32_e32 v116, 16, v155
	v_and_b32_e32 v117, 0xffff0000, v155
	v_mul_f32_e32 v116, 0xbfb8aa3b, v116
	v_mul_f32_e32 v117, 0xbfb8aa3b, v117
	v_exp_f32_e32 v116, v116
	v_exp_f32_e32 v117, v117
	v_lshlrev_b32_e32 v126, 16, v151
	v_and_b32_e32 v127, 0xffff0000, v151
	v_add_f32_e32 v116, 1.0, v116
	v_add_f32_e32 v117, 1.0, v117
	v_rcp_f32_e32 v116, v116
	v_rcp_f32_e32 v117, v117
	s_nop 0
	v_pk_fma_f32 v[126:127], v[118:119], v[116:117], v[126:127]
	v_cvt_pk_bf16_f32 v116, v120, v121
	v_cvt_pk_bf16_f32 v117, v122, v123
	v_cvt_pk_bf16_f32 v118, v124, v125
	v_cvt_pk_bf16_f32 v119, v126, v127
	global_store_dwordx4 v[194:195], v[116:119], off offset:256
	v_lshlrev_b32_e32 v120, 16, v140
	v_and_b32_e32 v121, 0xffff0000, v140
	v_lshlrev_b32_e32 v118, 16, v144
	v_and_b32_e32 v119, 0xffff0000, v144
	v_mul_f32_e32 v118, 0xbfb8aa3b, v118
	v_mul_f32_e32 v119, 0xbfb8aa3b, v119
	v_exp_f32_e32 v118, v118
	v_exp_f32_e32 v119, v119
	v_lshl_add_u64 v[116:117], v[184:185], 0, v[192:193]
	v_add_f32_e32 v118, 1.0, v118
	v_add_f32_e32 v119, 1.0, v119
	v_rcp_f32_e32 v118, v118
	v_rcp_f32_e32 v119, v119
	s_nop 0
	v_pk_fma_f32 v[112:113], v[112:113], v[118:119], v[120:121]
	v_lshlrev_b32_e32 v118, 16, v145
	v_and_b32_e32 v119, 0xffff0000, v145
	v_mul_f32_e32 v118, 0xbfb8aa3b, v118
	v_mul_f32_e32 v119, 0xbfb8aa3b, v119
	v_exp_f32_e32 v118, v118
	v_exp_f32_e32 v119, v119
	v_lshlrev_b32_e32 v120, 16, v141
	v_and_b32_e32 v121, 0xffff0000, v141
	v_add_f32_e32 v118, 1.0, v118
	v_add_f32_e32 v119, 1.0, v119
	v_rcp_f32_e32 v118, v118
	v_rcp_f32_e32 v119, v119
	s_nop 0
	v_pk_fma_f32 v[114:115], v[114:115], v[118:119], v[120:121]
	v_lshlrev_b32_e32 v118, 16, v146
	v_and_b32_e32 v119, 0xffff0000, v146
	v_mul_f32_e32 v118, 0xbfb8aa3b, v118
	v_mul_f32_e32 v119, 0xbfb8aa3b, v119
	v_exp_f32_e32 v118, v118
	v_exp_f32_e32 v119, v119
	v_lshlrev_b32_e32 v120, 16, v142
	v_and_b32_e32 v121, 0xffff0000, v142
	v_add_f32_e32 v118, 1.0, v118
	v_add_f32_e32 v119, 1.0, v119
	v_rcp_f32_e32 v118, v118
	v_rcp_f32_e32 v119, v119
	s_nop 0
	v_pk_fma_f32 v[118:119], v[108:109], v[118:119], v[120:121]
	v_lshlrev_b32_e32 v108, 16, v147
	v_and_b32_e32 v109, 0xffff0000, v147
	v_mul_f32_e32 v108, 0xbfb8aa3b, v108
	v_mul_f32_e32 v109, 0xbfb8aa3b, v109
	v_exp_f32_e32 v108, v108
	v_exp_f32_e32 v109, v109
	v_lshlrev_b32_e32 v120, 16, v143
	v_and_b32_e32 v121, 0xffff0000, v143
	v_add_f32_e32 v108, 1.0, v108
	v_add_f32_e32 v109, 1.0, v109
	v_rcp_f32_e32 v108, v108
	v_rcp_f32_e32 v109, v109
	s_nop 0
	v_pk_fma_f32 v[120:121], v[110:111], v[108:109], v[120:121]
	v_cvt_pk_bf16_f32 v108, v112, v113
	v_cvt_pk_bf16_f32 v109, v114, v115
	v_cvt_pk_bf16_f32 v110, v118, v119
	v_cvt_pk_bf16_f32 v111, v120, v121
	global_store_dwordx4 v[116:117], v[108:111], off
	s_nop 1
	v_lshlrev_b32_e32 v108, 16, v136
	v_and_b32_e32 v109, 0xffff0000, v136
	v_mul_f32_e32 v108, 0xbfb8aa3b, v108
	v_mul_f32_e32 v109, 0xbfb8aa3b, v109
	v_exp_f32_e32 v108, v108
	v_exp_f32_e32 v109, v109
	v_lshlrev_b32_e32 v110, 16, v132
	v_and_b32_e32 v111, 0xffff0000, v132
	v_add_f32_e32 v108, 1.0, v108
	v_add_f32_e32 v109, 1.0, v109
	v_rcp_f32_e32 v108, v108
	v_rcp_f32_e32 v109, v109
	s_nop 0
	v_pk_fma_f32 v[104:105], v[104:105], v[108:109], v[110:111]
	v_lshlrev_b32_e32 v108, 16, v137
	v_and_b32_e32 v109, 0xffff0000, v137
	v_mul_f32_e32 v108, 0xbfb8aa3b, v108
	v_mul_f32_e32 v109, 0xbfb8aa3b, v109
	v_exp_f32_e32 v108, v108
	v_exp_f32_e32 v109, v109
	v_lshlrev_b32_e32 v110, 16, v133
	v_and_b32_e32 v111, 0xffff0000, v133
	v_add_f32_e32 v108, 1.0, v108
	v_add_f32_e32 v109, 1.0, v109
	v_rcp_f32_e32 v108, v108
	v_rcp_f32_e32 v109, v109
	s_nop 0
	v_pk_fma_f32 v[106:107], v[106:107], v[108:109], v[110:111]
	v_lshlrev_b32_e32 v108, 16, v138
	v_and_b32_e32 v109, 0xffff0000, v138
	v_mul_f32_e32 v108, 0xbfb8aa3b, v108
	v_mul_f32_e32 v109, 0xbfb8aa3b, v109
	v_exp_f32_e32 v108, v108
	v_exp_f32_e32 v109, v109
	v_lshlrev_b32_e32 v110, 16, v134
	v_and_b32_e32 v111, 0xffff0000, v134
	v_add_f32_e32 v108, 1.0, v108
	v_add_f32_e32 v109, 1.0, v109
	v_rcp_f32_e32 v108, v108
	v_rcp_f32_e32 v109, v109
	s_nop 0
	v_pk_fma_f32 v[108:109], v[100:101], v[108:109], v[110:111]
	v_lshlrev_b32_e32 v100, 16, v139
	v_and_b32_e32 v101, 0xffff0000, v139
	v_mul_f32_e32 v100, 0xbfb8aa3b, v100
	v_mul_f32_e32 v101, 0xbfb8aa3b, v101
	v_exp_f32_e32 v100, v100
	v_exp_f32_e32 v101, v101
	v_lshlrev_b32_e32 v110, 16, v135
	v_and_b32_e32 v111, 0xffff0000, v135
	v_add_f32_e32 v100, 1.0, v100
	v_add_f32_e32 v101, 1.0, v101
	v_rcp_f32_e32 v100, v100
	v_rcp_f32_e32 v101, v101
	s_nop 0
	v_pk_fma_f32 v[110:111], v[102:103], v[100:101], v[110:111]
	v_cvt_pk_bf16_f32 v100, v104, v105
	v_cvt_pk_bf16_f32 v101, v106, v107
	v_cvt_pk_bf16_f32 v102, v108, v109
	v_cvt_pk_bf16_f32 v103, v110, v111
	global_store_dwordx4 v[116:117], v[100:103], off offset:256
	s_nop 1
	v_or_b32_e32 v100, 32, v186
	v_ashrrev_i32_e32 v101, 31, v100
	v_lshlrev_b32_e32 v102, 9, v100
	v_and_b32_e32 v166, 0x1fe00, v102
	v_lshlrev_b64 v[126:127], 11, v[100:101]
	v_lshl_add_u64 v[102:103], v[188:189], 0, v[166:167]
	v_lshl_add_u64 v[100:101], v[190:191], 0, v[126:127]
	global_load_dwordx4 v[128:131], v[102:103], off
	global_load_dwordx4 v[120:123], v[102:103], off offset:256
	global_load_dwordx4 v[132:135], v[100:101], off
	global_load_dwordx4 v[116:119], v[100:101], off offset:256
	v_or_b32_e32 v100, 48, v186
	v_ashrrev_i32_e32 v101, 31, v100
	v_lshlrev_b32_e32 v102, 9, v100
	v_and_b32_e32 v166, 0x1fe00, v102
	v_lshlrev_b64 v[124:125], 11, v[100:101]
	v_lshl_add_u64 v[102:103], v[188:189], 0, v[166:167]
	v_lshl_add_u64 v[100:101], v[190:191], 0, v[124:125]
	global_load_dwordx4 v[112:115], v[102:103], off
	global_load_dwordx4 v[104:107], v[102:103], off offset:256
	global_load_dwordx4 v[108:111], v[100:101], off
	s_nop 0
	global_load_dwordx4 v[100:103], v[100:101], off offset:256
	s_waitcnt vmcnt(0)
	v_lshlrev_b32_e32 v136, 16, v128
	v_and_b32_e32 v128, 0xffff0000, v128
	v_mul_f32_e32 v128, 0xbfb8aa3b, v128
	v_exp_f32_e32 v128, v128
	v_lshlrev_b32_e32 v138, 16, v132
	v_and_b32_e32 v139, 0xffff0000, v132
	v_lshlrev_b32_e32 v132, 16, v133
	v_add_f32_e32 v128, 1.0, v128
	v_rcp_f32_e32 v137, v128
	v_lshlrev_b32_e32 v128, 16, v129
	v_and_b32_e32 v129, 0xffff0000, v129
	v_mul_f32_e32 v128, 0xbfb8aa3b, v128
	v_mul_f32_e32 v129, 0xbfb8aa3b, v129
	v_exp_f32_e32 v128, v128
	v_exp_f32_e32 v129, v129
	v_and_b32_e32 v133, 0xffff0000, v133
	v_mul_f32_e32 v136, 0xbfb8aa3b, v136
	v_add_f32_e32 v128, 1.0, v128
	v_add_f32_e32 v129, 1.0, v129
	v_rcp_f32_e32 v128, v128
	v_rcp_f32_e32 v129, v129
	v_exp_f32_e32 v136, v136
	v_lshl_add_u64 v[126:127], v[184:185], 0, v[126:127]
	v_pk_fma_f32 v[98:99], v[98:99], v[128:129], v[132:133]
	v_lshlrev_b32_e32 v128, 16, v130
	v_and_b32_e32 v129, 0xffff0000, v130
	v_mul_f32_e32 v128, 0xbfb8aa3b, v128
	v_mul_f32_e32 v129, 0xbfb8aa3b, v129
	v_exp_f32_e32 v128, v128
	v_exp_f32_e32 v129, v129
	v_lshlrev_b32_e32 v132, 16, v134
	v_and_b32_e32 v133, 0xffff0000, v134
	v_add_f32_e32 v128, 1.0, v128
	v_add_f32_e32 v129, 1.0, v129
	v_rcp_f32_e32 v128, v128
	v_rcp_f32_e32 v129, v129
	v_add_f32_e32 v136, 1.0, v136
	v_rcp_f32_e32 v136, v136
	v_lshlrev_b32_e32 v130, 16, v135
	v_pk_fma_f32 v[128:129], v[92:93], v[128:129], v[132:133]
	v_lshlrev_b32_e32 v92, 16, v131
	v_and_b32_e32 v93, 0xffff0000, v131
	v_mul_f32_e32 v92, 0xbfb8aa3b, v92
	v_mul_f32_e32 v93, 0xbfb8aa3b, v93
	v_exp_f32_e32 v92, v92
	v_exp_f32_e32 v93, v93
	v_and_b32_e32 v131, 0xffff0000, v135
	v_pk_fma_f32 v[96:97], v[96:97], v[136:137], v[138:139]
	v_add_f32_e32 v92, 1.0, v92
	v_add_f32_e32 v93, 1.0, v93
	v_rcp_f32_e32 v92, v92
	v_rcp_f32_e32 v93, v93
	s_nop 0
	v_pk_fma_f32 v[130:131], v[94:95], v[92:93], v[130:131]
	v_cvt_pk_bf16_f32 v92, v96, v97
	v_cvt_pk_bf16_f32 v93, v98, v99
	v_cvt_pk_bf16_f32 v94, v128, v129
	v_cvt_pk_bf16_f32 v95, v130, v131
	global_store_dwordx4 v[126:127], v[92:95], off
	s_nop 1
	v_lshlrev_b32_e32 v92, 16, v120
	v_and_b32_e32 v93, 0xffff0000, v120
	v_mul_f32_e32 v92, 0xbfb8aa3b, v92
	v_mul_f32_e32 v93, 0xbfb8aa3b, v93
	v_exp_f32_e32 v92, v92
	v_exp_f32_e32 v93, v93
	v_lshlrev_b32_e32 v94, 16, v116
	v_and_b32_e32 v95, 0xffff0000, v116
	v_add_f32_e32 v92, 1.0, v92
	v_add_f32_e32 v93, 1.0, v93
	v_rcp_f32_e32 v92, v92
	v_rcp_f32_e32 v93, v93
	s_nop 0
	v_pk_fma_f32 v[88:89], v[88:89], v[92:93], v[94:95]
	v_lshlrev_b32_e32 v92, 16, v121
	v_and_b32_e32 v93, 0xffff0000, v121
	v_mul_f32_e32 v92, 0xbfb8aa3b, v92
	v_mul_f32_e32 v93, 0xbfb8aa3b, v93
	v_exp_f32_e32 v92, v92
	v_exp_f32_e32 v93, v93
	v_lshlrev_b32_e32 v94, 16, v117
	v_and_b32_e32 v95, 0xffff0000, v117
	v_add_f32_e32 v92, 1.0, v92
	v_add_f32_e32 v93, 1.0, v93
	v_rcp_f32_e32 v92, v92
	v_rcp_f32_e32 v93, v93
	s_nop 0
	v_pk_fma_f32 v[90:91], v[90:91], v[92:93], v[94:95]
	v_lshlrev_b32_e32 v92, 16, v122
	v_and_b32_e32 v93, 0xffff0000, v122
	v_mul_f32_e32 v92, 0xbfb8aa3b, v92
	v_mul_f32_e32 v93, 0xbfb8aa3b, v93
	v_exp_f32_e32 v92, v92
	v_exp_f32_e32 v93, v93
	v_lshlrev_b32_e32 v94, 16, v118
	v_and_b32_e32 v95, 0xffff0000, v118
	v_add_f32_e32 v92, 1.0, v92
	v_add_f32_e32 v93, 1.0, v93
	v_rcp_f32_e32 v92, v92
	v_rcp_f32_e32 v93, v93
	s_nop 0
	v_pk_fma_f32 v[92:93], v[84:85], v[92:93], v[94:95]
	v_lshlrev_b32_e32 v84, 16, v123
	v_and_b32_e32 v85, 0xffff0000, v123
	v_mul_f32_e32 v84, 0xbfb8aa3b, v84
	v_mul_f32_e32 v85, 0xbfb8aa3b, v85
	v_exp_f32_e32 v84, v84
	v_exp_f32_e32 v85, v85
	v_lshlrev_b32_e32 v94, 16, v119
	v_and_b32_e32 v95, 0xffff0000, v119
	v_add_f32_e32 v84, 1.0, v84
	v_add_f32_e32 v85, 1.0, v85
	v_rcp_f32_e32 v84, v84
	v_rcp_f32_e32 v85, v85
	s_nop 0
	v_pk_fma_f32 v[94:95], v[86:87], v[84:85], v[94:95]
	v_cvt_pk_bf16_f32 v84, v88, v89
	v_cvt_pk_bf16_f32 v85, v90, v91
	v_cvt_pk_bf16_f32 v86, v92, v93
	v_cvt_pk_bf16_f32 v87, v94, v95
	global_store_dwordx4 v[126:127], v[84:87], off offset:256
	v_lshlrev_b32_e32 v88, 16, v108
	v_and_b32_e32 v89, 0xffff0000, v108
	v_lshlrev_b32_e32 v86, 16, v112
	v_and_b32_e32 v87, 0xffff0000, v112
	v_mul_f32_e32 v86, 0xbfb8aa3b, v86
	v_mul_f32_e32 v87, 0xbfb8aa3b, v87
	v_exp_f32_e32 v86, v86
	v_exp_f32_e32 v87, v87
	v_lshl_add_u64 v[84:85], v[184:185], 0, v[124:125]
	v_add_f32_e32 v86, 1.0, v86
	v_add_f32_e32 v87, 1.0, v87
	v_rcp_f32_e32 v86, v86
	v_rcp_f32_e32 v87, v87
	s_nop 0
	v_pk_fma_f32 v[76:77], v[76:77], v[86:87], v[88:89]
	v_lshlrev_b32_e32 v86, 16, v113
	v_and_b32_e32 v87, 0xffff0000, v113
	v_mul_f32_e32 v86, 0xbfb8aa3b, v86
	v_mul_f32_e32 v87, 0xbfb8aa3b, v87
	v_exp_f32_e32 v86, v86
	v_exp_f32_e32 v87, v87
	v_lshlrev_b32_e32 v88, 16, v109
	v_and_b32_e32 v89, 0xffff0000, v109
	v_add_f32_e32 v86, 1.0, v86
	v_add_f32_e32 v87, 1.0, v87
	v_rcp_f32_e32 v86, v86
	v_rcp_f32_e32 v87, v87
	s_nop 0
	v_pk_fma_f32 v[78:79], v[78:79], v[86:87], v[88:89]
	v_lshlrev_b32_e32 v86, 16, v114
	v_and_b32_e32 v87, 0xffff0000, v114
	v_mul_f32_e32 v86, 0xbfb8aa3b, v86
	v_mul_f32_e32 v87, 0xbfb8aa3b, v87
	v_exp_f32_e32 v86, v86
	v_exp_f32_e32 v87, v87
	v_lshlrev_b32_e32 v88, 16, v110
	v_and_b32_e32 v89, 0xffff0000, v110
	v_add_f32_e32 v86, 1.0, v86
	v_add_f32_e32 v87, 1.0, v87
	v_rcp_f32_e32 v86, v86
	v_rcp_f32_e32 v87, v87
	s_nop 0
	v_pk_fma_f32 v[86:87], v[72:73], v[86:87], v[88:89]
	v_lshlrev_b32_e32 v72, 16, v115
	v_and_b32_e32 v73, 0xffff0000, v115
	v_mul_f32_e32 v72, 0xbfb8aa3b, v72
	v_mul_f32_e32 v73, 0xbfb8aa3b, v73
	v_exp_f32_e32 v72, v72
	v_exp_f32_e32 v73, v73
	v_lshlrev_b32_e32 v88, 16, v111
	v_and_b32_e32 v89, 0xffff0000, v111
	v_add_f32_e32 v72, 1.0, v72
	v_add_f32_e32 v73, 1.0, v73
	v_rcp_f32_e32 v72, v72
	v_rcp_f32_e32 v73, v73
	s_nop 0
	v_pk_fma_f32 v[88:89], v[74:75], v[72:73], v[88:89]
	v_cvt_pk_bf16_f32 v72, v76, v77
	v_cvt_pk_bf16_f32 v73, v78, v79
	v_cvt_pk_bf16_f32 v74, v86, v87
	v_cvt_pk_bf16_f32 v75, v88, v89
	global_store_dwordx4 v[84:85], v[72:75], off
	s_nop 1
	v_lshlrev_b32_e32 v72, 16, v104
	v_and_b32_e32 v73, 0xffff0000, v104
	v_mul_f32_e32 v72, 0xbfb8aa3b, v72
	v_mul_f32_e32 v73, 0xbfb8aa3b, v73
	v_exp_f32_e32 v72, v72
	v_exp_f32_e32 v73, v73
	v_lshlrev_b32_e32 v74, 16, v100
	v_and_b32_e32 v75, 0xffff0000, v100
	v_add_f32_e32 v72, 1.0, v72
	v_add_f32_e32 v73, 1.0, v73
	v_rcp_f32_e32 v72, v72
	v_rcp_f32_e32 v73, v73
	s_nop 0
	v_pk_fma_f32 v[68:69], v[68:69], v[72:73], v[74:75]
	v_lshlrev_b32_e32 v72, 16, v105
	v_and_b32_e32 v73, 0xffff0000, v105
	v_mul_f32_e32 v72, 0xbfb8aa3b, v72
	v_mul_f32_e32 v73, 0xbfb8aa3b, v73
	v_exp_f32_e32 v72, v72
	v_exp_f32_e32 v73, v73
	v_lshlrev_b32_e32 v74, 16, v101
	v_and_b32_e32 v75, 0xffff0000, v101
	v_add_f32_e32 v72, 1.0, v72
	v_add_f32_e32 v73, 1.0, v73
	v_rcp_f32_e32 v72, v72
	v_rcp_f32_e32 v73, v73
	s_nop 0
	v_pk_fma_f32 v[70:71], v[70:71], v[72:73], v[74:75]
	v_lshlrev_b32_e32 v72, 16, v106
	v_and_b32_e32 v73, 0xffff0000, v106
	v_mul_f32_e32 v72, 0xbfb8aa3b, v72
	v_mul_f32_e32 v73, 0xbfb8aa3b, v73
	v_exp_f32_e32 v72, v72
	v_exp_f32_e32 v73, v73
	v_lshlrev_b32_e32 v74, 16, v102
	v_and_b32_e32 v75, 0xffff0000, v102
	v_add_f32_e32 v72, 1.0, v72
	v_add_f32_e32 v73, 1.0, v73
	v_rcp_f32_e32 v72, v72
	v_rcp_f32_e32 v73, v73
	s_nop 0
	v_pk_fma_f32 v[72:73], v[64:65], v[72:73], v[74:75]
	v_lshlrev_b32_e32 v64, 16, v107
	v_and_b32_e32 v65, 0xffff0000, v107
	v_mul_f32_e32 v64, 0xbfb8aa3b, v64
	v_mul_f32_e32 v65, 0xbfb8aa3b, v65
	v_exp_f32_e32 v64, v64
	v_exp_f32_e32 v65, v65
	v_lshlrev_b32_e32 v74, 16, v103
	v_and_b32_e32 v75, 0xffff0000, v103
	v_add_f32_e32 v64, 1.0, v64
	v_add_f32_e32 v65, 1.0, v65
	v_rcp_f32_e32 v64, v64
	v_rcp_f32_e32 v65, v65
	s_nop 0
	v_pk_fma_f32 v[74:75], v[66:67], v[64:65], v[74:75]
	v_cvt_pk_bf16_f32 v64, v68, v69
	v_cvt_pk_bf16_f32 v65, v70, v71
	v_cvt_pk_bf16_f32 v66, v72, v73
	v_cvt_pk_bf16_f32 v67, v74, v75
	global_store_dwordx4 v[84:85], v[64:67], off offset:256
	s_nop 1
	v_add_u32_e32 v64, 0x80, v186
	v_ashrrev_i32_e32 v65, 31, v64
	v_lshlrev_b32_e32 v66, 9, v64
	v_and_b32_e32 v166, 0x1fe00, v66
	v_lshlrev_b64 v[94:95], 11, v[64:65]
	v_lshl_add_u64 v[66:67], v[188:189], 0, v[166:167]
	v_lshl_add_u64 v[64:65], v[190:191], 0, v[94:95]
	global_load_dwordx4 v[96:99], v[66:67], off
	global_load_dwordx4 v[88:91], v[66:67], off offset:256
	global_load_dwordx4 v[100:103], v[64:65], off
	global_load_dwordx4 v[84:87], v[64:65], off offset:256
	v_add_u32_e32 v64, 0x90, v186
	v_ashrrev_i32_e32 v65, 31, v64
	v_lshlrev_b32_e32 v66, 9, v64
	v_and_b32_e32 v166, 0x1fe00, v66
	v_lshlrev_b64 v[92:93], 11, v[64:65]
	v_lshl_add_u64 v[66:67], v[188:189], 0, v[166:167]
	v_lshl_add_u64 v[64:65], v[190:191], 0, v[92:93]
	global_load_dwordx4 v[76:79], v[66:67], off
	global_load_dwordx4 v[68:71], v[66:67], off offset:256
	global_load_dwordx4 v[72:75], v[64:65], off
	s_nop 0
	global_load_dwordx4 v[64:67], v[64:65], off offset:256
	s_waitcnt vmcnt(0)
	v_lshlrev_b32_e32 v104, 16, v96
	v_and_b32_e32 v96, 0xffff0000, v96
	v_mul_f32_e32 v96, 0xbfb8aa3b, v96
	v_exp_f32_e32 v96, v96
	v_lshlrev_b32_e32 v106, 16, v100
	v_and_b32_e32 v107, 0xffff0000, v100
	v_lshlrev_b32_e32 v100, 16, v101
	v_add_f32_e32 v96, 1.0, v96
	v_rcp_f32_e32 v105, v96
	v_lshlrev_b32_e32 v96, 16, v97
	v_and_b32_e32 v97, 0xffff0000, v97
	v_mul_f32_e32 v96, 0xbfb8aa3b, v96
	v_mul_f32_e32 v97, 0xbfb8aa3b, v97
	v_exp_f32_e32 v96, v96
	v_exp_f32_e32 v97, v97
	v_and_b32_e32 v101, 0xffff0000, v101
	v_mul_f32_e32 v104, 0xbfb8aa3b, v104
	v_add_f32_e32 v96, 1.0, v96
	v_add_f32_e32 v97, 1.0, v97
	v_rcp_f32_e32 v96, v96
	v_rcp_f32_e32 v97, v97
	v_exp_f32_e32 v104, v104
	v_lshl_add_u64 v[94:95], v[184:185], 0, v[94:95]
	v_pk_fma_f32 v[62:63], v[62:63], v[96:97], v[100:101]
	v_lshlrev_b32_e32 v96, 16, v98
	v_and_b32_e32 v97, 0xffff0000, v98
	v_mul_f32_e32 v96, 0xbfb8aa3b, v96
	v_mul_f32_e32 v97, 0xbfb8aa3b, v97
	v_exp_f32_e32 v96, v96
	v_exp_f32_e32 v97, v97
	v_lshlrev_b32_e32 v100, 16, v102
	v_and_b32_e32 v101, 0xffff0000, v102
	v_add_f32_e32 v96, 1.0, v96
	v_add_f32_e32 v97, 1.0, v97
	v_rcp_f32_e32 v96, v96
	v_rcp_f32_e32 v97, v97
	v_add_f32_e32 v104, 1.0, v104
	v_rcp_f32_e32 v104, v104
	v_lshlrev_b32_e32 v98, 16, v103
	v_pk_fma_f32 v[96:97], v[56:57], v[96:97], v[100:101]
	v_lshlrev_b32_e32 v56, 16, v99
	v_and_b32_e32 v57, 0xffff0000, v99
	v_mul_f32_e32 v56, 0xbfb8aa3b, v56
	v_mul_f32_e32 v57, 0xbfb8aa3b, v57
	v_exp_f32_e32 v56, v56
	v_exp_f32_e32 v57, v57
	v_and_b32_e32 v99, 0xffff0000, v103
	v_pk_fma_f32 v[60:61], v[60:61], v[104:105], v[106:107]
	v_add_f32_e32 v56, 1.0, v56
	v_add_f32_e32 v57, 1.0, v57
	v_rcp_f32_e32 v56, v56
	v_rcp_f32_e32 v57, v57
	s_nop 0
	v_pk_fma_f32 v[98:99], v[58:59], v[56:57], v[98:99]
	v_cvt_pk_bf16_f32 v56, v60, v61
	v_cvt_pk_bf16_f32 v57, v62, v63
	v_cvt_pk_bf16_f32 v58, v96, v97
	v_cvt_pk_bf16_f32 v59, v98, v99
	global_store_dwordx4 v[94:95], v[56:59], off
	s_nop 1
	v_lshlrev_b32_e32 v56, 16, v88
	v_and_b32_e32 v57, 0xffff0000, v88
	v_mul_f32_e32 v56, 0xbfb8aa3b, v56
	v_mul_f32_e32 v57, 0xbfb8aa3b, v57
	v_exp_f32_e32 v56, v56
	v_exp_f32_e32 v57, v57
	v_lshlrev_b32_e32 v58, 16, v84
	v_and_b32_e32 v59, 0xffff0000, v84
	v_add_f32_e32 v56, 1.0, v56
	v_add_f32_e32 v57, 1.0, v57
	v_rcp_f32_e32 v56, v56
	v_rcp_f32_e32 v57, v57
	s_nop 0
	v_pk_fma_f32 v[52:53], v[52:53], v[56:57], v[58:59]
	v_lshlrev_b32_e32 v56, 16, v89
	v_and_b32_e32 v57, 0xffff0000, v89
	v_mul_f32_e32 v56, 0xbfb8aa3b, v56
	v_mul_f32_e32 v57, 0xbfb8aa3b, v57
	v_exp_f32_e32 v56, v56
	v_exp_f32_e32 v57, v57
	v_lshlrev_b32_e32 v58, 16, v85
	v_and_b32_e32 v59, 0xffff0000, v85
	v_add_f32_e32 v56, 1.0, v56
	v_add_f32_e32 v57, 1.0, v57
	v_rcp_f32_e32 v56, v56
	v_rcp_f32_e32 v57, v57
	s_nop 0
	v_pk_fma_f32 v[54:55], v[54:55], v[56:57], v[58:59]
	v_lshlrev_b32_e32 v56, 16, v90
	v_and_b32_e32 v57, 0xffff0000, v90
	v_mul_f32_e32 v56, 0xbfb8aa3b, v56
	v_mul_f32_e32 v57, 0xbfb8aa3b, v57
	v_exp_f32_e32 v56, v56
	v_exp_f32_e32 v57, v57
	v_lshlrev_b32_e32 v58, 16, v86
	v_and_b32_e32 v59, 0xffff0000, v86
	v_add_f32_e32 v56, 1.0, v56
	v_add_f32_e32 v57, 1.0, v57
	v_rcp_f32_e32 v56, v56
	v_rcp_f32_e32 v57, v57
	s_nop 0
	v_pk_fma_f32 v[56:57], v[48:49], v[56:57], v[58:59]
	v_lshlrev_b32_e32 v48, 16, v91
	v_and_b32_e32 v49, 0xffff0000, v91
	v_mul_f32_e32 v48, 0xbfb8aa3b, v48
	v_mul_f32_e32 v49, 0xbfb8aa3b, v49
	v_exp_f32_e32 v48, v48
	v_exp_f32_e32 v49, v49
	v_lshlrev_b32_e32 v58, 16, v87
	v_and_b32_e32 v59, 0xffff0000, v87
	v_add_f32_e32 v48, 1.0, v48
	v_add_f32_e32 v49, 1.0, v49
	v_rcp_f32_e32 v48, v48
	v_rcp_f32_e32 v49, v49
	s_nop 0
	v_pk_fma_f32 v[58:59], v[50:51], v[48:49], v[58:59]
	v_cvt_pk_bf16_f32 v48, v52, v53
	v_cvt_pk_bf16_f32 v49, v54, v55
	v_cvt_pk_bf16_f32 v50, v56, v57
	v_cvt_pk_bf16_f32 v51, v58, v59
	global_store_dwordx4 v[94:95], v[48:51], off offset:256
	v_lshlrev_b32_e32 v52, 16, v72
	v_and_b32_e32 v53, 0xffff0000, v72
	v_lshlrev_b32_e32 v50, 16, v76
	v_and_b32_e32 v51, 0xffff0000, v76
	v_mul_f32_e32 v50, 0xbfb8aa3b, v50
	v_mul_f32_e32 v51, 0xbfb8aa3b, v51
	v_exp_f32_e32 v50, v50
	v_exp_f32_e32 v51, v51
	v_lshl_add_u64 v[48:49], v[184:185], 0, v[92:93]
	v_add_f32_e32 v50, 1.0, v50
	v_add_f32_e32 v51, 1.0, v51
	v_rcp_f32_e32 v50, v50
	v_rcp_f32_e32 v51, v51
	s_nop 0
	v_pk_fma_f32 v[44:45], v[44:45], v[50:51], v[52:53]
	v_lshlrev_b32_e32 v50, 16, v77
	v_and_b32_e32 v51, 0xffff0000, v77
	v_mul_f32_e32 v50, 0xbfb8aa3b, v50
	v_mul_f32_e32 v51, 0xbfb8aa3b, v51
	v_exp_f32_e32 v50, v50
	v_exp_f32_e32 v51, v51
	v_lshlrev_b32_e32 v52, 16, v73
	v_and_b32_e32 v53, 0xffff0000, v73
	v_add_f32_e32 v50, 1.0, v50
	v_add_f32_e32 v51, 1.0, v51
	v_rcp_f32_e32 v50, v50
	v_rcp_f32_e32 v51, v51
	s_nop 0
	v_pk_fma_f32 v[46:47], v[46:47], v[50:51], v[52:53]
	v_lshlrev_b32_e32 v50, 16, v78
	v_and_b32_e32 v51, 0xffff0000, v78
	v_mul_f32_e32 v50, 0xbfb8aa3b, v50
	v_mul_f32_e32 v51, 0xbfb8aa3b, v51
	v_exp_f32_e32 v50, v50
	v_exp_f32_e32 v51, v51
	v_lshlrev_b32_e32 v52, 16, v74
	v_and_b32_e32 v53, 0xffff0000, v74
	v_add_f32_e32 v50, 1.0, v50
	v_add_f32_e32 v51, 1.0, v51
	v_rcp_f32_e32 v50, v50
	v_rcp_f32_e32 v51, v51
	s_nop 0
	v_pk_fma_f32 v[50:51], v[40:41], v[50:51], v[52:53]
	v_lshlrev_b32_e32 v40, 16, v79
	v_and_b32_e32 v41, 0xffff0000, v79
	v_mul_f32_e32 v40, 0xbfb8aa3b, v40
	v_mul_f32_e32 v41, 0xbfb8aa3b, v41
	v_exp_f32_e32 v40, v40
	v_exp_f32_e32 v41, v41
	v_lshlrev_b32_e32 v52, 16, v75
	v_and_b32_e32 v53, 0xffff0000, v75
	v_add_f32_e32 v40, 1.0, v40
	v_add_f32_e32 v41, 1.0, v41
	v_rcp_f32_e32 v40, v40
	v_rcp_f32_e32 v41, v41
	s_nop 0
	v_pk_fma_f32 v[52:53], v[42:43], v[40:41], v[52:53]
	v_cvt_pk_bf16_f32 v40, v44, v45
	v_cvt_pk_bf16_f32 v41, v46, v47
	v_cvt_pk_bf16_f32 v42, v50, v51
	v_cvt_pk_bf16_f32 v43, v52, v53
	global_store_dwordx4 v[48:49], v[40:43], off
	s_nop 1
	v_lshlrev_b32_e32 v40, 16, v68
	v_and_b32_e32 v41, 0xffff0000, v68
	v_mul_f32_e32 v40, 0xbfb8aa3b, v40
	v_mul_f32_e32 v41, 0xbfb8aa3b, v41
	v_exp_f32_e32 v40, v40
	v_exp_f32_e32 v41, v41
	v_lshlrev_b32_e32 v42, 16, v64
	v_and_b32_e32 v43, 0xffff0000, v64
	v_add_f32_e32 v40, 1.0, v40
	v_add_f32_e32 v41, 1.0, v41
	v_rcp_f32_e32 v40, v40
	v_rcp_f32_e32 v41, v41
	s_nop 0
	v_pk_fma_f32 v[36:37], v[36:37], v[40:41], v[42:43]
	v_lshlrev_b32_e32 v40, 16, v69
	v_and_b32_e32 v41, 0xffff0000, v69
	v_mul_f32_e32 v40, 0xbfb8aa3b, v40
	v_mul_f32_e32 v41, 0xbfb8aa3b, v41
	v_exp_f32_e32 v40, v40
	v_exp_f32_e32 v41, v41
	v_lshlrev_b32_e32 v42, 16, v65
	v_and_b32_e32 v43, 0xffff0000, v65
	v_add_f32_e32 v40, 1.0, v40
	v_add_f32_e32 v41, 1.0, v41
	v_rcp_f32_e32 v40, v40
	v_rcp_f32_e32 v41, v41
	s_nop 0
	v_pk_fma_f32 v[38:39], v[38:39], v[40:41], v[42:43]
	v_lshlrev_b32_e32 v40, 16, v70
	v_and_b32_e32 v41, 0xffff0000, v70
	v_mul_f32_e32 v40, 0xbfb8aa3b, v40
	v_mul_f32_e32 v41, 0xbfb8aa3b, v41
	v_exp_f32_e32 v40, v40
	v_exp_f32_e32 v41, v41
	v_lshlrev_b32_e32 v42, 16, v66
	v_and_b32_e32 v43, 0xffff0000, v66
	v_add_f32_e32 v40, 1.0, v40
	v_add_f32_e32 v41, 1.0, v41
	v_rcp_f32_e32 v40, v40
	v_rcp_f32_e32 v41, v41
	s_nop 0
	v_pk_fma_f32 v[40:41], v[32:33], v[40:41], v[42:43]
	v_lshlrev_b32_e32 v32, 16, v71
	v_and_b32_e32 v33, 0xffff0000, v71
	v_mul_f32_e32 v32, 0xbfb8aa3b, v32
	v_mul_f32_e32 v33, 0xbfb8aa3b, v33
	v_exp_f32_e32 v32, v32
	v_exp_f32_e32 v33, v33
	v_lshlrev_b32_e32 v42, 16, v67
	v_and_b32_e32 v43, 0xffff0000, v67
	v_add_f32_e32 v32, 1.0, v32
	v_add_f32_e32 v33, 1.0, v33
	v_rcp_f32_e32 v32, v32
	v_rcp_f32_e32 v33, v33
	s_nop 0
	v_pk_fma_f32 v[42:43], v[34:35], v[32:33], v[42:43]
	v_cvt_pk_bf16_f32 v32, v36, v37
	v_cvt_pk_bf16_f32 v33, v38, v39
	v_cvt_pk_bf16_f32 v34, v40, v41
	v_cvt_pk_bf16_f32 v35, v42, v43
	global_store_dwordx4 v[48:49], v[32:35], off offset:256
	s_nop 1
	v_add_u32_e32 v32, 0xa0, v186
	v_ashrrev_i32_e32 v33, 31, v32
	v_lshlrev_b32_e32 v34, 9, v32
	v_and_b32_e32 v166, 0x1fe00, v34
	v_lshlrev_b64 v[58:59], 11, v[32:33]
	v_lshl_add_u64 v[34:35], v[188:189], 0, v[166:167]
	v_lshl_add_u64 v[32:33], v[190:191], 0, v[58:59]
	global_load_dwordx4 v[60:63], v[34:35], off
	global_load_dwordx4 v[52:55], v[34:35], off offset:256
	global_load_dwordx4 v[64:67], v[32:33], off
	global_load_dwordx4 v[48:51], v[32:33], off offset:256
	v_add_u32_e32 v32, 0xb0, v186
	v_ashrrev_i32_e32 v33, 31, v32
	v_lshlrev_b32_e32 v34, 9, v32
	v_and_b32_e32 v166, 0x1fe00, v34
	v_lshlrev_b64 v[56:57], 11, v[32:33]
	v_lshl_add_u64 v[34:35], v[188:189], 0, v[166:167]
	v_lshl_add_u64 v[32:33], v[190:191], 0, v[56:57]
	global_load_dwordx4 v[44:47], v[34:35], off
	global_load_dwordx4 v[36:39], v[34:35], off offset:256
	global_load_dwordx4 v[40:43], v[32:33], off
	s_nop 0
	global_load_dwordx4 v[32:35], v[32:33], off offset:256
	s_waitcnt vmcnt(0)
	v_lshlrev_b32_e32 v68, 16, v60
	v_and_b32_e32 v60, 0xffff0000, v60
	v_mul_f32_e32 v60, 0xbfb8aa3b, v60
	v_exp_f32_e32 v60, v60
	v_lshlrev_b32_e32 v70, 16, v64
	v_and_b32_e32 v71, 0xffff0000, v64
	v_lshlrev_b32_e32 v64, 16, v65
	v_add_f32_e32 v60, 1.0, v60
	v_rcp_f32_e32 v69, v60
	v_lshlrev_b32_e32 v60, 16, v61
	v_and_b32_e32 v61, 0xffff0000, v61
	v_mul_f32_e32 v60, 0xbfb8aa3b, v60
	v_mul_f32_e32 v61, 0xbfb8aa3b, v61
	v_exp_f32_e32 v60, v60
	v_exp_f32_e32 v61, v61
	v_and_b32_e32 v65, 0xffff0000, v65
	v_mul_f32_e32 v68, 0xbfb8aa3b, v68
	v_add_f32_e32 v60, 1.0, v60
	v_add_f32_e32 v61, 1.0, v61
	v_rcp_f32_e32 v60, v60
	v_rcp_f32_e32 v61, v61
	v_exp_f32_e32 v68, v68
	v_lshl_add_u64 v[58:59], v[184:185], 0, v[58:59]
	v_pk_fma_f32 v[30:31], v[30:31], v[60:61], v[64:65]
	v_lshlrev_b32_e32 v60, 16, v62
	v_and_b32_e32 v61, 0xffff0000, v62
	v_mul_f32_e32 v60, 0xbfb8aa3b, v60
	v_mul_f32_e32 v61, 0xbfb8aa3b, v61
	v_exp_f32_e32 v60, v60
	v_exp_f32_e32 v61, v61
	v_lshlrev_b32_e32 v64, 16, v66
	v_and_b32_e32 v65, 0xffff0000, v66
	v_add_f32_e32 v60, 1.0, v60
	v_add_f32_e32 v61, 1.0, v61
	v_rcp_f32_e32 v60, v60
	v_rcp_f32_e32 v61, v61
	v_add_f32_e32 v68, 1.0, v68
	v_rcp_f32_e32 v68, v68
	v_lshlrev_b32_e32 v62, 16, v67
	v_pk_fma_f32 v[60:61], v[24:25], v[60:61], v[64:65]
	v_lshlrev_b32_e32 v24, 16, v63
	v_and_b32_e32 v25, 0xffff0000, v63
	v_mul_f32_e32 v24, 0xbfb8aa3b, v24
	v_mul_f32_e32 v25, 0xbfb8aa3b, v25
	v_exp_f32_e32 v24, v24
	v_exp_f32_e32 v25, v25
	v_and_b32_e32 v63, 0xffff0000, v67
	v_pk_fma_f32 v[28:29], v[28:29], v[68:69], v[70:71]
	v_add_f32_e32 v24, 1.0, v24
	v_add_f32_e32 v25, 1.0, v25
	v_rcp_f32_e32 v24, v24
	v_rcp_f32_e32 v25, v25
	s_nop 0
	v_pk_fma_f32 v[62:63], v[26:27], v[24:25], v[62:63]
	v_cvt_pk_bf16_f32 v24, v28, v29
	v_cvt_pk_bf16_f32 v25, v30, v31
	v_cvt_pk_bf16_f32 v26, v60, v61
	v_cvt_pk_bf16_f32 v27, v62, v63
	global_store_dwordx4 v[58:59], v[24:27], off
	s_nop 1
	v_lshlrev_b32_e32 v24, 16, v52
	v_and_b32_e32 v25, 0xffff0000, v52
	v_mul_f32_e32 v24, 0xbfb8aa3b, v24
	v_mul_f32_e32 v25, 0xbfb8aa3b, v25
	v_exp_f32_e32 v24, v24
	v_exp_f32_e32 v25, v25
	v_lshlrev_b32_e32 v26, 16, v48
	v_and_b32_e32 v27, 0xffff0000, v48
	v_add_f32_e32 v24, 1.0, v24
	v_add_f32_e32 v25, 1.0, v25
	v_rcp_f32_e32 v24, v24
	v_rcp_f32_e32 v25, v25
	s_nop 0
	v_pk_fma_f32 v[20:21], v[20:21], v[24:25], v[26:27]
	v_lshlrev_b32_e32 v24, 16, v53
	v_and_b32_e32 v25, 0xffff0000, v53
	v_mul_f32_e32 v24, 0xbfb8aa3b, v24
	v_mul_f32_e32 v25, 0xbfb8aa3b, v25
	v_exp_f32_e32 v24, v24
	v_exp_f32_e32 v25, v25
	v_lshlrev_b32_e32 v26, 16, v49
	v_and_b32_e32 v27, 0xffff0000, v49
	v_add_f32_e32 v24, 1.0, v24
	v_add_f32_e32 v25, 1.0, v25
	v_rcp_f32_e32 v24, v24
	v_rcp_f32_e32 v25, v25
	s_nop 0
	v_pk_fma_f32 v[22:23], v[22:23], v[24:25], v[26:27]
	v_lshlrev_b32_e32 v24, 16, v54
	v_and_b32_e32 v25, 0xffff0000, v54
	v_mul_f32_e32 v24, 0xbfb8aa3b, v24
	v_mul_f32_e32 v25, 0xbfb8aa3b, v25
	v_exp_f32_e32 v24, v24
	v_exp_f32_e32 v25, v25
	v_lshlrev_b32_e32 v26, 16, v50
	v_and_b32_e32 v27, 0xffff0000, v50
	v_add_f32_e32 v24, 1.0, v24
	v_add_f32_e32 v25, 1.0, v25
	v_rcp_f32_e32 v24, v24
	v_rcp_f32_e32 v25, v25
	s_nop 0
	v_pk_fma_f32 v[24:25], v[16:17], v[24:25], v[26:27]
	v_lshlrev_b32_e32 v16, 16, v55
	v_and_b32_e32 v17, 0xffff0000, v55
	v_mul_f32_e32 v16, 0xbfb8aa3b, v16
	v_mul_f32_e32 v17, 0xbfb8aa3b, v17
	v_exp_f32_e32 v16, v16
	v_exp_f32_e32 v17, v17
	v_lshlrev_b32_e32 v26, 16, v51
	v_and_b32_e32 v27, 0xffff0000, v51
	v_add_f32_e32 v16, 1.0, v16
	v_add_f32_e32 v17, 1.0, v17
	v_rcp_f32_e32 v16, v16
	v_rcp_f32_e32 v17, v17
	s_nop 0
	v_pk_fma_f32 v[26:27], v[18:19], v[16:17], v[26:27]
	v_cvt_pk_bf16_f32 v16, v20, v21
	v_cvt_pk_bf16_f32 v17, v22, v23
	v_cvt_pk_bf16_f32 v18, v24, v25
	v_cvt_pk_bf16_f32 v19, v26, v27
	global_store_dwordx4 v[58:59], v[16:19], off offset:256
	v_lshlrev_b32_e32 v20, 16, v40
	v_and_b32_e32 v21, 0xffff0000, v40
	v_lshlrev_b32_e32 v18, 16, v44
	v_and_b32_e32 v19, 0xffff0000, v44
	v_mul_f32_e32 v18, 0xbfb8aa3b, v18
	v_mul_f32_e32 v19, 0xbfb8aa3b, v19
	v_exp_f32_e32 v18, v18
	v_exp_f32_e32 v19, v19
	v_lshl_add_u64 v[16:17], v[184:185], 0, v[56:57]
	v_add_f32_e32 v18, 1.0, v18
	v_add_f32_e32 v19, 1.0, v19
	v_rcp_f32_e32 v18, v18
	v_rcp_f32_e32 v19, v19
	s_nop 0
	v_pk_fma_f32 v[12:13], v[12:13], v[18:19], v[20:21]
	v_lshlrev_b32_e32 v18, 16, v45
	v_and_b32_e32 v19, 0xffff0000, v45
	v_mul_f32_e32 v18, 0xbfb8aa3b, v18
	v_mul_f32_e32 v19, 0xbfb8aa3b, v19
	v_exp_f32_e32 v18, v18
	v_exp_f32_e32 v19, v19
	v_lshlrev_b32_e32 v20, 16, v41
	v_and_b32_e32 v21, 0xffff0000, v41
	v_add_f32_e32 v18, 1.0, v18
	v_add_f32_e32 v19, 1.0, v19
	v_rcp_f32_e32 v18, v18
	v_rcp_f32_e32 v19, v19
	s_nop 0
	v_pk_fma_f32 v[14:15], v[14:15], v[18:19], v[20:21]
	v_lshlrev_b32_e32 v18, 16, v46
	v_and_b32_e32 v19, 0xffff0000, v46
	v_mul_f32_e32 v18, 0xbfb8aa3b, v18
	v_mul_f32_e32 v19, 0xbfb8aa3b, v19
	v_exp_f32_e32 v18, v18
	v_exp_f32_e32 v19, v19
	v_lshlrev_b32_e32 v20, 16, v42
	v_and_b32_e32 v21, 0xffff0000, v42
	v_add_f32_e32 v18, 1.0, v18
	v_add_f32_e32 v19, 1.0, v19
	v_rcp_f32_e32 v18, v18
	v_rcp_f32_e32 v19, v19
	s_nop 0
	v_pk_fma_f32 v[18:19], v[8:9], v[18:19], v[20:21]
	v_lshlrev_b32_e32 v8, 16, v47
	v_and_b32_e32 v9, 0xffff0000, v47
	v_mul_f32_e32 v8, 0xbfb8aa3b, v8
	v_mul_f32_e32 v9, 0xbfb8aa3b, v9
	v_exp_f32_e32 v8, v8
	v_exp_f32_e32 v9, v9
	v_lshlrev_b32_e32 v20, 16, v43
	v_and_b32_e32 v21, 0xffff0000, v43
	v_add_f32_e32 v8, 1.0, v8
	v_add_f32_e32 v9, 1.0, v9
	v_rcp_f32_e32 v8, v8
	v_rcp_f32_e32 v9, v9
	s_nop 0
	v_pk_fma_f32 v[20:21], v[10:11], v[8:9], v[20:21]
	v_cvt_pk_bf16_f32 v8, v12, v13
	v_cvt_pk_bf16_f32 v9, v14, v15
	v_cvt_pk_bf16_f32 v10, v18, v19
	v_cvt_pk_bf16_f32 v11, v20, v21
	global_store_dwordx4 v[16:17], v[8:11], off
	s_nop 1
	v_lshlrev_b32_e32 v8, 16, v36
	v_and_b32_e32 v9, 0xffff0000, v36
	v_mul_f32_e32 v8, 0xbfb8aa3b, v8
	v_mul_f32_e32 v9, 0xbfb8aa3b, v9
	v_exp_f32_e32 v8, v8
	v_exp_f32_e32 v9, v9
	v_lshlrev_b32_e32 v10, 16, v32
	v_and_b32_e32 v11, 0xffff0000, v32
	v_add_f32_e32 v8, 1.0, v8
	v_add_f32_e32 v9, 1.0, v9
	v_rcp_f32_e32 v8, v8
	v_rcp_f32_e32 v9, v9
	s_nop 0
	v_pk_fma_f32 v[4:5], v[4:5], v[8:9], v[10:11]
	v_lshlrev_b32_e32 v8, 16, v37
	v_and_b32_e32 v9, 0xffff0000, v37
	v_mul_f32_e32 v8, 0xbfb8aa3b, v8
	v_mul_f32_e32 v9, 0xbfb8aa3b, v9
	v_exp_f32_e32 v8, v8
	v_exp_f32_e32 v9, v9
	v_lshlrev_b32_e32 v10, 16, v33
	v_and_b32_e32 v11, 0xffff0000, v33
	v_add_f32_e32 v8, 1.0, v8
	v_add_f32_e32 v9, 1.0, v9
	v_rcp_f32_e32 v8, v8
	v_rcp_f32_e32 v9, v9
	s_nop 0
	v_pk_fma_f32 v[6:7], v[6:7], v[8:9], v[10:11]
	v_lshlrev_b32_e32 v8, 16, v38
	v_and_b32_e32 v9, 0xffff0000, v38
	v_mul_f32_e32 v8, 0xbfb8aa3b, v8
	v_mul_f32_e32 v9, 0xbfb8aa3b, v9
	v_exp_f32_e32 v8, v8
	v_exp_f32_e32 v9, v9
	v_lshlrev_b32_e32 v10, 16, v34
	v_and_b32_e32 v11, 0xffff0000, v34
	v_add_f32_e32 v8, 1.0, v8
	v_add_f32_e32 v9, 1.0, v9
	v_rcp_f32_e32 v8, v8
	v_rcp_f32_e32 v9, v9
	s_nop 0
	v_pk_fma_f32 v[8:9], v[0:1], v[8:9], v[10:11]
	v_lshlrev_b32_e32 v0, 16, v39
	v_and_b32_e32 v1, 0xffff0000, v39
	v_mul_f32_e32 v0, 0xbfb8aa3b, v0
	v_mul_f32_e32 v1, 0xbfb8aa3b, v1
	v_exp_f32_e32 v0, v0
	v_exp_f32_e32 v1, v1
	v_lshlrev_b32_e32 v10, 16, v35
	v_and_b32_e32 v11, 0xffff0000, v35
	v_add_f32_e32 v0, 1.0, v0
	v_add_f32_e32 v1, 1.0, v1
	v_rcp_f32_e32 v0, v0
	v_rcp_f32_e32 v1, v1
	s_nop 0
	v_pk_fma_f32 v[10:11], v[2:3], v[0:1], v[10:11]
	v_cvt_pk_bf16_f32 v0, v4, v5
	v_cvt_pk_bf16_f32 v1, v6, v7
	v_cvt_pk_bf16_f32 v2, v8, v9
	v_cvt_pk_bf16_f32 v3, v10, v11
	global_store_dwordx4 v[16:17], v[0:3], off offset:256
.Lp6e2_done:
	s_and_b64 vcc, exec, s[8:9]
	s_mov_b32 s42, s40
	s_mov_b32 s43, s41
	s_mov_b64 s[20:21], s[10:11]
	s_mov_b64 s[18:19], s[12:13]
	s_cbranch_vccnz .LBB0_1812
